# GEMM K-loops: first iteration peeled with C=0 on each accumulator's first MFMA, accumulator zeroing removed
# speedup vs baseline: 1.0058x; 1.0053x over previous
; #define STAGE(P, BASE, br, kt) do { int _so = ((br) * K + (kt) * BK) * 2; \
;     __builtin_amdgcn_raw_ptr_buffer_load_lds(rs_##BASE, (__attribute__((address_space(3))) void*)((char*)(P) + tx * 16), 16, voff0, _so, 0, 0); \
;     __builtin_amdgcn_raw_ptr_buffer_load_lds(rs_##BASE, (__attribute__((address_space(3))) void*)((char*)(P) + tx * 16 + 8192), 16, voff1, _so, 0, 0); } while (0)
; #define LDA(dst, b, h) _Pragma("unroll") for (int m = 0; m < 4; ++m) _Pragma("unroll") for (int k = 0; k < 2; ++k) \
;     dst[m][k] = *reinterpret_cast<const bf16x8*>((char*)SA(b, h) + lds_byte(wr * 64 + m * 16 + fr, k * 32 + fq * 8))
; #define LDB(dst, b, h) _Pragma("unroll") for (int n = 0; n < 2; ++n) _Pragma("unroll") for (int k = 0; k < 2; ++k) \
;     dst[n][k] = *reinterpret_cast<const bf16x8*>((char*)SB(b, h) + lds_byte(wc * 32 + n * 16 + fr, k * 32 + fq * 8))
; #define WAIT_V(n) asm volatile("s_waitcnt vmcnt(" #n ")" ::: "memory")
; #define WAIT_L(n) asm volatile("s_waitcnt lgkmcnt(" #n ")" ::: "memory")
; #define BAR __builtin_amdgcn_s_barrier()
; #define SCHED __builtin_amdgcn_sched_barrier(0)
; template <class Epi> ...
;     ...
;   int wid = tx >> 6, lane = tx & 63, wr = wid >> 2, wc = wid & 3, fr = lane & 15, fq = lane >> 4;
;   f32x4 acc[2][2][4][2] = {};
;   bf16x8 At[4][2], B0[2][2], B1[2][2];
;   int nt = K / BK;
;   int voff0, voff1;
;   { int _r, _c; stage_rc(tx * 16, _r, _c); voff0 = (_r * K + _c) * 2; stage_rc(tx * 16 + 8192, _r, _c); voff1 = (_r * K + _c) * 2; }
;   __amdgpu_buffer_rsrc_t rs_A = __builtin_amdgcn_make_buffer_rsrc((void*)A, 0, 0x7fffffff, 0x00020000);
;   __amdgpu_buffer_rsrc_t rs_Bt = __builtin_amdgcn_make_buffer_rsrc((void*)Bt, 0, 0x7fffffff, 0x00020000);
;   if (!pre) {
;     STAGE(SB(0, 0), Bt, bcol, 0); STAGE(SA(0, 0), A, brow, 0);
;     STAGE(SB(0, 1), Bt, bcol + HALF, 0); STAGE(SA(0, 1), A, brow + HALF, 0);
;   }
;   if (wr == 1) BAR;
;   if (pre) { WAIT_V(0); } else { WAIT_V(4); }
;   BAR;
;   STAGE(SB(1, 0), Bt, bcol, 1); STAGE(SA(1, 0), A, brow, 1); STAGE(SB(1, 1), Bt, bcol + HALF, 1);
;   WAIT_V(6); BAR;
;   for (int t = 0; t < nt - 2; t += 2) {
;     LDB(B0, 0, 0); SCHED; LDA(At, 0, 0); STAGE(SA(1, 1), A, brow + HALF, t + 1);
;     WAIT_L(8); BAR; WAIT_L(0); MMA(0, 0, At, B0); BAR; SCHED;
;     LDB(B1, 0, 1); STAGE(SB(0, 0), Bt, bcol, t + 2);
;     BAR; WAIT_L(0); MMA(0, 1, At, B1); BAR;
.LBB0_73:
	v_readlane_b32 s35, v254, 30
	s_lshl_b32 s20, s34, 11
	s_or_b32 s6, s20, 0x80
	v_add_u32_e32 v146, s35, v0
	v_add_u32_e32 v147, 0x2000, v146
	v_readfirstlane_b32 s7, v146
	s_mov_b32 m0, s7
	v_readfirstlane_b32 s7, v147
	v_add_u32_e32 v148, 0x8000, v136
	s_barrier
	buffer_load_dwordx4 v32, s[76:79], s6 offen lds
	s_mov_b32 m0, s7
	s_lshl_b32 s21, s31, 11
	v_readfirstlane_b32 s34, v148
	v_add_u32_e32 v150, 0xa000, v136
	v_readlane_b32 s36, v254, 31
	buffer_load_dwordx4 v130, s[76:79], s6 offen lds
	s_or_b32 s31, s21, 0x80
	s_mov_b32 s6, s78
	s_mov_b32 s7, s79
	s_mov_b32 m0, s34
	v_readfirstlane_b32 s34, v150
	v_add_u32_e32 v153, s36, v0
	buffer_load_dwordx4 v32, s[4:7], s31 offen lds
	s_mov_b32 m0, s34
	v_readfirstlane_b32 s34, v153
	v_add_u32_e32 v154, 0x2000, v153
	buffer_load_dwordx4 v130, s[4:7], s31 offen lds
	s_add_i32 s31, s20, 0x40080
	s_mov_b32 m0, s34
	v_readfirstlane_b32 s34, v154
	buffer_load_dwordx4 v32, s[76:79], s31 offen lds
	s_mov_b32 m0, s34
	v_and_b32_e32 v2, 15, v133
	buffer_load_dwordx4 v130, s[76:79], s31 offen lds
	v_lshlrev_b32_e32 v0, 6, v2
	v_lshlrev_b32_e32 v2, 2, v133
	v_and_b32_e32 v3, 48, v133
	v_and_b32_e32 v2, 32, v2
	v_bitop3_b32 v0, v0, v2, v3 bitop3:0x36
	s_waitcnt vmcnt(11)
	v_lshlrev_b32_e32 v8, 6, v133
	s_movk_i32 s31, 0x3c0
	s_waitcnt vmcnt(6)
	v_add_u32_e32 v4, s71, v0
	v_add_u32_e32 v5, s73, v0
	v_add_u32_e32 v6, s35, v0
	v_add_u32_e32 v7, s36, v0
	v_lshlrev_b32_e32 v1, 13, v1
	v_add_u32_e32 v10, 0, v0
	v_and_or_b32 v0, v8, s31, v3
	v_and_b32_e32 v9, 0x3000, v8
	v_xad_u32 v2, v0, v2, 0
	v_or_b32_e32 v3, 0x800, v1
	v_or_b32_e32 v8, 0x1000, v1
	v_or_b32_e32 v11, 0x1800, v1
	v_add_u32_e32 v152, 0xc000, v136
	v_add_u32_e32 v151, 0xe000, v136
	v_add_u32_e32 v139, 0x2000, v137
	v_add_u32_e32 v138, 0x2000, v134
	s_mov_b32 s31, -2
	s_mov_b32 s34, 0
	v_add_u32_e32 v155, v4, v9
	v_add_u32_e32 v143, v10, v1
	v_add_u32_e32 v142, v2, v3
	v_add_u32_e32 v141, v2, v8
	v_add_u32_e32 v140, v2, v11
	v_add_u32_e32 v149, v5, v9
	v_add_u32_e32 v145, v6, v9
	v_add_u32_e32 v144, v7, v9
	s_waitcnt vmcnt(10)
	s_barrier
.Lpk0:
	ds_read_b128 v[156:159], v155
	ds_read_b128 v[166:169], v155 offset:1024
	ds_read_b128 v[170:173], v155 offset:2048
	ds_read_b128 v[186:189], v155 offset:3072
	s_add_i32 s35, s21, s34
	v_readfirstlane_b32 s37, v152
	s_add_i32 s36, s35, 0x40080
	s_mov_b32 m0, s37
	v_readfirstlane_b32 s37, v151
	ds_read_b128 v[190:193], v143
	ds_read_b128 v[194:197], v143 offset:1024
	ds_read_b128 v[198:201], v142
	ds_read_b128 v[202:205], v142 offset:1024
	ds_read_b128 v[206:209], v141
	ds_read_b128 v[210:213], v141 offset:1024
	ds_read_b128 v[214:217], v140
	ds_read_b128 v[218:221], v140 offset:1024
	buffer_load_dwordx4 v32, s[4:7], s36 offen lds
	s_mov_b32 m0, s37
	s_nop 0
	buffer_load_dwordx4 v130, s[4:7], s36 offen lds
	s_waitcnt lgkmcnt(8)
	s_barrier
	s_waitcnt lgkmcnt(0)
	s_setprio 1
	s_waitcnt lgkmcnt(7)
	v_mfma_f32_16x16x32_bf16 v[126:129], v[190:193], v[156:159], 0
	v_mfma_f32_16x16x32_bf16 v[122:125], v[190:193], v[170:173], 0
	s_waitcnt lgkmcnt(5)
	v_mfma_f32_16x16x32_bf16 v[118:121], v[198:201], v[156:159], 0
	v_mfma_f32_16x16x32_bf16 v[114:117], v[198:201], v[170:173], 0
	s_waitcnt lgkmcnt(3)
	v_mfma_f32_16x16x32_bf16 v[110:113], v[206:209], v[156:159], 0
	v_mfma_f32_16x16x32_bf16 v[106:109], v[206:209], v[170:173], 0
	s_waitcnt lgkmcnt(1)
	v_mfma_f32_16x16x32_bf16 v[102:105], v[214:217], v[156:159], 0
	v_mfma_f32_16x16x32_bf16 v[98:101], v[214:217], v[170:173], 0
	v_mfma_f32_16x16x32_bf16 v[126:129], v[194:197], v[166:169], v[126:129]
	v_mfma_f32_16x16x32_bf16 v[122:125], v[194:197], v[186:189], v[122:125]
	v_mfma_f32_16x16x32_bf16 v[118:121], v[202:205], v[166:169], v[118:121]
	v_mfma_f32_16x16x32_bf16 v[114:117], v[202:205], v[186:189], v[114:117]
	v_mfma_f32_16x16x32_bf16 v[110:113], v[210:213], v[166:169], v[110:113]
	v_mfma_f32_16x16x32_bf16 v[106:109], v[210:213], v[186:189], v[106:109]
	s_waitcnt lgkmcnt(0)
	v_mfma_f32_16x16x32_bf16 v[102:105], v[218:221], v[166:169], v[102:105]
	v_mfma_f32_16x16x32_bf16 v[98:101], v[218:221], v[186:189], v[98:101]
	s_setprio 0
	s_barrier
	s_add_i32 s36, s20, s34
	v_readfirstlane_b32 s38, v137
	s_add_i32 s37, s36, 0x100
	s_mov_b32 m0, s38
	v_readfirstlane_b32 s38, v139
	ds_read_b128 v[222:225], v149
	ds_read_b128 v[226:229], v149 offset:1024
	ds_read_b128 v[230:233], v149 offset:2048
	ds_read_b128 v[234:237], v149 offset:3072
	buffer_load_dwordx4 v32, s[76:79], s37 offen lds
	s_mov_b32 m0, s38
	s_nop 0
	buffer_load_dwordx4 v130, s[76:79], s37 offen lds
	s_barrier
	s_waitcnt lgkmcnt(0)
	s_setprio 1
	s_waitcnt lgkmcnt(3)
	v_mfma_f32_16x16x32_bf16 v[94:97], v[190:193], v[222:225], 0
	s_waitcnt lgkmcnt(1)
	v_mfma_f32_16x16x32_bf16 v[90:93], v[190:193], v[230:233], 0
	v_mfma_f32_16x16x32_bf16 v[86:89], v[198:201], v[222:225], 0
	v_mfma_f32_16x16x32_bf16 v[82:85], v[198:201], v[230:233], 0
	v_mfma_f32_16x16x32_bf16 v[78:81], v[206:209], v[222:225], 0
	v_mfma_f32_16x16x32_bf16 v[74:77], v[206:209], v[230:233], 0
	v_mfma_f32_16x16x32_bf16 v[70:73], v[214:217], v[222:225], 0
	v_mfma_f32_16x16x32_bf16 v[66:69], v[214:217], v[230:233], 0
	v_mfma_f32_16x16x32_bf16 v[94:97], v[194:197], v[226:229], v[94:97]
	s_waitcnt lgkmcnt(0)
	v_mfma_f32_16x16x32_bf16 v[90:93], v[194:197], v[234:237], v[90:93]
	v_mfma_f32_16x16x32_bf16 v[86:89], v[202:205], v[226:229], v[86:89]
	v_mfma_f32_16x16x32_bf16 v[82:85], v[202:205], v[234:237], v[82:85]
	v_mfma_f32_16x16x32_bf16 v[78:81], v[210:213], v[226:229], v[78:81]
	v_mfma_f32_16x16x32_bf16 v[74:77], v[210:213], v[234:237], v[74:77]
	v_mfma_f32_16x16x32_bf16 v[70:73], v[218:221], v[226:229], v[70:73]
	v_mfma_f32_16x16x32_bf16 v[66:69], v[218:221], v[234:237], v[66:69]
	s_setprio 0
	v_readfirstlane_b32 s38, v136
	s_add_i32 s37, s35, 0x100
	s_mov_b32 m0, s38
	v_readfirstlane_b32 s38, v135
	s_barrier
; #define STAGE(P, BASE, br, kt) do { int _so = ((br) * K + (kt) * BK) * 2; \
;     __builtin_amdgcn_raw_ptr_buffer_load_lds(rs_##BASE, (__attribute__((address_space(3))) void*)((char*)(P) + tx * 16), 16, voff0, _so, 0, 0); \
;     __builtin_amdgcn_raw_ptr_buffer_load_lds(rs_##BASE, (__attribute__((address_space(3))) void*)((char*)(P) + tx * 16 + 8192), 16, voff1, _so, 0, 0); } while (0)
; #define LDA(dst, b, h) _Pragma("unroll") for (int m = 0; m < 4; ++m) _Pragma("unroll") for (int k = 0; k < 2; ++k) \
;     dst[m][k] = *reinterpret_cast<const bf16x8*>((char*)SA(b, h) + lds_byte(wr * 64 + m * 16 + fr, k * 32 + fq * 8))
; #define LDB(dst, b, h) _Pragma("unroll") for (int n = 0; n < 2; ++n) _Pragma("unroll") for (int k = 0; k < 2; ++k) \
;     dst[n][k] = *reinterpret_cast<const bf16x8*>((char*)SB(b, h) + lds_byte(wc * 32 + n * 16 + fr, k * 32 + fq * 8))
; #define MMA(ai, bj, At, Bt_) do { __builtin_amdgcn_s_setprio(1); \
;     _Pragma("unroll") for (int m = 0; m < 4; ++m) _Pragma("unroll") for (int n = 0; n < 2; ++n) _Pragma("unroll") for (int k = 0; k < 2; ++k) \
;       acc[ai][bj][m][n] = __builtin_amdgcn_mfma_f32_16x16x32_bf16(At[m][k], Bt_[n][k], acc[ai][bj][m][n], 0, 0, 0); \
;     __builtin_amdgcn_s_setprio(0); } while (0)
; #define WAIT_V(n) asm volatile("s_waitcnt vmcnt(" #n ")" ::: "memory")
; #define WAIT_L(n) asm volatile("s_waitcnt lgkmcnt(" #n ")" ::: "memory")
; #define BAR __builtin_amdgcn_s_barrier()
; #define SCHED __builtin_amdgcn_sched_barrier(0)
; template <class Epi> ...
;     ...
;     LDA(At, 0, 1); STAGE(SA(0, 0), A, brow, t + 2);
;     BAR; WAIT_L(0); MMA(1, 0, At, B0); BAR; SCHED;
;     STAGE(SB(0, 1), Bt, bcol + HALF, t + 2);
;     WAIT_V(6); BAR; MMA(1, 1, At, B1); BAR;
;     LDB(B0, 1, 0); SCHED; LDA(At, 1, 0); STAGE(SA(0, 1), A, brow + HALF, t + 2);
;     WAIT_L(8); BAR; WAIT_L(0); MMA(0, 0, At, B0); BAR; SCHED;
	ds_read_b128 v[190:193], v143 offset:16384
	ds_read_b128 v[194:197], v143 offset:17408
	ds_read_b128 v[198:201], v142 offset:16384
	ds_read_b128 v[202:205], v142 offset:17408
	ds_read_b128 v[206:209], v141 offset:16384
	ds_read_b128 v[210:213], v141 offset:17408
	ds_read_b128 v[214:217], v140 offset:16384
	ds_read_b128 v[218:221], v140 offset:17408
	buffer_load_dwordx4 v32, s[4:7], s37 offen lds
	s_mov_b32 m0, s38
	s_nop 0
	buffer_load_dwordx4 v130, s[4:7], s37 offen lds
	s_barrier
	s_waitcnt lgkmcnt(0)
	s_setprio 1
	s_waitcnt lgkmcnt(7)
	v_mfma_f32_16x16x32_bf16 v[62:65], v[190:193], v[156:159], 0
	v_mfma_f32_16x16x32_bf16 v[58:61], v[190:193], v[170:173], 0
	s_waitcnt lgkmcnt(5)
	v_mfma_f32_16x16x32_bf16 v[54:57], v[198:201], v[156:159], 0
	v_mfma_f32_16x16x32_bf16 v[50:53], v[198:201], v[170:173], 0
	s_waitcnt lgkmcnt(3)
	v_mfma_f32_16x16x32_bf16 v[46:49], v[206:209], v[156:159], 0
	v_mfma_f32_16x16x32_bf16 v[42:45], v[206:209], v[170:173], 0
	s_waitcnt lgkmcnt(1)
	v_mfma_f32_16x16x32_bf16 v[38:41], v[214:217], v[156:159], 0
	v_mfma_f32_16x16x32_bf16 v[34:37], v[214:217], v[170:173], 0
	v_mfma_f32_16x16x32_bf16 v[62:65], v[194:197], v[166:169], v[62:65]
	v_mfma_f32_16x16x32_bf16 v[58:61], v[194:197], v[186:189], v[58:61]
	v_mfma_f32_16x16x32_bf16 v[54:57], v[202:205], v[166:169], v[54:57]
	v_mfma_f32_16x16x32_bf16 v[50:53], v[202:205], v[186:189], v[50:53]
	v_mfma_f32_16x16x32_bf16 v[46:49], v[210:213], v[166:169], v[46:49]
	v_mfma_f32_16x16x32_bf16 v[42:45], v[210:213], v[186:189], v[42:45]
	s_waitcnt lgkmcnt(0)
	v_mfma_f32_16x16x32_bf16 v[38:41], v[218:221], v[166:169], v[38:41]
	v_mfma_f32_16x16x32_bf16 v[34:37], v[218:221], v[186:189], v[34:37]
	s_setprio 0
	s_barrier
	v_readfirstlane_b32 s38, v134
	s_add_i32 s37, s36, 0x40100
	s_mov_b32 m0, s38
	v_readfirstlane_b32 s38, v138
	buffer_load_dwordx4 v32, s[76:79], s37 offen lds
	s_mov_b32 m0, s38
	s_nop 0
	buffer_load_dwordx4 v130, s[76:79], s37 offen lds
	s_waitcnt vmcnt(6)
	s_barrier
	s_setprio 1
	v_mfma_f32_16x16x32_bf16 v[28:31], v[190:193], v[222:225], 0
	v_mfma_f32_16x16x32_bf16 v[24:27], v[190:193], v[230:233], 0
	v_mfma_f32_16x16x32_bf16 v[20:23], v[198:201], v[222:225], 0
	v_mfma_f32_16x16x32_bf16 v[16:19], v[198:201], v[230:233], 0
	v_mfma_f32_16x16x32_bf16 v[12:15], v[206:209], v[222:225], 0
	v_mfma_f32_16x16x32_bf16 v[8:11], v[206:209], v[230:233], 0
	v_mfma_f32_16x16x32_bf16 v[4:7], v[214:217], v[222:225], 0
	v_mfma_f32_16x16x32_bf16 v[0:3], v[214:217], v[230:233], 0
	v_mfma_f32_16x16x32_bf16 v[28:31], v[194:197], v[226:229], v[28:31]
	v_mfma_f32_16x16x32_bf16 v[24:27], v[194:197], v[234:237], v[24:27]
	v_mfma_f32_16x16x32_bf16 v[20:23], v[202:205], v[226:229], v[20:23]
	v_mfma_f32_16x16x32_bf16 v[16:19], v[202:205], v[234:237], v[16:19]
	v_mfma_f32_16x16x32_bf16 v[12:15], v[210:213], v[226:229], v[12:15]
	v_mfma_f32_16x16x32_bf16 v[8:11], v[210:213], v[234:237], v[8:11]
	v_mfma_f32_16x16x32_bf16 v[4:7], v[218:221], v[226:229], v[4:7]
	v_mfma_f32_16x16x32_bf16 v[0:3], v[218:221], v[234:237], v[0:3]
	s_setprio 0
	s_barrier
	ds_read_b128 v[156:159], v145
	ds_read_b128 v[166:169], v145 offset:1024
	ds_read_b128 v[170:173], v145 offset:2048
	ds_read_b128 v[186:189], v145 offset:3072
	v_readfirstlane_b32 s38, v132
	s_add_i32 s37, s35, 0x40100
	s_mov_b32 m0, s38
	v_readfirstlane_b32 s38, v131
	ds_read_b128 v[190:193], v143 offset:32768
	ds_read_b128 v[194:197], v143 offset:33792
	ds_read_b128 v[198:201], v142 offset:32768
	ds_read_b128 v[202:205], v142 offset:33792
	ds_read_b128 v[206:209], v141 offset:32768
	ds_read_b128 v[210:213], v141 offset:33792
	ds_read_b128 v[214:217], v140 offset:32768
	ds_read_b128 v[218:221], v140 offset:33792
	buffer_load_dwordx4 v32, s[4:7], s37 offen lds
	s_mov_b32 m0, s38
	s_nop 0
	buffer_load_dwordx4 v130, s[4:7], s37 offen lds
	s_waitcnt lgkmcnt(8)
	s_barrier
	s_waitcnt lgkmcnt(0)
	s_setprio 1
	s_waitcnt lgkmcnt(7)
	v_mfma_f32_16x16x32_bf16 v[126:129], v[190:193], v[156:159], v[126:129]
	v_mfma_f32_16x16x32_bf16 v[122:125], v[190:193], v[170:173], v[122:125]
	s_waitcnt lgkmcnt(5)
	v_mfma_f32_16x16x32_bf16 v[118:121], v[198:201], v[156:159], v[118:121]
	v_mfma_f32_16x16x32_bf16 v[114:117], v[198:201], v[170:173], v[114:117]
	s_waitcnt lgkmcnt(3)
	v_mfma_f32_16x16x32_bf16 v[110:113], v[206:209], v[156:159], v[110:113]
	v_mfma_f32_16x16x32_bf16 v[106:109], v[206:209], v[170:173], v[106:109]
	s_waitcnt lgkmcnt(1)
	v_mfma_f32_16x16x32_bf16 v[102:105], v[214:217], v[156:159], v[102:105]
	v_mfma_f32_16x16x32_bf16 v[98:101], v[214:217], v[170:173], v[98:101]
	v_mfma_f32_16x16x32_bf16 v[126:129], v[194:197], v[166:169], v[126:129]
	v_mfma_f32_16x16x32_bf16 v[122:125], v[194:197], v[186:189], v[122:125]
	v_mfma_f32_16x16x32_bf16 v[118:121], v[202:205], v[166:169], v[118:121]
	v_mfma_f32_16x16x32_bf16 v[114:117], v[202:205], v[186:189], v[114:117]
	v_mfma_f32_16x16x32_bf16 v[110:113], v[210:213], v[166:169], v[110:113]
	v_mfma_f32_16x16x32_bf16 v[106:109], v[210:213], v[186:189], v[106:109]
	s_waitcnt lgkmcnt(0)
	v_mfma_f32_16x16x32_bf16 v[102:105], v[218:221], v[166:169], v[102:105]
	v_mfma_f32_16x16x32_bf16 v[98:101], v[218:221], v[186:189], v[98:101]
	s_setprio 0
	s_barrier
; #define STAGE(P, BASE, br, kt) do { int _so = ((br) * K + (kt) * BK) * 2; \
;     __builtin_amdgcn_raw_ptr_buffer_load_lds(rs_##BASE, (__attribute__((address_space(3))) void*)((char*)(P) + tx * 16), 16, voff0, _so, 0, 0); \
;     __builtin_amdgcn_raw_ptr_buffer_load_lds(rs_##BASE, (__attribute__((address_space(3))) void*)((char*)(P) + tx * 16 + 8192), 16, voff1, _so, 0, 0); } while (0)
; #define LDA(dst, b, h) _Pragma("unroll") for (int m = 0; m < 4; ++m) _Pragma("unroll") for (int k = 0; k < 2; ++k) \
;     dst[m][k] = *reinterpret_cast<const bf16x8*>((char*)SA(b, h) + lds_byte(wr * 64 + m * 16 + fr, k * 32 + fq * 8))
; #define LDB(dst, b, h) _Pragma("unroll") for (int n = 0; n < 2; ++n) _Pragma("unroll") for (int k = 0; k < 2; ++k) \
;     dst[n][k] = *reinterpret_cast<const bf16x8*>((char*)SB(b, h) + lds_byte(wc * 32 + n * 16 + fr, k * 32 + fq * 8))
; #define MMA(ai, bj, At, Bt_) do { __builtin_amdgcn_s_setprio(1); \
;     _Pragma("unroll") for (int m = 0; m < 4; ++m) _Pragma("unroll") for (int n = 0; n < 2; ++n) _Pragma("unroll") for (int k = 0; k < 2; ++k) \
;       acc[ai][bj][m][n] = __builtin_amdgcn_mfma_f32_16x16x32_bf16(At[m][k], Bt_[n][k], acc[ai][bj][m][n], 0, 0, 0); \
;     __builtin_amdgcn_s_setprio(0); } while (0)
; #define WAIT_V(n) asm volatile("s_waitcnt vmcnt(" #n ")" ::: "memory")
; #define WAIT_L(n) asm volatile("s_waitcnt lgkmcnt(" #n ")" ::: "memory")
; #define BAR __builtin_amdgcn_s_barrier()
; #define SCHED __builtin_amdgcn_sched_barrier(0)
; template <class Epi> ...
;     ...
;     LDB(B1, 1, 1); STAGE(SB(1, 0), Bt, bcol, t + 3);
;     BAR; WAIT_L(0); MMA(0, 1, At, B1); BAR;
;     LDA(At, 1, 1); STAGE(SA(1, 0), A, brow, t + 3);
;     BAR; WAIT_L(0); MMA(1, 0, At, B0); BAR; SCHED;
;     STAGE(SB(1, 1), Bt, bcol + HALF, t + 3);
;     WAIT_V(6); BAR; MMA(1, 1, At, B1); BAR;
;   }
	v_readfirstlane_b32 s38, v146
	s_add_i32 s37, s36, 0x180
	s_mov_b32 m0, s38
	v_readfirstlane_b32 s38, v147
	ds_read_b128 v[222:225], v144
	ds_read_b128 v[226:229], v144 offset:1024
	ds_read_b128 v[230:233], v144 offset:2048
	ds_read_b128 v[234:237], v144 offset:3072
	buffer_load_dwordx4 v32, s[76:79], s37 offen lds
	s_mov_b32 m0, s38
	s_nop 0
	buffer_load_dwordx4 v130, s[76:79], s37 offen lds
	s_barrier
	s_waitcnt lgkmcnt(0)
	s_setprio 1
	s_waitcnt lgkmcnt(3)
	v_mfma_f32_16x16x32_bf16 v[94:97], v[190:193], v[222:225], v[94:97]
	s_waitcnt lgkmcnt(1)
	v_mfma_f32_16x16x32_bf16 v[90:93], v[190:193], v[230:233], v[90:93]
	v_mfma_f32_16x16x32_bf16 v[86:89], v[198:201], v[222:225], v[86:89]
	v_mfma_f32_16x16x32_bf16 v[82:85], v[198:201], v[230:233], v[82:85]
	v_mfma_f32_16x16x32_bf16 v[78:81], v[206:209], v[222:225], v[78:81]
	v_mfma_f32_16x16x32_bf16 v[74:77], v[206:209], v[230:233], v[74:77]
	v_mfma_f32_16x16x32_bf16 v[70:73], v[214:217], v[222:225], v[70:73]
	v_mfma_f32_16x16x32_bf16 v[66:69], v[214:217], v[230:233], v[66:69]
	v_mfma_f32_16x16x32_bf16 v[94:97], v[194:197], v[226:229], v[94:97]
	s_waitcnt lgkmcnt(0)
	v_mfma_f32_16x16x32_bf16 v[90:93], v[194:197], v[234:237], v[90:93]
	v_mfma_f32_16x16x32_bf16 v[86:89], v[202:205], v[226:229], v[86:89]
	v_mfma_f32_16x16x32_bf16 v[82:85], v[202:205], v[234:237], v[82:85]
	v_mfma_f32_16x16x32_bf16 v[78:81], v[210:213], v[226:229], v[78:81]
	v_mfma_f32_16x16x32_bf16 v[74:77], v[210:213], v[234:237], v[74:77]
	v_mfma_f32_16x16x32_bf16 v[70:73], v[218:221], v[226:229], v[70:73]
	v_mfma_f32_16x16x32_bf16 v[66:69], v[218:221], v[234:237], v[66:69]
	s_setprio 0
	v_readfirstlane_b32 s37, v148
	s_addk_i32 s35, 0x180
	s_mov_b32 m0, s37
	v_readfirstlane_b32 s37, v150
	s_barrier
	ds_read_b128 v[190:193], v143 offset:49152
	ds_read_b128 v[194:197], v143 offset:50176
	ds_read_b128 v[198:201], v142 offset:49152
	ds_read_b128 v[202:205], v142 offset:50176
	ds_read_b128 v[206:209], v141 offset:49152
	ds_read_b128 v[210:213], v141 offset:50176
	ds_read_b128 v[214:217], v140 offset:49152
	ds_read_b128 v[218:221], v140 offset:50176
	buffer_load_dwordx4 v32, s[4:7], s35 offen lds
	s_mov_b32 m0, s37
	s_nop 0
	buffer_load_dwordx4 v130, s[4:7], s35 offen lds
	s_barrier
	s_waitcnt lgkmcnt(0)
	s_setprio 1
	s_waitcnt lgkmcnt(7)
	v_mfma_f32_16x16x32_bf16 v[62:65], v[190:193], v[156:159], v[62:65]
	v_mfma_f32_16x16x32_bf16 v[58:61], v[190:193], v[170:173], v[58:61]
	s_waitcnt lgkmcnt(5)
	v_mfma_f32_16x16x32_bf16 v[54:57], v[198:201], v[156:159], v[54:57]
	v_mfma_f32_16x16x32_bf16 v[50:53], v[198:201], v[170:173], v[50:53]
	s_waitcnt lgkmcnt(3)
	v_mfma_f32_16x16x32_bf16 v[46:49], v[206:209], v[156:159], v[46:49]
	v_mfma_f32_16x16x32_bf16 v[42:45], v[206:209], v[170:173], v[42:45]
	s_waitcnt lgkmcnt(1)
	v_mfma_f32_16x16x32_bf16 v[38:41], v[214:217], v[156:159], v[38:41]
	v_mfma_f32_16x16x32_bf16 v[34:37], v[214:217], v[170:173], v[34:37]
	v_mfma_f32_16x16x32_bf16 v[62:65], v[194:197], v[166:169], v[62:65]
	v_mfma_f32_16x16x32_bf16 v[58:61], v[194:197], v[186:189], v[58:61]
	v_mfma_f32_16x16x32_bf16 v[54:57], v[202:205], v[166:169], v[54:57]
	v_mfma_f32_16x16x32_bf16 v[50:53], v[202:205], v[186:189], v[50:53]
	v_mfma_f32_16x16x32_bf16 v[46:49], v[210:213], v[166:169], v[46:49]
	v_mfma_f32_16x16x32_bf16 v[42:45], v[210:213], v[186:189], v[42:45]
	s_waitcnt lgkmcnt(0)
	v_mfma_f32_16x16x32_bf16 v[38:41], v[218:221], v[166:169], v[38:41]
	v_mfma_f32_16x16x32_bf16 v[34:37], v[218:221], v[186:189], v[34:37]
	s_setprio 0
	s_barrier
	v_readfirstlane_b32 s35, v153
	s_add_i32 s36, s36, 0x40180
	s_mov_b32 m0, s35
	v_readfirstlane_b32 s35, v154
	buffer_load_dwordx4 v32, s[76:79], s36 offen lds
	s_mov_b32 m0, s35
	s_nop 0
	buffer_load_dwordx4 v130, s[76:79], s36 offen lds
	s_waitcnt vmcnt(6)
	s_barrier
	s_setprio 1
	v_mfma_f32_16x16x32_bf16 v[28:31], v[190:193], v[222:225], v[28:31]
	v_mfma_f32_16x16x32_bf16 v[24:27], v[190:193], v[230:233], v[24:27]
	v_mfma_f32_16x16x32_bf16 v[20:23], v[198:201], v[222:225], v[20:23]
	v_mfma_f32_16x16x32_bf16 v[16:19], v[198:201], v[230:233], v[16:19]
	v_mfma_f32_16x16x32_bf16 v[12:15], v[206:209], v[222:225], v[12:15]
	v_mfma_f32_16x16x32_bf16 v[8:11], v[206:209], v[230:233], v[8:11]
	v_mfma_f32_16x16x32_bf16 v[4:7], v[214:217], v[222:225], v[4:7]
	v_mfma_f32_16x16x32_bf16 v[0:3], v[214:217], v[230:233], v[0:3]
	v_mfma_f32_16x16x32_bf16 v[28:31], v[194:197], v[226:229], v[28:31]
	v_mfma_f32_16x16x32_bf16 v[24:27], v[194:197], v[234:237], v[24:27]
	v_mfma_f32_16x16x32_bf16 v[20:23], v[202:205], v[226:229], v[20:23]
	v_mfma_f32_16x16x32_bf16 v[16:19], v[202:205], v[234:237], v[16:19]
	v_mfma_f32_16x16x32_bf16 v[12:15], v[210:213], v[226:229], v[12:15]
	v_mfma_f32_16x16x32_bf16 v[8:11], v[210:213], v[234:237], v[8:11]
	v_mfma_f32_16x16x32_bf16 v[4:7], v[218:221], v[226:229], v[4:7]
	v_mfma_f32_16x16x32_bf16 v[0:3], v[218:221], v[234:237], v[0:3]
	s_setprio 0
	s_add_i32 s31, s31, 2
	s_addk_i32 s34, 0x100
	s_cmp_lt_u32 s31, 12
	s_barrier
	s_cbranch_scc1 .LBB0_74
	s_branch .Lpx0

; #define STAGE(P, BASE, br, kt) do { int _so = ((br) * K + (kt) * BK) * 2; \
;     __builtin_amdgcn_raw_ptr_buffer_load_lds(rs_##BASE, (__attribute__((address_space(3))) void*)((char*)(P) + tx * 16), 16, voff0, _so, 0, 0); \
;     __builtin_amdgcn_raw_ptr_buffer_load_lds(rs_##BASE, (__attribute__((address_space(3))) void*)((char*)(P) + tx * 16 + 8192), 16, voff1, _so, 0, 0); } while (0)
; #define LDA(dst, b, h) _Pragma("unroll") for (int m = 0; m < 4; ++m) _Pragma("unroll") for (int k = 0; k < 2; ++k) \
;     dst[m][k] = *reinterpret_cast<const bf16x8*>((char*)SA(b, h) + lds_byte(wr * 64 + m * 16 + fr, k * 32 + fq * 8))
; #define LDB(dst, b, h) _Pragma("unroll") for (int n = 0; n < 2; ++n) _Pragma("unroll") for (int k = 0; k < 2; ++k) \
;     dst[n][k] = *reinterpret_cast<const bf16x8*>((char*)SB(b, h) + lds_byte(wc * 32 + n * 16 + fr, k * 32 + fq * 8))
; #define MMA(ai, bj, At, Bt_) do { __builtin_amdgcn_s_setprio(1); \
;     _Pragma("unroll") for (int m = 0; m < 4; ++m) _Pragma("unroll") for (int n = 0; n < 2; ++n) _Pragma("unroll") for (int k = 0; k < 2; ++k) \
;       acc[ai][bj][m][n] = __builtin_amdgcn_mfma_f32_16x16x32_bf16(At[m][k], Bt_[n][k], acc[ai][bj][m][n], 0, 0, 0); \
;     __builtin_amdgcn_s_setprio(0); } while (0)
; #define WAIT_V(n) asm volatile("s_waitcnt vmcnt(" #n ")" ::: "memory")
; #define WAIT_L(n) asm volatile("s_waitcnt lgkmcnt(" #n ")" ::: "memory")
; #define BAR __builtin_amdgcn_s_barrier()
; template <class Epi> ...
;     ...
;   { LDB(B0, 0, 0); LDA(At, 0, 0); STAGE(SA(1, 1), A, brow + HALF, nt - 1);
;     BAR; WAIT_L(0); MMA(0, 0, At, B0); BAR;
;     LDB(B1, 0, 1); BAR; WAIT_L(0); MMA(0, 1, At, B1); BAR;
;     LDA(At, 0, 1); WAIT_V(4); BAR; WAIT_L(0); MMA(1, 0, At, B0); MMA(1, 1, At, B1); BAR; }
.Lpx0:
	v_readfirstlane_b32 s20, v152
	s_add_i32 s21, s21, 0x40780
	s_mov_b32 s6, s78
	s_mov_b32 s7, s79
	s_mov_b32 m0, s20
	v_readfirstlane_b32 s20, v151
	ds_read_b128 v[156:159], v155
	ds_read_b128 v[166:169], v155 offset:1024
	ds_read_b128 v[170:173], v155 offset:2048
	ds_read_b128 v[186:189], v155 offset:3072
	ds_read_b128 v[190:193], v143
	ds_read_b128 v[194:197], v143 offset:1024
	ds_read_b128 v[198:201], v142
	ds_read_b128 v[202:205], v142 offset:1024
	ds_read_b128 v[206:209], v141
	ds_read_b128 v[210:213], v141 offset:1024
	ds_read_b128 v[214:217], v140
	ds_read_b128 v[218:221], v140 offset:1024
	buffer_load_dwordx4 v32, s[4:7], s21 offen lds
	s_mov_b32 m0, s20
	s_nop 0
	buffer_load_dwordx4 v130, s[4:7], s21 offen lds
	s_barrier
	s_waitcnt lgkmcnt(0)
	s_setprio 1
	s_waitcnt lgkmcnt(7)
	v_mfma_f32_16x16x32_bf16 v[126:129], v[190:193], v[156:159], v[126:129]
	v_mfma_f32_16x16x32_bf16 v[122:125], v[190:193], v[170:173], v[122:125]
	s_waitcnt lgkmcnt(5)
	v_mfma_f32_16x16x32_bf16 v[118:121], v[198:201], v[156:159], v[118:121]
	v_mfma_f32_16x16x32_bf16 v[114:117], v[198:201], v[170:173], v[114:117]
	s_waitcnt lgkmcnt(3)
	v_mfma_f32_16x16x32_bf16 v[110:113], v[206:209], v[156:159], v[110:113]
	v_mfma_f32_16x16x32_bf16 v[106:109], v[206:209], v[170:173], v[106:109]
	s_waitcnt lgkmcnt(1)
	v_mfma_f32_16x16x32_bf16 v[102:105], v[214:217], v[156:159], v[102:105]
	v_mfma_f32_16x16x32_bf16 v[98:101], v[214:217], v[170:173], v[98:101]
	v_mfma_f32_16x16x32_bf16 v[126:129], v[194:197], v[166:169], v[126:129]
	v_mfma_f32_16x16x32_bf16 v[122:125], v[194:197], v[186:189], v[122:125]
	v_mfma_f32_16x16x32_bf16 v[118:121], v[202:205], v[166:169], v[118:121]
	v_mfma_f32_16x16x32_bf16 v[114:117], v[202:205], v[186:189], v[114:117]
	v_mfma_f32_16x16x32_bf16 v[110:113], v[210:213], v[166:169], v[110:113]
	v_mfma_f32_16x16x32_bf16 v[106:109], v[210:213], v[186:189], v[106:109]
	s_waitcnt lgkmcnt(0)
	v_mfma_f32_16x16x32_bf16 v[102:105], v[218:221], v[166:169], v[102:105]
	v_mfma_f32_16x16x32_bf16 v[98:101], v[218:221], v[186:189], v[98:101]
	s_setprio 0
	s_barrier
	ds_read_b128 v[150:153], v149
	ds_read_b128 v[222:225], v149 offset:1024
	ds_read_b128 v[226:229], v149 offset:2048
	ds_read_b128 v[146:149], v149 offset:3072
	s_barrier
	s_waitcnt lgkmcnt(0)
	s_setprio 1
	s_waitcnt lgkmcnt(3)
	v_mfma_f32_16x16x32_bf16 v[78:81], v[206:209], v[150:153], v[78:81]
	s_waitcnt lgkmcnt(1)
	v_mfma_f32_16x16x32_bf16 v[74:77], v[206:209], v[226:229], v[74:77]
	v_mfma_f32_16x16x32_bf16 v[70:73], v[214:217], v[150:153], v[70:73]
	v_mfma_f32_16x16x32_bf16 v[66:69], v[214:217], v[226:229], v[66:69]
	v_mfma_f32_16x16x32_bf16 v[94:97], v[190:193], v[150:153], v[94:97]
	v_mfma_f32_16x16x32_bf16 v[90:93], v[190:193], v[226:229], v[90:93]
	v_mfma_f32_16x16x32_bf16 v[86:89], v[198:201], v[150:153], v[86:89]
	v_mfma_f32_16x16x32_bf16 v[82:85], v[198:201], v[226:229], v[82:85]
	v_mfma_f32_16x16x32_bf16 v[78:81], v[210:213], v[222:225], v[78:81]
	s_waitcnt lgkmcnt(0)
	v_mfma_f32_16x16x32_bf16 v[74:77], v[210:213], v[146:149], v[74:77]
	v_mfma_f32_16x16x32_bf16 v[70:73], v[218:221], v[222:225], v[70:73]
	v_mfma_f32_16x16x32_bf16 v[66:69], v[218:221], v[146:149], v[66:69]
	v_mfma_f32_16x16x32_bf16 v[230:233], v[194:197], v[222:225], v[94:97]
	v_mfma_f32_16x16x32_bf16 v[190:193], v[194:197], v[146:149], v[90:93]
	v_mfma_f32_16x16x32_bf16 v[194:197], v[202:205], v[222:225], v[86:89]
	v_mfma_f32_16x16x32_bf16 v[198:201], v[202:205], v[146:149], v[82:85]
	s_setprio 0
	s_barrier
	s_nop 0
	ds_read_b128 v[82:85], v143 offset:16384
	ds_read_b128 v[86:89], v143 offset:17408
	ds_read_b128 v[90:93], v142 offset:16384
	ds_read_b128 v[94:97], v142 offset:17408
	ds_read_b128 v[202:205], v141 offset:16384
	ds_read_b128 v[206:209], v141 offset:17408
	ds_read_b128 v[210:213], v140 offset:16384
	ds_read_b128 v[214:217], v140 offset:17408
	s_waitcnt vmcnt(4)
	s_barrier
	s_waitcnt lgkmcnt(0)
	s_setprio 1
	s_waitcnt lgkmcnt(3)
	v_mfma_f32_16x16x32_bf16 v[46:49], v[202:205], v[156:159], v[46:49]
	v_mfma_f32_16x16x32_bf16 v[42:45], v[202:205], v[170:173], v[42:45]
	s_waitcnt lgkmcnt(1)
	v_mfma_f32_16x16x32_bf16 v[38:41], v[210:213], v[156:159], v[38:41]
	v_mfma_f32_16x16x32_bf16 v[34:37], v[210:213], v[170:173], v[34:37]
	v_mfma_f32_16x16x32_bf16 v[62:65], v[82:85], v[156:159], v[62:65]
	v_mfma_f32_16x16x32_bf16 v[58:61], v[82:85], v[170:173], v[58:61]
	v_mfma_f32_16x16x32_bf16 v[54:57], v[90:93], v[156:159], v[54:57]
	v_mfma_f32_16x16x32_bf16 v[50:53], v[90:93], v[170:173], v[50:53]
	v_mfma_f32_16x16x32_bf16 v[46:49], v[206:209], v[166:169], v[46:49]
	v_mfma_f32_16x16x32_bf16 v[42:45], v[206:209], v[186:189], v[42:45]
	s_waitcnt lgkmcnt(0)
	v_mfma_f32_16x16x32_bf16 v[38:41], v[214:217], v[166:169], v[38:41]
	v_mfma_f32_16x16x32_bf16 v[34:37], v[214:217], v[186:189], v[34:37]
	v_mfma_f32_16x16x32_bf16 v[218:221], v[86:89], v[166:169], v[62:65]
	v_mfma_f32_16x16x32_bf16 v[234:237], v[86:89], v[186:189], v[58:61]
	v_mfma_f32_16x16x32_bf16 v[238:241], v[94:97], v[166:169], v[54:57]
	v_mfma_f32_16x16x32_bf16 v[242:245], v[94:97], v[186:189], v[50:53]
	s_setprio 0
	s_setprio 1
	v_mfma_f32_16x16x32_bf16 v[0:3], v[210:213], v[226:229], v[0:3]
	v_mfma_f32_16x16x32_bf16 v[28:31], v[82:85], v[150:153], v[28:31]
	v_mfma_f32_16x16x32_bf16 v[24:27], v[82:85], v[226:229], v[24:27]
	v_mfma_f32_16x16x32_bf16 v[20:23], v[90:93], v[150:153], v[20:23]
	v_mfma_f32_16x16x32_bf16 v[16:19], v[90:93], v[226:229], v[16:19]
	v_mfma_f32_16x16x32_bf16 v[12:15], v[202:205], v[150:153], v[12:15]
	v_mfma_f32_16x16x32_bf16 v[8:11], v[202:205], v[226:229], v[8:11]
	v_mfma_f32_16x16x32_bf16 v[4:7], v[210:213], v[150:153], v[4:7]
	v_mfma_f32_16x16x32_bf16 v[0:3], v[214:217], v[146:149], v[0:3]
	v_mfma_f32_16x16x32_bf16 v[154:157], v[86:89], v[222:225], v[28:31]
	v_mfma_f32_16x16x32_bf16 v[158:161], v[86:89], v[146:149], v[24:27]
	v_mfma_f32_16x16x32_bf16 v[166:169], v[94:97], v[222:225], v[20:23]
	v_mfma_f32_16x16x32_bf16 v[170:173], v[94:97], v[146:149], v[16:19]
	v_mfma_f32_16x16x32_bf16 v[186:189], v[206:209], v[222:225], v[12:15]
	v_mfma_f32_16x16x32_bf16 v[202:205], v[206:209], v[146:149], v[8:11]
	v_mfma_f32_16x16x32_bf16 v[150:153], v[214:217], v[222:225], v[4:7]
	s_setprio 0
	s_barrier
; #define LDA(dst, b, h) _Pragma("unroll") for (int m = 0; m < 4; ++m) _Pragma("unroll") for (int k = 0; k < 2; ++k) \
;     dst[m][k] = *reinterpret_cast<const bf16x8*>((char*)SA(b, h) + lds_byte(wr * 64 + m * 16 + fr, k * 32 + fq * 8))
; #define LDB(dst, b, h) _Pragma("unroll") for (int n = 0; n < 2; ++n) _Pragma("unroll") for (int k = 0; k < 2; ++k) \
;     dst[n][k] = *reinterpret_cast<const bf16x8*>((char*)SB(b, h) + lds_byte(wc * 32 + n * 16 + fr, k * 32 + fq * 8))
; #define MMA(ai, bj, At, Bt_) do { __builtin_amdgcn_s_setprio(1); \
;     _Pragma("unroll") for (int m = 0; m < 4; ++m) _Pragma("unroll") for (int n = 0; n < 2; ++n) _Pragma("unroll") for (int k = 0; k < 2; ++k) \
;       acc[ai][bj][m][n] = __builtin_amdgcn_mfma_f32_16x16x32_bf16(At[m][k], Bt_[n][k], acc[ai][bj][m][n], 0, 0, 0); \
;     __builtin_amdgcn_s_setprio(0); } while (0)
; #define WAIT_V(n) asm volatile("s_waitcnt vmcnt(" #n ")" ::: "memory")
; #define WAIT_L(n) asm volatile("s_waitcnt lgkmcnt(" #n ")" ::: "memory")
; #define BAR __builtin_amdgcn_s_barrier()
; template <class Epi> ...
;     ...
;   { LDB(B0, 1, 0); LDA(At, 1, 0); WAIT_V(2); BAR; WAIT_L(0); MMA(0, 0, At, B0); BAR;
;     LDB(B1, 1, 1); WAIT_V(0); BAR; WAIT_L(0); MMA(0, 1, At, B1); BAR;
;     LDA(At, 1, 1); BAR; WAIT_L(0); MMA(1, 0, At, B0); MMA(1, 1, At, B1); BAR; }
;   if (wr == 0) BAR;
	s_nop 0
	ds_read_b128 v[4:7], v145
	ds_read_b128 v[8:11], v145 offset:1024
	ds_read_b128 v[12:15], v145 offset:2048
	ds_read_b128 v[146:149], v145 offset:3072
	ds_read_b128 v[16:19], v143 offset:32768
	ds_read_b128 v[20:23], v143 offset:33792
	ds_read_b128 v[24:27], v142 offset:32768
	ds_read_b128 v[50:53], v142 offset:33792
	ds_read_b128 v[206:209], v141 offset:32768
	ds_read_b128 v[210:213], v141 offset:33792
	ds_read_b128 v[214:217], v140 offset:32768
	ds_read_b128 v[222:225], v140 offset:33792
	s_waitcnt vmcnt(2)
	s_barrier
	s_waitcnt lgkmcnt(0)
	s_setprio 1
	s_waitcnt lgkmcnt(7)
	v_mfma_f32_16x16x32_bf16 v[28:31], v[16:19], v[4:7], v[126:129]
	s_waitcnt lgkmcnt(6)
	v_mfma_f32_16x16x32_bf16 v[126:129], v[20:23], v[8:11], v[28:31]
	v_mfma_f32_16x16x32_bf16 v[28:31], v[16:19], v[12:15], v[122:125]
	v_mfma_f32_16x16x32_bf16 v[94:97], v[20:23], v[146:149], v[28:31]
	s_waitcnt lgkmcnt(5)
	v_mfma_f32_16x16x32_bf16 v[28:31], v[24:27], v[4:7], v[118:121]
	s_waitcnt lgkmcnt(4)
	v_mfma_f32_16x16x32_bf16 v[122:125], v[50:53], v[8:11], v[28:31]
	v_mfma_f32_16x16x32_bf16 v[28:31], v[24:27], v[12:15], v[114:117]
	v_mfma_f32_16x16x32_bf16 v[90:93], v[50:53], v[146:149], v[28:31]
	s_waitcnt lgkmcnt(3)
	v_mfma_f32_16x16x32_bf16 v[28:31], v[206:209], v[4:7], v[110:113]
	s_waitcnt lgkmcnt(2)
	v_mfma_f32_16x16x32_bf16 v[118:121], v[210:213], v[8:11], v[28:31]
	v_mfma_f32_16x16x32_bf16 v[28:31], v[206:209], v[12:15], v[106:109]
	v_mfma_f32_16x16x32_bf16 v[86:89], v[210:213], v[146:149], v[28:31]
	s_waitcnt lgkmcnt(1)
	v_mfma_f32_16x16x32_bf16 v[28:31], v[214:217], v[4:7], v[102:105]
	s_waitcnt lgkmcnt(0)
	v_mfma_f32_16x16x32_bf16 v[114:117], v[222:225], v[8:11], v[28:31]
	v_mfma_f32_16x16x32_bf16 v[28:31], v[214:217], v[12:15], v[98:101]
	v_mfma_f32_16x16x32_bf16 v[82:85], v[222:225], v[146:149], v[28:31]
	s_setprio 0
	s_barrier
	ds_read_b128 v[226:229], v144
	ds_read_b128 v[246:249], v144 offset:1024
	ds_read_b128 v[250:253], v144 offset:2048
	ds_read_b128 v[174:177], v144 offset:3072
	s_waitcnt vmcnt(0)
	s_barrier
	s_waitcnt lgkmcnt(0)
	s_setprio 1
	s_waitcnt lgkmcnt(3)
	v_mfma_f32_16x16x32_bf16 v[28:31], v[16:19], v[226:229], v[230:233]
	s_waitcnt lgkmcnt(1)
	v_mfma_f32_16x16x32_bf16 v[16:19], v[16:19], v[250:253], v[190:193]
	v_mfma_f32_16x16x32_bf16 v[62:65], v[20:23], v[246:249], v[28:31]
	s_waitcnt lgkmcnt(0)
	v_mfma_f32_16x16x32_bf16 v[28:31], v[20:23], v[174:177], v[16:19]
	v_mfma_f32_16x16x32_bf16 v[16:19], v[24:27], v[226:229], v[194:197]
	v_mfma_f32_16x16x32_bf16 v[58:61], v[50:53], v[246:249], v[16:19]
	v_mfma_f32_16x16x32_bf16 v[16:19], v[24:27], v[250:253], v[198:201]
	v_mfma_f32_16x16x32_bf16 v[24:27], v[50:53], v[174:177], v[16:19]
	v_mfma_f32_16x16x32_bf16 v[16:19], v[206:209], v[226:229], v[78:81]
	v_mfma_f32_16x16x32_bf16 v[54:57], v[210:213], v[246:249], v[16:19]
	v_mfma_f32_16x16x32_bf16 v[16:19], v[206:209], v[250:253], v[74:77]
	v_mfma_f32_16x16x32_bf16 v[20:23], v[210:213], v[174:177], v[16:19]
	v_mfma_f32_16x16x32_bf16 v[16:19], v[214:217], v[226:229], v[70:73]
	v_mfma_f32_16x16x32_bf16 v[50:53], v[222:225], v[246:249], v[16:19]
	v_mfma_f32_16x16x32_bf16 v[16:19], v[214:217], v[250:253], v[66:69]
	v_mfma_f32_16x16x32_bf16 v[16:19], v[222:225], v[174:177], v[16:19]
	s_setprio 0
	s_barrier
	ds_read_b128 v[190:193], v143 offset:49152
	ds_read_b128 v[194:197], v143 offset:50176
	ds_read_b128 v[198:201], v142 offset:49152
	ds_read_b128 v[142:145], v142 offset:50176
	ds_read_b128 v[206:209], v141 offset:49152
	ds_read_b128 v[210:213], v141 offset:50176
	ds_read_b128 v[214:217], v140 offset:49152
	ds_read_b128 v[222:225], v140 offset:50176
	s_barrier
	s_waitcnt lgkmcnt(0)
	s_setprio 1
	s_waitcnt lgkmcnt(7)
	v_mfma_f32_16x16x32_bf16 v[66:69], v[190:193], v[4:7], v[218:221]
	s_waitcnt lgkmcnt(6)
	v_mfma_f32_16x16x32_bf16 v[110:113], v[194:197], v[8:11], v[66:69]
	v_mfma_f32_16x16x32_bf16 v[66:69], v[190:193], v[12:15], v[234:237]
	v_mfma_f32_16x16x32_bf16 v[78:81], v[194:197], v[146:149], v[66:69]
	s_waitcnt lgkmcnt(5)
	v_mfma_f32_16x16x32_bf16 v[66:69], v[198:201], v[4:7], v[238:241]
	s_waitcnt lgkmcnt(3)
	v_mfma_f32_16x16x32_bf16 v[46:49], v[206:209], v[4:7], v[46:49]
	s_waitcnt lgkmcnt(1)
	v_mfma_f32_16x16x32_bf16 v[4:7], v[214:217], v[4:7], v[38:41]
	v_mfma_f32_16x16x32_bf16 v[106:109], v[142:145], v[8:11], v[66:69]
	v_mfma_f32_16x16x32_bf16 v[66:69], v[198:201], v[12:15], v[242:245]
	v_mfma_f32_16x16x32_bf16 v[42:45], v[206:209], v[12:15], v[42:45]
	s_waitcnt lgkmcnt(0)
	v_mfma_f32_16x16x32_bf16 v[98:101], v[222:225], v[8:11], v[4:7]
	v_mfma_f32_16x16x32_bf16 v[4:7], v[214:217], v[12:15], v[34:37]
	v_mfma_f32_16x16x32_bf16 v[74:77], v[142:145], v[146:149], v[66:69]
	v_mfma_f32_16x16x32_bf16 v[102:105], v[210:213], v[8:11], v[46:49]
	v_mfma_f32_16x16x32_bf16 v[70:73], v[210:213], v[146:149], v[42:45]
	v_mfma_f32_16x16x32_bf16 v[66:69], v[222:225], v[146:149], v[4:7]
	s_setprio 0
	s_setprio 1
	v_mfma_f32_16x16x32_bf16 v[4:7], v[190:193], v[226:229], v[154:157]
	v_mfma_f32_16x16x32_bf16 v[46:49], v[194:197], v[246:249], v[4:7]
	v_mfma_f32_16x16x32_bf16 v[4:7], v[190:193], v[250:253], v[158:161]
	v_mfma_f32_16x16x32_bf16 v[12:15], v[194:197], v[174:177], v[4:7]
	v_mfma_f32_16x16x32_bf16 v[4:7], v[198:201], v[226:229], v[166:169]
	v_mfma_f32_16x16x32_bf16 v[42:45], v[142:145], v[246:249], v[4:7]
	v_mfma_f32_16x16x32_bf16 v[4:7], v[198:201], v[250:253], v[170:173]
	v_mfma_f32_16x16x32_bf16 v[8:11], v[142:145], v[174:177], v[4:7]
	v_mfma_f32_16x16x32_bf16 v[4:7], v[206:209], v[226:229], v[186:189]
	v_mfma_f32_16x16x32_bf16 v[38:41], v[210:213], v[246:249], v[4:7]
	v_mfma_f32_16x16x32_bf16 v[4:7], v[206:209], v[250:253], v[202:205]
	v_mfma_f32_16x16x32_bf16 v[34:37], v[214:217], v[226:229], v[150:153]
	v_mfma_f32_16x16x32_bf16 v[0:3], v[214:217], v[250:253], v[0:3]
	v_mfma_f32_16x16x32_bf16 v[4:7], v[210:213], v[174:177], v[4:7]
	v_mfma_f32_16x16x32_bf16 v[34:37], v[222:225], v[246:249], v[34:37]
	v_mfma_f32_16x16x32_bf16 v[0:3], v[222:225], v[174:177], v[0:3]
	s_setprio 0
	v_cmp_gt_u32_e32 vcc, s59, v133
	s_barrier
	s_and_saveexec_b64 s[4:5], vcc
	s_cbranch_execz .LBB0_77
	s_barrier

; #define STAGE(P, BASE, br, kt) do { int _so = ((br) * K + (kt) * BK) * 2; \
;     __builtin_amdgcn_raw_ptr_buffer_load_lds(rs_##BASE, (__attribute__((address_space(3))) void*)((char*)(P) + tx * 16), 16, voff0, _so, 0, 0); \
;     __builtin_amdgcn_raw_ptr_buffer_load_lds(rs_##BASE, (__attribute__((address_space(3))) void*)((char*)(P) + tx * 16 + 8192), 16, voff1, _so, 0, 0); } while (0)
; #define LDA(dst, b, h) _Pragma("unroll") for (int m = 0; m < 4; ++m) _Pragma("unroll") for (int k = 0; k < 2; ++k) \
;     dst[m][k] = *reinterpret_cast<const bf16x8*>((char*)SA(b, h) + lds_byte(wr * 64 + m * 16 + fr, k * 32 + fq * 8))
; #define LDB(dst, b, h) _Pragma("unroll") for (int n = 0; n < 2; ++n) _Pragma("unroll") for (int k = 0; k < 2; ++k) \
;     dst[n][k] = *reinterpret_cast<const bf16x8*>((char*)SB(b, h) + lds_byte(wc * 32 + n * 16 + fr, k * 32 + fq * 8))
; #define MMA(ai, bj, At, Bt_) do { __builtin_amdgcn_s_setprio(1); \
;     _Pragma("unroll") for (int m = 0; m < 4; ++m) _Pragma("unroll") for (int n = 0; n < 2; ++n) _Pragma("unroll") for (int k = 0; k < 2; ++k) \
;       acc[ai][bj][m][n] = __builtin_amdgcn_mfma_f32_16x16x32_bf16(At[m][k], Bt_[n][k], acc[ai][bj][m][n], 0, 0, 0); \
;     __builtin_amdgcn_s_setprio(0); } while (0)
; #define WAIT_V(n) asm volatile("s_waitcnt vmcnt(" #n ")" ::: "memory")
; #define WAIT_L(n) asm volatile("s_waitcnt lgkmcnt(" #n ")" ::: "memory")
; #define BAR __builtin_amdgcn_s_barrier()
; template <class Epi> ...
;     ...
;   { LDB(B0, 0, 0); LDA(At, 0, 0); STAGE(SA(1, 1), A, brow + HALF, nt - 1);
;     BAR; WAIT_L(0); MMA(0, 0, At, B0); BAR;
;     LDB(B1, 0, 1); BAR; WAIT_L(0); MMA(0, 1, At, B1); BAR;
;     LDA(At, 0, 1); WAIT_V(4); BAR; WAIT_L(0); MMA(1, 0, At, B0); MMA(1, 1, At, B1); BAR; }
.Lpx1:
	v_readfirstlane_b32 s20, v152
	s_add_i32 s21, s21, 0x40780
	s_mov_b32 s6, s78
	s_mov_b32 s7, s79
	s_mov_b32 m0, s20
	v_readfirstlane_b32 s20, v151
	ds_read_b128 v[156:159], v155
	ds_read_b128 v[166:169], v155 offset:1024
	ds_read_b128 v[170:173], v155 offset:2048
	ds_read_b128 v[186:189], v155 offset:3072
	ds_read_b128 v[190:193], v143
	ds_read_b128 v[194:197], v143 offset:1024
	ds_read_b128 v[198:201], v142
	ds_read_b128 v[202:205], v142 offset:1024
	ds_read_b128 v[206:209], v141
	ds_read_b128 v[210:213], v141 offset:1024
	ds_read_b128 v[214:217], v140
	ds_read_b128 v[218:221], v140 offset:1024
	buffer_load_dwordx4 v32, s[4:7], s21 offen lds
	s_mov_b32 m0, s20
	s_nop 0
	buffer_load_dwordx4 v130, s[4:7], s21 offen lds
	s_barrier
	s_waitcnt lgkmcnt(0)
	s_setprio 1
	s_waitcnt lgkmcnt(7)
	v_mfma_f32_16x16x32_bf16 v[126:129], v[190:193], v[156:159], v[126:129]
	v_mfma_f32_16x16x32_bf16 v[122:125], v[190:193], v[170:173], v[122:125]
	s_waitcnt lgkmcnt(5)
	v_mfma_f32_16x16x32_bf16 v[114:117], v[198:201], v[170:173], v[114:117]
	s_waitcnt lgkmcnt(3)
	v_mfma_f32_16x16x32_bf16 v[106:109], v[206:209], v[170:173], v[106:109]
	s_waitcnt lgkmcnt(1)
	v_mfma_f32_16x16x32_bf16 v[102:105], v[214:217], v[156:159], v[102:105]
	v_mfma_f32_16x16x32_bf16 v[126:129], v[194:197], v[166:169], v[126:129]
	v_mfma_f32_16x16x32_bf16 v[122:125], v[194:197], v[186:189], v[122:125]
	v_mfma_f32_16x16x32_bf16 v[118:121], v[198:201], v[156:159], v[118:121]
	v_mfma_f32_16x16x32_bf16 v[114:117], v[202:205], v[186:189], v[114:117]
	v_mfma_f32_16x16x32_bf16 v[110:113], v[206:209], v[156:159], v[110:113]
	v_mfma_f32_16x16x32_bf16 v[106:109], v[210:213], v[186:189], v[106:109]
	s_waitcnt lgkmcnt(0)
	v_mfma_f32_16x16x32_bf16 v[102:105], v[218:221], v[166:169], v[102:105]
	v_mfma_f32_16x16x32_bf16 v[98:101], v[214:217], v[170:173], v[98:101]
	v_mfma_f32_16x16x32_bf16 v[150:153], v[202:205], v[166:169], v[118:121]
	v_mfma_f32_16x16x32_bf16 v[222:225], v[210:213], v[166:169], v[110:113]
	v_mfma_f32_16x16x32_bf16 v[226:229], v[218:221], v[186:189], v[98:101]
	s_setprio 0
	s_barrier
	s_nop 2
	ds_read_b128 v[98:101], v149
	ds_read_b128 v[110:113], v149 offset:1024
	ds_read_b128 v[118:121], v149 offset:2048
	ds_read_b128 v[146:149], v149 offset:3072
	s_barrier
	s_waitcnt lgkmcnt(0)
	s_setprio 1
	s_waitcnt lgkmcnt(1)
	v_mfma_f32_16x16x32_bf16 v[90:93], v[190:193], v[118:121], v[90:93]
	v_mfma_f32_16x16x32_bf16 v[86:89], v[198:201], v[98:101], v[86:89]
	v_mfma_f32_16x16x32_bf16 v[74:77], v[206:209], v[118:121], v[74:77]
	v_mfma_f32_16x16x32_bf16 v[70:73], v[214:217], v[98:101], v[70:73]
	v_mfma_f32_16x16x32_bf16 v[94:97], v[190:193], v[98:101], v[94:97]
	s_waitcnt lgkmcnt(0)
	v_mfma_f32_16x16x32_bf16 v[90:93], v[194:197], v[146:149], v[90:93]
	v_mfma_f32_16x16x32_bf16 v[86:89], v[202:205], v[110:113], v[86:89]
	v_mfma_f32_16x16x32_bf16 v[82:85], v[198:201], v[118:121], v[82:85]
	v_mfma_f32_16x16x32_bf16 v[78:81], v[206:209], v[98:101], v[78:81]
	v_mfma_f32_16x16x32_bf16 v[74:77], v[210:213], v[146:149], v[74:77]
	v_mfma_f32_16x16x32_bf16 v[70:73], v[218:221], v[110:113], v[70:73]
	v_mfma_f32_16x16x32_bf16 v[66:69], v[214:217], v[118:121], v[66:69]
	v_mfma_f32_16x16x32_bf16 v[230:233], v[194:197], v[110:113], v[94:97]
	v_mfma_f32_16x16x32_bf16 v[190:193], v[202:205], v[146:149], v[82:85]
	v_mfma_f32_16x16x32_bf16 v[194:197], v[210:213], v[110:113], v[78:81]
	v_mfma_f32_16x16x32_bf16 v[198:201], v[218:221], v[146:149], v[66:69]
	s_setprio 0
	s_barrier
	s_nop 1
	ds_read_b128 v[66:69], v143 offset:16384
	ds_read_b128 v[78:81], v143 offset:17408
	ds_read_b128 v[82:85], v142 offset:16384
	ds_read_b128 v[94:97], v142 offset:17408
	ds_read_b128 v[202:205], v141 offset:16384
	ds_read_b128 v[206:209], v141 offset:17408
	ds_read_b128 v[210:213], v140 offset:16384
	ds_read_b128 v[214:217], v140 offset:17408
	s_waitcnt vmcnt(4)
	s_barrier
	s_waitcnt lgkmcnt(0)
	s_setprio 1
	s_waitcnt lgkmcnt(7)
	v_mfma_f32_16x16x32_bf16 v[62:65], v[66:69], v[156:159], v[62:65]
	v_mfma_f32_16x16x32_bf16 v[58:61], v[66:69], v[170:173], v[58:61]
	s_waitcnt lgkmcnt(5)
	v_mfma_f32_16x16x32_bf16 v[54:57], v[82:85], v[156:159], v[54:57]
	v_mfma_f32_16x16x32_bf16 v[50:53], v[82:85], v[170:173], v[50:53]
	s_waitcnt lgkmcnt(3)
	v_mfma_f32_16x16x32_bf16 v[42:45], v[202:205], v[170:173], v[42:45]
	s_waitcnt lgkmcnt(1)
	v_mfma_f32_16x16x32_bf16 v[34:37], v[210:213], v[170:173], v[34:37]
	v_mfma_f32_16x16x32_bf16 v[62:65], v[78:81], v[166:169], v[62:65]
	v_mfma_f32_16x16x32_bf16 v[58:61], v[78:81], v[186:189], v[58:61]
	v_mfma_f32_16x16x32_bf16 v[54:57], v[94:97], v[166:169], v[54:57]
	v_mfma_f32_16x16x32_bf16 v[50:53], v[94:97], v[186:189], v[50:53]
	v_mfma_f32_16x16x32_bf16 v[46:49], v[202:205], v[156:159], v[46:49]
	v_mfma_f32_16x16x32_bf16 v[42:45], v[206:209], v[186:189], v[42:45]
	v_mfma_f32_16x16x32_bf16 v[38:41], v[210:213], v[156:159], v[38:41]
	s_waitcnt lgkmcnt(0)
	v_mfma_f32_16x16x32_bf16 v[34:37], v[214:217], v[186:189], v[34:37]
	v_mfma_f32_16x16x32_bf16 v[218:221], v[206:209], v[166:169], v[46:49]
	v_mfma_f32_16x16x32_bf16 v[154:157], v[214:217], v[166:169], v[38:41]
	s_setprio 0
	s_setprio 1
	v_mfma_f32_16x16x32_bf16 v[24:27], v[66:69], v[118:121], v[24:27]
	v_mfma_f32_16x16x32_bf16 v[16:19], v[82:85], v[118:121], v[16:19]
	v_mfma_f32_16x16x32_bf16 v[8:11], v[202:205], v[118:121], v[8:11]
	v_mfma_f32_16x16x32_bf16 v[0:3], v[210:213], v[118:121], v[0:3]
	v_mfma_f32_16x16x32_bf16 v[28:31], v[66:69], v[98:101], v[28:31]
	v_mfma_f32_16x16x32_bf16 v[24:27], v[78:81], v[146:149], v[24:27]
	v_mfma_f32_16x16x32_bf16 v[20:23], v[82:85], v[98:101], v[20:23]
	v_mfma_f32_16x16x32_bf16 v[16:19], v[94:97], v[146:149], v[16:19]
	v_mfma_f32_16x16x32_bf16 v[12:15], v[202:205], v[98:101], v[12:15]
	v_mfma_f32_16x16x32_bf16 v[8:11], v[206:209], v[146:149], v[8:11]
	v_mfma_f32_16x16x32_bf16 v[4:7], v[210:213], v[98:101], v[4:7]
	v_mfma_f32_16x16x32_bf16 v[0:3], v[214:217], v[146:149], v[0:3]
	v_mfma_f32_16x16x32_bf16 v[158:161], v[78:81], v[110:113], v[28:31]
	v_mfma_f32_16x16x32_bf16 v[166:169], v[94:97], v[110:113], v[20:23]
	v_mfma_f32_16x16x32_bf16 v[170:173], v[206:209], v[110:113], v[12:15]
	v_mfma_f32_16x16x32_bf16 v[186:189], v[214:217], v[110:113], v[4:7]
	s_setprio 0
	s_barrier
; #define LDA(dst, b, h) _Pragma("unroll") for (int m = 0; m < 4; ++m) _Pragma("unroll") for (int k = 0; k < 2; ++k) \
;     dst[m][k] = *reinterpret_cast<const bf16x8*>((char*)SA(b, h) + lds_byte(wr * 64 + m * 16 + fr, k * 32 + fq * 8))
; #define LDB(dst, b, h) _Pragma("unroll") for (int n = 0; n < 2; ++n) _Pragma("unroll") for (int k = 0; k < 2; ++k) \
;     dst[n][k] = *reinterpret_cast<const bf16x8*>((char*)SB(b, h) + lds_byte(wc * 32 + n * 16 + fr, k * 32 + fq * 8))
; #define MMA(ai, bj, At, Bt_) do { __builtin_amdgcn_s_setprio(1); \
;     _Pragma("unroll") for (int m = 0; m < 4; ++m) _Pragma("unroll") for (int n = 0; n < 2; ++n) _Pragma("unroll") for (int k = 0; k < 2; ++k) \
;       acc[ai][bj][m][n] = __builtin_amdgcn_mfma_f32_16x16x32_bf16(At[m][k], Bt_[n][k], acc[ai][bj][m][n], 0, 0, 0); \
;     __builtin_amdgcn_s_setprio(0); } while (0)
; #define WAIT_V(n) asm volatile("s_waitcnt vmcnt(" #n ")" ::: "memory")
; #define WAIT_L(n) asm volatile("s_waitcnt lgkmcnt(" #n ")" ::: "memory")
; #define BAR __builtin_amdgcn_s_barrier()
; template <class Epi> ...
;     ...
;   { LDB(B0, 1, 0); LDA(At, 1, 0); WAIT_V(2); BAR; WAIT_L(0); MMA(0, 0, At, B0); BAR;
;     LDB(B1, 1, 1); WAIT_V(0); BAR; WAIT_L(0); MMA(0, 1, At, B1); BAR;
;     LDA(At, 1, 1); BAR; WAIT_L(0); MMA(1, 0, At, B0); MMA(1, 1, At, B1); BAR; }
;   if (wr == 0) BAR;
	s_nop 0
	ds_read_b128 v[4:7], v145
	ds_read_b128 v[12:15], v145 offset:1024
	ds_read_b128 v[146:149], v145 offset:2048
	ds_read_b128 v[202:205], v145 offset:3072
	ds_read_b128 v[20:23], v143 offset:32768
	ds_read_b128 v[28:31], v143 offset:33792
	ds_read_b128 v[38:41], v142 offset:32768
	ds_read_b128 v[46:49], v142 offset:33792
	ds_read_b128 v[206:209], v141 offset:32768
	ds_read_b128 v[210:213], v141 offset:33792
	ds_read_b128 v[214:217], v140 offset:32768
	ds_read_b128 v[234:237], v140 offset:33792
	s_waitcnt vmcnt(2)
	s_barrier
	s_waitcnt lgkmcnt(0)
	s_setprio 1
	s_waitcnt lgkmcnt(7)
	v_mfma_f32_16x16x32_bf16 v[66:69], v[20:23], v[4:7], v[126:129]
	s_waitcnt lgkmcnt(6)
	v_mfma_f32_16x16x32_bf16 v[126:129], v[28:31], v[12:15], v[66:69]
	v_mfma_f32_16x16x32_bf16 v[66:69], v[20:23], v[146:149], v[122:125]
	v_mfma_f32_16x16x32_bf16 v[118:121], v[28:31], v[202:205], v[66:69]
	s_waitcnt lgkmcnt(5)
	v_mfma_f32_16x16x32_bf16 v[66:69], v[38:41], v[4:7], v[150:153]
	s_waitcnt lgkmcnt(4)
	v_mfma_f32_16x16x32_bf16 v[110:113], v[46:49], v[12:15], v[66:69]
	v_mfma_f32_16x16x32_bf16 v[66:69], v[38:41], v[146:149], v[114:117]
	v_mfma_f32_16x16x32_bf16 v[98:101], v[46:49], v[202:205], v[66:69]
	s_waitcnt lgkmcnt(3)
	v_mfma_f32_16x16x32_bf16 v[66:69], v[206:209], v[4:7], v[222:225]
	s_waitcnt lgkmcnt(2)
	v_mfma_f32_16x16x32_bf16 v[94:97], v[210:213], v[12:15], v[66:69]
	v_mfma_f32_16x16x32_bf16 v[66:69], v[206:209], v[146:149], v[106:109]
	v_mfma_f32_16x16x32_bf16 v[82:85], v[210:213], v[202:205], v[66:69]
	s_waitcnt lgkmcnt(1)
	v_mfma_f32_16x16x32_bf16 v[66:69], v[214:217], v[4:7], v[102:105]
	s_waitcnt lgkmcnt(0)
	v_mfma_f32_16x16x32_bf16 v[78:81], v[234:237], v[12:15], v[66:69]
	v_mfma_f32_16x16x32_bf16 v[66:69], v[214:217], v[146:149], v[226:229]
	v_mfma_f32_16x16x32_bf16 v[66:69], v[234:237], v[202:205], v[66:69]
	s_setprio 0
	s_barrier
	ds_read_b128 v[150:153], v144
	ds_read_b128 v[222:225], v144 offset:1024
	ds_read_b128 v[226:229], v144 offset:2048
	ds_read_b128 v[238:241], v144 offset:3072
	s_waitcnt vmcnt(0)
	s_barrier
	s_waitcnt lgkmcnt(0)
	s_setprio 1
	s_waitcnt lgkmcnt(3)
	v_mfma_f32_16x16x32_bf16 v[102:105], v[20:23], v[150:153], v[230:233]
	s_waitcnt lgkmcnt(1)
	v_mfma_f32_16x16x32_bf16 v[20:23], v[20:23], v[226:229], v[90:93]
	s_waitcnt lgkmcnt(0)
	v_mfma_f32_16x16x32_bf16 v[114:117], v[28:31], v[238:241], v[20:23]
	v_mfma_f32_16x16x32_bf16 v[20:23], v[38:41], v[150:153], v[86:89]
	v_mfma_f32_16x16x32_bf16 v[106:109], v[46:49], v[222:225], v[20:23]
	v_mfma_f32_16x16x32_bf16 v[20:23], v[38:41], v[226:229], v[190:193]
	v_mfma_f32_16x16x32_bf16 v[122:125], v[28:31], v[222:225], v[102:105]
	v_mfma_f32_16x16x32_bf16 v[102:105], v[46:49], v[238:241], v[20:23]
	v_mfma_f32_16x16x32_bf16 v[20:23], v[206:209], v[150:153], v[194:197]
	v_mfma_f32_16x16x32_bf16 v[90:93], v[210:213], v[222:225], v[20:23]
	v_mfma_f32_16x16x32_bf16 v[20:23], v[206:209], v[226:229], v[74:77]
	v_mfma_f32_16x16x32_bf16 v[86:89], v[210:213], v[238:241], v[20:23]
	v_mfma_f32_16x16x32_bf16 v[20:23], v[214:217], v[150:153], v[70:73]
	v_mfma_f32_16x16x32_bf16 v[74:77], v[234:237], v[222:225], v[20:23]
	v_mfma_f32_16x16x32_bf16 v[20:23], v[214:217], v[226:229], v[198:201]
	v_mfma_f32_16x16x32_bf16 v[70:73], v[234:237], v[238:241], v[20:23]
	s_setprio 0
	s_barrier
	ds_read_b128 v[190:193], v143 offset:49152
	ds_read_b128 v[194:197], v143 offset:50176
	ds_read_b128 v[198:201], v142 offset:49152
	ds_read_b128 v[142:145], v142 offset:50176
	ds_read_b128 v[206:209], v141 offset:49152
	ds_read_b128 v[210:213], v141 offset:50176
	ds_read_b128 v[214:217], v140 offset:49152
	ds_read_b128 v[230:233], v140 offset:50176
	s_barrier
	s_waitcnt lgkmcnt(0)
	s_setprio 1
	s_waitcnt lgkmcnt(7)
	v_mfma_f32_16x16x32_bf16 v[20:23], v[190:193], v[4:7], v[62:65]
	s_waitcnt lgkmcnt(6)
	v_mfma_f32_16x16x32_bf16 v[62:65], v[194:197], v[12:15], v[20:23]
	v_mfma_f32_16x16x32_bf16 v[20:23], v[190:193], v[146:149], v[58:61]
	v_mfma_f32_16x16x32_bf16 v[58:61], v[194:197], v[202:205], v[20:23]
	s_waitcnt lgkmcnt(5)
	v_mfma_f32_16x16x32_bf16 v[20:23], v[198:201], v[4:7], v[54:57]
	s_waitcnt lgkmcnt(4)
	v_mfma_f32_16x16x32_bf16 v[46:49], v[142:145], v[12:15], v[20:23]
	v_mfma_f32_16x16x32_bf16 v[20:23], v[198:201], v[146:149], v[50:53]
	v_mfma_f32_16x16x32_bf16 v[38:41], v[142:145], v[202:205], v[20:23]
	s_waitcnt lgkmcnt(3)
	v_mfma_f32_16x16x32_bf16 v[20:23], v[206:209], v[4:7], v[218:221]
	s_waitcnt lgkmcnt(1)
	v_mfma_f32_16x16x32_bf16 v[4:7], v[214:217], v[4:7], v[154:157]
	v_mfma_f32_16x16x32_bf16 v[28:31], v[210:213], v[12:15], v[20:23]
	v_mfma_f32_16x16x32_bf16 v[20:23], v[206:209], v[146:149], v[42:45]
	s_waitcnt lgkmcnt(0)
	v_mfma_f32_16x16x32_bf16 v[12:15], v[230:233], v[12:15], v[4:7]
	v_mfma_f32_16x16x32_bf16 v[4:7], v[214:217], v[146:149], v[34:37]
	v_mfma_f32_16x16x32_bf16 v[20:23], v[210:213], v[202:205], v[20:23]
	v_mfma_f32_16x16x32_bf16 v[4:7], v[230:233], v[202:205], v[4:7]
	s_setprio 0
	s_setprio 1
	v_mfma_f32_16x16x32_bf16 v[34:37], v[190:193], v[150:153], v[158:161]
	v_mfma_f32_16x16x32_bf16 v[24:27], v[190:193], v[226:229], v[24:27]
	v_mfma_f32_16x16x32_bf16 v[16:19], v[198:201], v[226:229], v[16:19]
	v_mfma_f32_16x16x32_bf16 v[54:57], v[194:197], v[222:225], v[34:37]
	v_mfma_f32_16x16x32_bf16 v[50:53], v[194:197], v[238:241], v[24:27]
	v_mfma_f32_16x16x32_bf16 v[24:27], v[198:201], v[150:153], v[166:169]
	v_mfma_f32_16x16x32_bf16 v[34:37], v[142:145], v[238:241], v[16:19]
	v_mfma_f32_16x16x32_bf16 v[16:19], v[206:209], v[150:153], v[170:173]
	v_mfma_f32_16x16x32_bf16 v[8:11], v[206:209], v[226:229], v[8:11]
	v_mfma_f32_16x16x32_bf16 v[42:45], v[142:145], v[222:225], v[24:27]
	v_mfma_f32_16x16x32_bf16 v[24:27], v[210:213], v[222:225], v[16:19]
	v_mfma_f32_16x16x32_bf16 v[16:19], v[210:213], v[238:241], v[8:11]
	v_mfma_f32_16x16x32_bf16 v[8:11], v[214:217], v[150:153], v[186:189]
	v_mfma_f32_16x16x32_bf16 v[0:3], v[214:217], v[226:229], v[0:3]
	v_mfma_f32_16x16x32_bf16 v[8:11], v[230:233], v[222:225], v[8:11]
	v_mfma_f32_16x16x32_bf16 v[0:3], v[230:233], v[238:241], v[0:3]
	s_setprio 0
	v_cmp_gt_u32_e32 vcc, s59, v133
	s_barrier
	s_and_saveexec_b64 s[4:5], vcc
	s_cbranch_execz .LBB0_1370
	s_barrier

; #define STAGE(P, BASE, br, kt) do { int _so = ((br) * K + (kt) * BK) * 2; \
;     __builtin_amdgcn_raw_ptr_buffer_load_lds(rs_##BASE, (__attribute__((address_space(3))) void*)((char*)(P) + tx * 16), 16, voff0, _so, 0, 0); \
;     __builtin_amdgcn_raw_ptr_buffer_load_lds(rs_##BASE, (__attribute__((address_space(3))) void*)((char*)(P) + tx * 16 + 8192), 16, voff1, _so, 0, 0); } while (0)
; #define LDA(dst, b, h) _Pragma("unroll") for (int m = 0; m < 4; ++m) _Pragma("unroll") for (int k = 0; k < 2; ++k) \
;     dst[m][k] = *reinterpret_cast<const bf16x8*>((char*)SA(b, h) + lds_byte(wr * 64 + m * 16 + fr, k * 32 + fq * 8))
; #define LDB(dst, b, h) _Pragma("unroll") for (int n = 0; n < 2; ++n) _Pragma("unroll") for (int k = 0; k < 2; ++k) \
;     dst[n][k] = *reinterpret_cast<const bf16x8*>((char*)SB(b, h) + lds_byte(wc * 32 + n * 16 + fr, k * 32 + fq * 8))
; #define WAIT_V(n) asm volatile("s_waitcnt vmcnt(" #n ")" ::: "memory")
; #define WAIT_L(n) asm volatile("s_waitcnt lgkmcnt(" #n ")" ::: "memory")
; #define BAR __builtin_amdgcn_s_barrier()
; #define SCHED __builtin_amdgcn_sched_barrier(0)
; template <class Epi> ...
;     ...
;   int wid = tx >> 6, lane = tx & 63, wr = wid >> 2, wc = wid & 3, fr = lane & 15, fq = lane >> 4;
;   f32x4 acc[2][2][4][2] = {};
;   bf16x8 At[4][2], B0[2][2], B1[2][2];
;   int nt = K / BK;
;   int voff0, voff1;
;   { int _r, _c; stage_rc(tx * 16, _r, _c); voff0 = (_r * K + _c) * 2; stage_rc(tx * 16 + 8192, _r, _c); voff1 = (_r * K + _c) * 2; }
;   __amdgpu_buffer_rsrc_t rs_A = __builtin_amdgcn_make_buffer_rsrc((void*)A, 0, 0x7fffffff, 0x00020000);
;   __amdgpu_buffer_rsrc_t rs_Bt = __builtin_amdgcn_make_buffer_rsrc((void*)Bt, 0, 0x7fffffff, 0x00020000);
;   if (!pre) {
;     STAGE(SB(0, 0), Bt, bcol, 0); STAGE(SA(0, 0), A, brow, 0);
;     STAGE(SB(0, 1), Bt, bcol + HALF, 0); STAGE(SA(0, 1), A, brow + HALF, 0);
;   }
;   if (wr == 1) BAR;
;   if (pre) { WAIT_V(0); } else { WAIT_V(4); }
;   BAR;
;   STAGE(SB(1, 0), Bt, bcol, 1); STAGE(SA(1, 0), A, brow, 1); STAGE(SB(1, 1), Bt, bcol + HALF, 1);
;   WAIT_V(6); BAR;
;   for (int t = 0; t < nt - 2; t += 2) {
;     LDB(B0, 0, 0); SCHED; LDA(At, 0, 0); STAGE(SA(1, 1), A, brow + HALF, t + 1);
;     WAIT_L(8); BAR; WAIT_L(0); MMA(0, 0, At, B0); BAR; SCHED;
;     LDB(B1, 0, 1); STAGE(SB(0, 0), Bt, bcol, t + 2);
;     BAR; WAIT_L(0); MMA(0, 1, At, B1); BAR;
.LBB0_1656:
	s_or_b64 exec, exec, s[6:7]
	v_readlane_b32 s28, v254, 30
	s_or_b32 s6, s25, 0x80
	v_add_u32_e32 v148, 0x8000, v140
	v_add_u32_e32 v146, s28, v0
	v_add_u32_e32 v147, 0x2000, v146
	v_readfirstlane_b32 s7, v146
	s_mov_b32 m0, s7
	v_readfirstlane_b32 s7, v147
	s_waitcnt vmcnt(4)
	s_barrier
	buffer_load_dwordx4 v134, s[76:79], s6 offen lds
	s_mov_b32 m0, s7
	v_readfirstlane_b32 s27, v148
	v_add_u32_e32 v150, 0xa000, v140
	v_readlane_b32 s29, v254, 31
	buffer_load_dwordx4 v135, s[76:79], s6 offen lds
	s_or_b32 s26, s24, 0x80
	s_mov_b32 s6, s78
	s_mov_b32 s7, s79
	s_mov_b32 m0, s27
	v_readfirstlane_b32 s27, v150
	v_add_u32_e32 v151, s29, v0
	buffer_load_dwordx4 v134, s[4:7], s26 offen lds
	s_mov_b32 m0, s27
	v_readfirstlane_b32 s27, v151
	v_add_u32_e32 v152, 0x2000, v151
	buffer_load_dwordx4 v135, s[4:7], s26 offen lds
	s_or_b32 s26, s25, 0x40080
	s_mov_b32 m0, s27
	v_readfirstlane_b32 s27, v152
	buffer_load_dwordx4 v134, s[76:79], s26 offen lds
	s_mov_b32 m0, s27
	v_and_b32_e32 v2, 15, v32
	buffer_load_dwordx4 v135, s[76:79], s26 offen lds
	v_lshlrev_b32_e32 v0, 6, v2
	v_lshlrev_b32_e32 v2, 2, v32
	v_and_b32_e32 v3, 48, v32
	v_and_b32_e32 v2, 32, v2
	v_bitop3_b32 v0, v0, v2, v3 bitop3:0x36
	v_lshlrev_b32_e32 v8, 6, v32
	s_movk_i32 s26, 0x3c0
	s_waitcnt vmcnt(6)
	v_add_u32_e32 v4, s71, v0
	v_add_u32_e32 v5, s73, v0
	v_add_u32_e32 v6, s28, v0
	v_add_u32_e32 v7, s29, v0
	v_lshlrev_b32_e32 v1, 13, v1
	v_add_u32_e32 v10, 0, v0
	v_and_or_b32 v0, v8, s26, v3
	v_and_b32_e32 v9, 0x3000, v8
	v_xad_u32 v2, v0, v2, 0
	v_or_b32_e32 v3, 0x800, v1
	v_or_b32_e32 v8, 0x1000, v1
	v_or_b32_e32 v11, 0x1800, v1
	s_mov_b32 s26, -2
	s_mov_b32 s27, 0
	v_add_u32_e32 v153, v4, v9
	v_add_u32_e32 v133, v10, v1
	v_add_u32_e32 v132, v2, v3
	v_add_u32_e32 v131, v2, v8
	v_add_u32_e32 v130, v2, v11
	v_add_u32_e32 v149, v5, v9
	v_add_u32_e32 v137, v6, v9
	v_add_u32_e32 v136, v7, v9
	v_add_u32_e32 v155, 0xc000, v140
	v_add_u32_e32 v154, 0xe000, v140
	s_barrier
.Lpk2:
	ds_read_b128 v[156:159], v153
	ds_read_b128 v[166:169], v153 offset:1024
	ds_read_b128 v[170:173], v153 offset:2048
	ds_read_b128 v[186:189], v153 offset:3072
	s_add_i32 s28, s24, s27
	v_readfirstlane_b32 s30, v155
	s_add_i32 s29, s28, 0x40080
	s_mov_b32 m0, s30
	v_readfirstlane_b32 s30, v154
	ds_read_b128 v[190:193], v133
	ds_read_b128 v[194:197], v133 offset:1024
	ds_read_b128 v[198:201], v132
	ds_read_b128 v[202:205], v132 offset:1024
	ds_read_b128 v[206:209], v131
	ds_read_b128 v[210:213], v131 offset:1024
	ds_read_b128 v[214:217], v130
	ds_read_b128 v[218:221], v130 offset:1024
	buffer_load_dwordx4 v134, s[4:7], s29 offen lds
	s_mov_b32 m0, s30
	s_nop 0
	buffer_load_dwordx4 v135, s[4:7], s29 offen lds
	s_waitcnt lgkmcnt(8)
	s_barrier
	s_waitcnt lgkmcnt(0)
	s_setprio 1
	s_waitcnt lgkmcnt(7)
	v_mfma_f32_16x16x32_bf16 v[126:129], v[190:193], v[156:159], 0
	v_mfma_f32_16x16x32_bf16 v[122:125], v[190:193], v[170:173], 0
	s_waitcnt lgkmcnt(5)
	v_mfma_f32_16x16x32_bf16 v[118:121], v[198:201], v[156:159], 0
	v_mfma_f32_16x16x32_bf16 v[114:117], v[198:201], v[170:173], 0
	s_waitcnt lgkmcnt(3)
	v_mfma_f32_16x16x32_bf16 v[110:113], v[206:209], v[156:159], 0
	v_mfma_f32_16x16x32_bf16 v[106:109], v[206:209], v[170:173], 0
	s_waitcnt lgkmcnt(1)
	v_mfma_f32_16x16x32_bf16 v[102:105], v[214:217], v[156:159], 0
	v_mfma_f32_16x16x32_bf16 v[98:101], v[214:217], v[170:173], 0
	v_mfma_f32_16x16x32_bf16 v[126:129], v[194:197], v[166:169], v[126:129]
	v_mfma_f32_16x16x32_bf16 v[122:125], v[194:197], v[186:189], v[122:125]
	v_mfma_f32_16x16x32_bf16 v[118:121], v[202:205], v[166:169], v[118:121]
	v_mfma_f32_16x16x32_bf16 v[114:117], v[202:205], v[186:189], v[114:117]
	v_mfma_f32_16x16x32_bf16 v[110:113], v[210:213], v[166:169], v[110:113]
	v_mfma_f32_16x16x32_bf16 v[106:109], v[210:213], v[186:189], v[106:109]
	s_waitcnt lgkmcnt(0)
	v_mfma_f32_16x16x32_bf16 v[102:105], v[218:221], v[166:169], v[102:105]
	v_mfma_f32_16x16x32_bf16 v[98:101], v[218:221], v[186:189], v[98:101]
	s_setprio 0
	s_barrier
	s_add_i32 s29, s25, s27
	v_readfirstlane_b32 s31, v138
	s_add_i32 s30, s29, 0x100
	s_mov_b32 m0, s31
	v_readfirstlane_b32 s31, v139
	ds_read_b128 v[222:225], v149
	ds_read_b128 v[226:229], v149 offset:1024
	ds_read_b128 v[230:233], v149 offset:2048
	ds_read_b128 v[234:237], v149 offset:3072
	buffer_load_dwordx4 v134, s[76:79], s30 offen lds
	s_mov_b32 m0, s31
	s_nop 0
	buffer_load_dwordx4 v135, s[76:79], s30 offen lds
	s_barrier
	s_waitcnt lgkmcnt(0)
	s_setprio 1
	s_waitcnt lgkmcnt(3)
	v_mfma_f32_16x16x32_bf16 v[94:97], v[190:193], v[222:225], 0
	s_waitcnt lgkmcnt(1)
	v_mfma_f32_16x16x32_bf16 v[90:93], v[190:193], v[230:233], 0
	v_mfma_f32_16x16x32_bf16 v[86:89], v[198:201], v[222:225], 0
	v_mfma_f32_16x16x32_bf16 v[82:85], v[198:201], v[230:233], 0
	v_mfma_f32_16x16x32_bf16 v[78:81], v[206:209], v[222:225], 0
	v_mfma_f32_16x16x32_bf16 v[74:77], v[206:209], v[230:233], 0
	v_mfma_f32_16x16x32_bf16 v[70:73], v[214:217], v[222:225], 0
	v_mfma_f32_16x16x32_bf16 v[66:69], v[214:217], v[230:233], 0
	v_mfma_f32_16x16x32_bf16 v[94:97], v[194:197], v[226:229], v[94:97]
	s_waitcnt lgkmcnt(0)
	v_mfma_f32_16x16x32_bf16 v[90:93], v[194:197], v[234:237], v[90:93]
	v_mfma_f32_16x16x32_bf16 v[86:89], v[202:205], v[226:229], v[86:89]
	v_mfma_f32_16x16x32_bf16 v[82:85], v[202:205], v[234:237], v[82:85]
	v_mfma_f32_16x16x32_bf16 v[78:81], v[210:213], v[226:229], v[78:81]
	v_mfma_f32_16x16x32_bf16 v[74:77], v[210:213], v[234:237], v[74:77]
	v_mfma_f32_16x16x32_bf16 v[70:73], v[218:221], v[226:229], v[70:73]
	v_mfma_f32_16x16x32_bf16 v[66:69], v[218:221], v[234:237], v[66:69]
	s_setprio 0
	v_readfirstlane_b32 s31, v140
	s_add_i32 s30, s28, 0x100
	s_mov_b32 m0, s31
	v_readfirstlane_b32 s31, v141
	s_barrier
; #define STAGE(P, BASE, br, kt) do { int _so = ((br) * K + (kt) * BK) * 2; \
;     __builtin_amdgcn_raw_ptr_buffer_load_lds(rs_##BASE, (__attribute__((address_space(3))) void*)((char*)(P) + tx * 16), 16, voff0, _so, 0, 0); \
;     __builtin_amdgcn_raw_ptr_buffer_load_lds(rs_##BASE, (__attribute__((address_space(3))) void*)((char*)(P) + tx * 16 + 8192), 16, voff1, _so, 0, 0); } while (0)
; #define LDA(dst, b, h) _Pragma("unroll") for (int m = 0; m < 4; ++m) _Pragma("unroll") for (int k = 0; k < 2; ++k) \
;     dst[m][k] = *reinterpret_cast<const bf16x8*>((char*)SA(b, h) + lds_byte(wr * 64 + m * 16 + fr, k * 32 + fq * 8))
; #define LDB(dst, b, h) _Pragma("unroll") for (int n = 0; n < 2; ++n) _Pragma("unroll") for (int k = 0; k < 2; ++k) \
;     dst[n][k] = *reinterpret_cast<const bf16x8*>((char*)SB(b, h) + lds_byte(wc * 32 + n * 16 + fr, k * 32 + fq * 8))
; #define MMA(ai, bj, At, Bt_) do { __builtin_amdgcn_s_setprio(1); \
;     _Pragma("unroll") for (int m = 0; m < 4; ++m) _Pragma("unroll") for (int n = 0; n < 2; ++n) _Pragma("unroll") for (int k = 0; k < 2; ++k) \
;       acc[ai][bj][m][n] = __builtin_amdgcn_mfma_f32_16x16x32_bf16(At[m][k], Bt_[n][k], acc[ai][bj][m][n], 0, 0, 0); \
;     __builtin_amdgcn_s_setprio(0); } while (0)
; #define WAIT_V(n) asm volatile("s_waitcnt vmcnt(" #n ")" ::: "memory")
; #define WAIT_L(n) asm volatile("s_waitcnt lgkmcnt(" #n ")" ::: "memory")
; #define BAR __builtin_amdgcn_s_barrier()
; #define SCHED __builtin_amdgcn_sched_barrier(0)
; template <class Epi> ...
;     ...
;     LDA(At, 0, 1); STAGE(SA(0, 0), A, brow, t + 2);
;     BAR; WAIT_L(0); MMA(1, 0, At, B0); BAR; SCHED;
;     STAGE(SB(0, 1), Bt, bcol + HALF, t + 2);
;     WAIT_V(6); BAR; MMA(1, 1, At, B1); BAR;
;     LDB(B0, 1, 0); SCHED; LDA(At, 1, 0); STAGE(SA(0, 1), A, brow + HALF, t + 2);
;     WAIT_L(8); BAR; WAIT_L(0); MMA(0, 0, At, B0); BAR; SCHED;
	ds_read_b128 v[190:193], v133 offset:16384
	ds_read_b128 v[194:197], v133 offset:17408
	ds_read_b128 v[198:201], v132 offset:16384
	ds_read_b128 v[202:205], v132 offset:17408
	ds_read_b128 v[206:209], v131 offset:16384
	ds_read_b128 v[210:213], v131 offset:17408
	ds_read_b128 v[214:217], v130 offset:16384
	ds_read_b128 v[218:221], v130 offset:17408
	buffer_load_dwordx4 v134, s[4:7], s30 offen lds
	s_mov_b32 m0, s31
	s_nop 0
	buffer_load_dwordx4 v135, s[4:7], s30 offen lds
	s_barrier
	s_waitcnt lgkmcnt(0)
	s_setprio 1
	s_waitcnt lgkmcnt(7)
	v_mfma_f32_16x16x32_bf16 v[62:65], v[190:193], v[156:159], 0
	v_mfma_f32_16x16x32_bf16 v[58:61], v[190:193], v[170:173], 0
	s_waitcnt lgkmcnt(5)
	v_mfma_f32_16x16x32_bf16 v[54:57], v[198:201], v[156:159], 0
	v_mfma_f32_16x16x32_bf16 v[50:53], v[198:201], v[170:173], 0
	s_waitcnt lgkmcnt(3)
	v_mfma_f32_16x16x32_bf16 v[46:49], v[206:209], v[156:159], 0
	v_mfma_f32_16x16x32_bf16 v[42:45], v[206:209], v[170:173], 0
	s_waitcnt lgkmcnt(1)
	v_mfma_f32_16x16x32_bf16 v[38:41], v[214:217], v[156:159], 0
	v_mfma_f32_16x16x32_bf16 v[34:37], v[214:217], v[170:173], 0
	v_mfma_f32_16x16x32_bf16 v[62:65], v[194:197], v[166:169], v[62:65]
	v_mfma_f32_16x16x32_bf16 v[58:61], v[194:197], v[186:189], v[58:61]
	v_mfma_f32_16x16x32_bf16 v[54:57], v[202:205], v[166:169], v[54:57]
	v_mfma_f32_16x16x32_bf16 v[50:53], v[202:205], v[186:189], v[50:53]
	v_mfma_f32_16x16x32_bf16 v[46:49], v[210:213], v[166:169], v[46:49]
	v_mfma_f32_16x16x32_bf16 v[42:45], v[210:213], v[186:189], v[42:45]
	s_waitcnt lgkmcnt(0)
	v_mfma_f32_16x16x32_bf16 v[38:41], v[218:221], v[166:169], v[38:41]
	v_mfma_f32_16x16x32_bf16 v[34:37], v[218:221], v[186:189], v[34:37]
	s_setprio 0
	s_barrier
	v_readfirstlane_b32 s31, v142
	s_add_i32 s30, s29, 0x40100
	s_mov_b32 m0, s31
	v_readfirstlane_b32 s31, v143
	buffer_load_dwordx4 v134, s[76:79], s30 offen lds
	s_mov_b32 m0, s31
	s_nop 0
	buffer_load_dwordx4 v135, s[76:79], s30 offen lds
	s_waitcnt vmcnt(6)
	s_barrier
	s_setprio 1
	v_mfma_f32_16x16x32_bf16 v[28:31], v[190:193], v[222:225], 0
	v_mfma_f32_16x16x32_bf16 v[24:27], v[190:193], v[230:233], 0
	v_mfma_f32_16x16x32_bf16 v[20:23], v[198:201], v[222:225], 0
	v_mfma_f32_16x16x32_bf16 v[16:19], v[198:201], v[230:233], 0
	v_mfma_f32_16x16x32_bf16 v[12:15], v[206:209], v[222:225], 0
	v_mfma_f32_16x16x32_bf16 v[8:11], v[206:209], v[230:233], 0
	v_mfma_f32_16x16x32_bf16 v[4:7], v[214:217], v[222:225], 0
	v_mfma_f32_16x16x32_bf16 v[0:3], v[214:217], v[230:233], 0
	v_mfma_f32_16x16x32_bf16 v[28:31], v[194:197], v[226:229], v[28:31]
	v_mfma_f32_16x16x32_bf16 v[24:27], v[194:197], v[234:237], v[24:27]
	v_mfma_f32_16x16x32_bf16 v[20:23], v[202:205], v[226:229], v[20:23]
	v_mfma_f32_16x16x32_bf16 v[16:19], v[202:205], v[234:237], v[16:19]
	v_mfma_f32_16x16x32_bf16 v[12:15], v[210:213], v[226:229], v[12:15]
	v_mfma_f32_16x16x32_bf16 v[8:11], v[210:213], v[234:237], v[8:11]
	v_mfma_f32_16x16x32_bf16 v[4:7], v[218:221], v[226:229], v[4:7]
	v_mfma_f32_16x16x32_bf16 v[0:3], v[218:221], v[234:237], v[0:3]
	s_setprio 0
	s_barrier
	ds_read_b128 v[156:159], v137
	ds_read_b128 v[166:169], v137 offset:1024
	ds_read_b128 v[170:173], v137 offset:2048
	ds_read_b128 v[186:189], v137 offset:3072
	v_readfirstlane_b32 s31, v144
	s_add_i32 s30, s28, 0x40100
	s_mov_b32 m0, s31
	v_readfirstlane_b32 s31, v145
	ds_read_b128 v[190:193], v133 offset:32768
	ds_read_b128 v[194:197], v133 offset:33792
	ds_read_b128 v[198:201], v132 offset:32768
	ds_read_b128 v[202:205], v132 offset:33792
	ds_read_b128 v[206:209], v131 offset:32768
	ds_read_b128 v[210:213], v131 offset:33792
	ds_read_b128 v[214:217], v130 offset:32768
	ds_read_b128 v[218:221], v130 offset:33792
	buffer_load_dwordx4 v134, s[4:7], s30 offen lds
	s_mov_b32 m0, s31
	s_nop 0
	buffer_load_dwordx4 v135, s[4:7], s30 offen lds
	s_waitcnt lgkmcnt(8)
	s_barrier
	s_waitcnt lgkmcnt(0)
	s_setprio 1
	s_waitcnt lgkmcnt(7)
	v_mfma_f32_16x16x32_bf16 v[126:129], v[190:193], v[156:159], v[126:129]
	v_mfma_f32_16x16x32_bf16 v[122:125], v[190:193], v[170:173], v[122:125]
	s_waitcnt lgkmcnt(5)
	v_mfma_f32_16x16x32_bf16 v[118:121], v[198:201], v[156:159], v[118:121]
	v_mfma_f32_16x16x32_bf16 v[114:117], v[198:201], v[170:173], v[114:117]
	s_waitcnt lgkmcnt(3)
	v_mfma_f32_16x16x32_bf16 v[110:113], v[206:209], v[156:159], v[110:113]
	v_mfma_f32_16x16x32_bf16 v[106:109], v[206:209], v[170:173], v[106:109]
	s_waitcnt lgkmcnt(1)
	v_mfma_f32_16x16x32_bf16 v[102:105], v[214:217], v[156:159], v[102:105]
	v_mfma_f32_16x16x32_bf16 v[98:101], v[214:217], v[170:173], v[98:101]
	v_mfma_f32_16x16x32_bf16 v[126:129], v[194:197], v[166:169], v[126:129]
	v_mfma_f32_16x16x32_bf16 v[122:125], v[194:197], v[186:189], v[122:125]
	v_mfma_f32_16x16x32_bf16 v[118:121], v[202:205], v[166:169], v[118:121]
	v_mfma_f32_16x16x32_bf16 v[114:117], v[202:205], v[186:189], v[114:117]
	v_mfma_f32_16x16x32_bf16 v[110:113], v[210:213], v[166:169], v[110:113]
	v_mfma_f32_16x16x32_bf16 v[106:109], v[210:213], v[186:189], v[106:109]
	s_waitcnt lgkmcnt(0)
	v_mfma_f32_16x16x32_bf16 v[102:105], v[218:221], v[166:169], v[102:105]
	v_mfma_f32_16x16x32_bf16 v[98:101], v[218:221], v[186:189], v[98:101]
	s_setprio 0
	s_barrier
; #define STAGE(P, BASE, br, kt) do { int _so = ((br) * K + (kt) * BK) * 2; \
;     __builtin_amdgcn_raw_ptr_buffer_load_lds(rs_##BASE, (__attribute__((address_space(3))) void*)((char*)(P) + tx * 16), 16, voff0, _so, 0, 0); \
;     __builtin_amdgcn_raw_ptr_buffer_load_lds(rs_##BASE, (__attribute__((address_space(3))) void*)((char*)(P) + tx * 16 + 8192), 16, voff1, _so, 0, 0); } while (0)
; #define LDA(dst, b, h) _Pragma("unroll") for (int m = 0; m < 4; ++m) _Pragma("unroll") for (int k = 0; k < 2; ++k) \
;     dst[m][k] = *reinterpret_cast<const bf16x8*>((char*)SA(b, h) + lds_byte(wr * 64 + m * 16 + fr, k * 32 + fq * 8))
; #define LDB(dst, b, h) _Pragma("unroll") for (int n = 0; n < 2; ++n) _Pragma("unroll") for (int k = 0; k < 2; ++k) \
;     dst[n][k] = *reinterpret_cast<const bf16x8*>((char*)SB(b, h) + lds_byte(wc * 32 + n * 16 + fr, k * 32 + fq * 8))
; #define MMA(ai, bj, At, Bt_) do { __builtin_amdgcn_s_setprio(1); \
;     _Pragma("unroll") for (int m = 0; m < 4; ++m) _Pragma("unroll") for (int n = 0; n < 2; ++n) _Pragma("unroll") for (int k = 0; k < 2; ++k) \
;       acc[ai][bj][m][n] = __builtin_amdgcn_mfma_f32_16x16x32_bf16(At[m][k], Bt_[n][k], acc[ai][bj][m][n], 0, 0, 0); \
;     __builtin_amdgcn_s_setprio(0); } while (0)
; #define WAIT_V(n) asm volatile("s_waitcnt vmcnt(" #n ")" ::: "memory")
; #define WAIT_L(n) asm volatile("s_waitcnt lgkmcnt(" #n ")" ::: "memory")
; #define BAR __builtin_amdgcn_s_barrier()
; #define SCHED __builtin_amdgcn_sched_barrier(0)
; template <class Epi> ...
;     ...
;     LDB(B1, 1, 1); STAGE(SB(1, 0), Bt, bcol, t + 3);
;     BAR; WAIT_L(0); MMA(0, 1, At, B1); BAR;
;     LDA(At, 1, 1); STAGE(SA(1, 0), A, brow, t + 3);
;     BAR; WAIT_L(0); MMA(1, 0, At, B0); BAR; SCHED;
;     STAGE(SB(1, 1), Bt, bcol + HALF, t + 3);
;     WAIT_V(6); BAR; MMA(1, 1, At, B1); BAR;
;   }
	v_readfirstlane_b32 s31, v146
	s_add_i32 s30, s29, 0x180
	s_mov_b32 m0, s31
	v_readfirstlane_b32 s31, v147
	ds_read_b128 v[222:225], v136
	ds_read_b128 v[226:229], v136 offset:1024
	ds_read_b128 v[230:233], v136 offset:2048
	ds_read_b128 v[234:237], v136 offset:3072
	buffer_load_dwordx4 v134, s[76:79], s30 offen lds
	s_mov_b32 m0, s31
	s_nop 0
	buffer_load_dwordx4 v135, s[76:79], s30 offen lds
	s_barrier
	s_waitcnt lgkmcnt(0)
	s_setprio 1
	s_waitcnt lgkmcnt(3)
	v_mfma_f32_16x16x32_bf16 v[94:97], v[190:193], v[222:225], v[94:97]
	s_waitcnt lgkmcnt(1)
	v_mfma_f32_16x16x32_bf16 v[90:93], v[190:193], v[230:233], v[90:93]
	v_mfma_f32_16x16x32_bf16 v[86:89], v[198:201], v[222:225], v[86:89]
	v_mfma_f32_16x16x32_bf16 v[82:85], v[198:201], v[230:233], v[82:85]
	v_mfma_f32_16x16x32_bf16 v[78:81], v[206:209], v[222:225], v[78:81]
	v_mfma_f32_16x16x32_bf16 v[74:77], v[206:209], v[230:233], v[74:77]
	v_mfma_f32_16x16x32_bf16 v[70:73], v[214:217], v[222:225], v[70:73]
	v_mfma_f32_16x16x32_bf16 v[66:69], v[214:217], v[230:233], v[66:69]
	v_mfma_f32_16x16x32_bf16 v[94:97], v[194:197], v[226:229], v[94:97]
	s_waitcnt lgkmcnt(0)
	v_mfma_f32_16x16x32_bf16 v[90:93], v[194:197], v[234:237], v[90:93]
	v_mfma_f32_16x16x32_bf16 v[86:89], v[202:205], v[226:229], v[86:89]
	v_mfma_f32_16x16x32_bf16 v[82:85], v[202:205], v[234:237], v[82:85]
	v_mfma_f32_16x16x32_bf16 v[78:81], v[210:213], v[226:229], v[78:81]
	v_mfma_f32_16x16x32_bf16 v[74:77], v[210:213], v[234:237], v[74:77]
	v_mfma_f32_16x16x32_bf16 v[70:73], v[218:221], v[226:229], v[70:73]
	v_mfma_f32_16x16x32_bf16 v[66:69], v[218:221], v[234:237], v[66:69]
	s_setprio 0
	v_readfirstlane_b32 s30, v148
	s_addk_i32 s28, 0x180
	s_mov_b32 m0, s30
	v_readfirstlane_b32 s30, v150
	s_barrier
	ds_read_b128 v[190:193], v133 offset:49152
	ds_read_b128 v[194:197], v133 offset:50176
	ds_read_b128 v[198:201], v132 offset:49152
	ds_read_b128 v[202:205], v132 offset:50176
	ds_read_b128 v[206:209], v131 offset:49152
	ds_read_b128 v[210:213], v131 offset:50176
	ds_read_b128 v[214:217], v130 offset:49152
	ds_read_b128 v[218:221], v130 offset:50176
	buffer_load_dwordx4 v134, s[4:7], s28 offen lds
	s_mov_b32 m0, s30
	s_nop 0
	buffer_load_dwordx4 v135, s[4:7], s28 offen lds
	s_barrier
	s_waitcnt lgkmcnt(0)
	s_setprio 1
	s_waitcnt lgkmcnt(7)
	v_mfma_f32_16x16x32_bf16 v[62:65], v[190:193], v[156:159], v[62:65]
	v_mfma_f32_16x16x32_bf16 v[58:61], v[190:193], v[170:173], v[58:61]
	s_waitcnt lgkmcnt(5)
	v_mfma_f32_16x16x32_bf16 v[54:57], v[198:201], v[156:159], v[54:57]
	v_mfma_f32_16x16x32_bf16 v[50:53], v[198:201], v[170:173], v[50:53]
	s_waitcnt lgkmcnt(3)
	v_mfma_f32_16x16x32_bf16 v[46:49], v[206:209], v[156:159], v[46:49]
	v_mfma_f32_16x16x32_bf16 v[42:45], v[206:209], v[170:173], v[42:45]
	s_waitcnt lgkmcnt(1)
	v_mfma_f32_16x16x32_bf16 v[38:41], v[214:217], v[156:159], v[38:41]
	v_mfma_f32_16x16x32_bf16 v[34:37], v[214:217], v[170:173], v[34:37]
	v_mfma_f32_16x16x32_bf16 v[62:65], v[194:197], v[166:169], v[62:65]
	v_mfma_f32_16x16x32_bf16 v[58:61], v[194:197], v[186:189], v[58:61]
	v_mfma_f32_16x16x32_bf16 v[54:57], v[202:205], v[166:169], v[54:57]
	v_mfma_f32_16x16x32_bf16 v[50:53], v[202:205], v[186:189], v[50:53]
	v_mfma_f32_16x16x32_bf16 v[46:49], v[210:213], v[166:169], v[46:49]
	v_mfma_f32_16x16x32_bf16 v[42:45], v[210:213], v[186:189], v[42:45]
	s_waitcnt lgkmcnt(0)
	v_mfma_f32_16x16x32_bf16 v[38:41], v[218:221], v[166:169], v[38:41]
	v_mfma_f32_16x16x32_bf16 v[34:37], v[218:221], v[186:189], v[34:37]
	s_setprio 0
	s_barrier
	v_readfirstlane_b32 s28, v151
	s_add_i32 s29, s29, 0x40180
	s_mov_b32 m0, s28
	v_readfirstlane_b32 s28, v152
	buffer_load_dwordx4 v134, s[76:79], s29 offen lds
	s_mov_b32 m0, s28
	s_nop 0
	buffer_load_dwordx4 v135, s[76:79], s29 offen lds
	s_waitcnt vmcnt(6)
	s_barrier
	s_setprio 1
	v_mfma_f32_16x16x32_bf16 v[28:31], v[190:193], v[222:225], v[28:31]
	v_mfma_f32_16x16x32_bf16 v[24:27], v[190:193], v[230:233], v[24:27]
	v_mfma_f32_16x16x32_bf16 v[20:23], v[198:201], v[222:225], v[20:23]
	v_mfma_f32_16x16x32_bf16 v[16:19], v[198:201], v[230:233], v[16:19]
	v_mfma_f32_16x16x32_bf16 v[12:15], v[206:209], v[222:225], v[12:15]
	v_mfma_f32_16x16x32_bf16 v[8:11], v[206:209], v[230:233], v[8:11]
	v_mfma_f32_16x16x32_bf16 v[4:7], v[214:217], v[222:225], v[4:7]
	v_mfma_f32_16x16x32_bf16 v[0:3], v[214:217], v[230:233], v[0:3]
	v_mfma_f32_16x16x32_bf16 v[28:31], v[194:197], v[226:229], v[28:31]
	v_mfma_f32_16x16x32_bf16 v[24:27], v[194:197], v[234:237], v[24:27]
	v_mfma_f32_16x16x32_bf16 v[20:23], v[202:205], v[226:229], v[20:23]
	v_mfma_f32_16x16x32_bf16 v[16:19], v[202:205], v[234:237], v[16:19]
	v_mfma_f32_16x16x32_bf16 v[12:15], v[210:213], v[226:229], v[12:15]
	v_mfma_f32_16x16x32_bf16 v[8:11], v[210:213], v[234:237], v[8:11]
	v_mfma_f32_16x16x32_bf16 v[4:7], v[218:221], v[226:229], v[4:7]
	v_mfma_f32_16x16x32_bf16 v[0:3], v[218:221], v[234:237], v[0:3]
	s_setprio 0
	s_add_i32 s26, s26, 2
	s_addk_i32 s27, 0x100
	s_cmp_lt_u32 s26, 12
	s_barrier
	s_cbranch_scc1 .LBB0_1657
	s_branch .Lpx2

; #define STAGE(P, BASE, br, kt) do { int _so = ((br) * K + (kt) * BK) * 2; \
;     __builtin_amdgcn_raw_ptr_buffer_load_lds(rs_##BASE, (__attribute__((address_space(3))) void*)((char*)(P) + tx * 16), 16, voff0, _so, 0, 0); \
;     __builtin_amdgcn_raw_ptr_buffer_load_lds(rs_##BASE, (__attribute__((address_space(3))) void*)((char*)(P) + tx * 16 + 8192), 16, voff1, _so, 0, 0); } while (0)
; #define LDA(dst, b, h) _Pragma("unroll") for (int m = 0; m < 4; ++m) _Pragma("unroll") for (int k = 0; k < 2; ++k) \
;     dst[m][k] = *reinterpret_cast<const bf16x8*>((char*)SA(b, h) + lds_byte(wr * 64 + m * 16 + fr, k * 32 + fq * 8))
; #define LDB(dst, b, h) _Pragma("unroll") for (int n = 0; n < 2; ++n) _Pragma("unroll") for (int k = 0; k < 2; ++k) \
;     dst[n][k] = *reinterpret_cast<const bf16x8*>((char*)SB(b, h) + lds_byte(wc * 32 + n * 16 + fr, k * 32 + fq * 8))
; #define MMA(ai, bj, At, Bt_) do { __builtin_amdgcn_s_setprio(1); \
;     _Pragma("unroll") for (int m = 0; m < 4; ++m) _Pragma("unroll") for (int n = 0; n < 2; ++n) _Pragma("unroll") for (int k = 0; k < 2; ++k) \
;       acc[ai][bj][m][n] = __builtin_amdgcn_mfma_f32_16x16x32_bf16(At[m][k], Bt_[n][k], acc[ai][bj][m][n], 0, 0, 0); \
;     __builtin_amdgcn_s_setprio(0); } while (0)
; #define WAIT_V(n) asm volatile("s_waitcnt vmcnt(" #n ")" ::: "memory")
; #define WAIT_L(n) asm volatile("s_waitcnt lgkmcnt(" #n ")" ::: "memory")
; #define BAR __builtin_amdgcn_s_barrier()
; template <class Epi> ...
;     ...
;   { LDB(B0, 0, 0); LDA(At, 0, 0); STAGE(SA(1, 1), A, brow + HALF, nt - 1);
;     BAR; WAIT_L(0); MMA(0, 0, At, B0); BAR;
;     LDB(B1, 0, 1); BAR; WAIT_L(0); MMA(0, 1, At, B1); BAR;
;     LDA(At, 0, 1); WAIT_V(4); BAR; WAIT_L(0); MMA(1, 0, At, B0); MMA(1, 1, At, B1); BAR; }
.Lpx2:
	v_readfirstlane_b32 s25, v155
	s_or_b32 s24, s24, 0x40780
	s_mov_b32 s6, s78
	s_mov_b32 s7, s79
	s_mov_b32 m0, s25
	v_readfirstlane_b32 s25, v154
	ds_read_b128 v[138:141], v153
	ds_read_b128 v[142:145], v153 offset:1024
	ds_read_b128 v[156:159], v153 offset:2048
	ds_read_b128 v[150:153], v153 offset:3072
	ds_read_b128 v[166:169], v133
	ds_read_b128 v[170:173], v133 offset:1024
	ds_read_b128 v[186:189], v132
	ds_read_b128 v[190:193], v132 offset:1024
	ds_read_b128 v[194:197], v131
	ds_read_b128 v[198:201], v131 offset:1024
	ds_read_b128 v[202:205], v130
	ds_read_b128 v[206:209], v130 offset:1024
	buffer_load_dwordx4 v134, s[4:7], s24 offen lds
	s_mov_b32 m0, s25
	s_nop 0
	buffer_load_dwordx4 v135, s[4:7], s24 offen lds
	s_barrier
	s_waitcnt lgkmcnt(0)
	s_setprio 1
	s_waitcnt lgkmcnt(7)
	v_mfma_f32_16x16x32_bf16 v[126:129], v[166:169], v[138:141], v[126:129]
	v_mfma_f32_16x16x32_bf16 v[122:125], v[166:169], v[156:159], v[122:125]
	s_waitcnt lgkmcnt(5)
	v_mfma_f32_16x16x32_bf16 v[118:121], v[186:189], v[138:141], v[118:121]
	v_mfma_f32_16x16x32_bf16 v[114:117], v[186:189], v[156:159], v[114:117]
	s_waitcnt lgkmcnt(3)
	v_mfma_f32_16x16x32_bf16 v[110:113], v[194:197], v[138:141], v[110:113]
	v_mfma_f32_16x16x32_bf16 v[106:109], v[194:197], v[156:159], v[106:109]
	s_waitcnt lgkmcnt(1)
	v_mfma_f32_16x16x32_bf16 v[102:105], v[202:205], v[138:141], v[102:105]
	v_mfma_f32_16x16x32_bf16 v[98:101], v[202:205], v[156:159], v[98:101]
	v_mfma_f32_16x16x32_bf16 v[126:129], v[170:173], v[142:145], v[126:129]
	v_mfma_f32_16x16x32_bf16 v[122:125], v[170:173], v[150:153], v[122:125]
	v_mfma_f32_16x16x32_bf16 v[118:121], v[190:193], v[142:145], v[118:121]
	v_mfma_f32_16x16x32_bf16 v[114:117], v[190:193], v[150:153], v[114:117]
	v_mfma_f32_16x16x32_bf16 v[110:113], v[198:201], v[142:145], v[110:113]
	v_mfma_f32_16x16x32_bf16 v[106:109], v[198:201], v[150:153], v[106:109]
	s_waitcnt lgkmcnt(0)
	v_mfma_f32_16x16x32_bf16 v[102:105], v[206:209], v[142:145], v[102:105]
	v_mfma_f32_16x16x32_bf16 v[98:101], v[206:209], v[150:153], v[98:101]
	s_setprio 0
	s_barrier
	ds_read_b128 v[210:213], v149
	ds_read_b128 v[214:217], v149 offset:1024
	ds_read_b128 v[218:221], v149 offset:2048
	ds_read_b128 v[146:149], v149 offset:3072
	s_barrier
	s_waitcnt lgkmcnt(0)
	s_setprio 1
	s_waitcnt lgkmcnt(3)
	v_mfma_f32_16x16x32_bf16 v[94:97], v[166:169], v[210:213], v[94:97]
	s_waitcnt lgkmcnt(1)
	v_mfma_f32_16x16x32_bf16 v[90:93], v[166:169], v[218:221], v[90:93]
	v_mfma_f32_16x16x32_bf16 v[82:85], v[186:189], v[218:221], v[82:85]
	v_mfma_f32_16x16x32_bf16 v[78:81], v[194:197], v[210:213], v[78:81]
	v_mfma_f32_16x16x32_bf16 v[66:69], v[202:205], v[218:221], v[66:69]
	v_mfma_f32_16x16x32_bf16 v[94:97], v[170:173], v[214:217], v[94:97]
	s_waitcnt lgkmcnt(0)
	v_mfma_f32_16x16x32_bf16 v[90:93], v[170:173], v[146:149], v[90:93]
	v_mfma_f32_16x16x32_bf16 v[86:89], v[186:189], v[210:213], v[86:89]
	v_mfma_f32_16x16x32_bf16 v[82:85], v[190:193], v[146:149], v[82:85]
	v_mfma_f32_16x16x32_bf16 v[78:81], v[198:201], v[214:217], v[78:81]
	v_mfma_f32_16x16x32_bf16 v[74:77], v[194:197], v[218:221], v[74:77]
	v_mfma_f32_16x16x32_bf16 v[70:73], v[202:205], v[210:213], v[70:73]
	v_mfma_f32_16x16x32_bf16 v[66:69], v[206:209], v[146:149], v[66:69]
	v_mfma_f32_16x16x32_bf16 v[166:169], v[190:193], v[214:217], v[86:89]
	v_mfma_f32_16x16x32_bf16 v[170:173], v[198:201], v[146:149], v[74:77]
	v_mfma_f32_16x16x32_bf16 v[186:189], v[206:209], v[214:217], v[70:73]
	s_setprio 0
	s_barrier
	s_nop 1
	ds_read_b128 v[70:73], v133 offset:16384
	ds_read_b128 v[74:77], v133 offset:17408
	ds_read_b128 v[86:89], v132 offset:16384
	ds_read_b128 v[190:193], v132 offset:17408
	ds_read_b128 v[194:197], v131 offset:16384
	ds_read_b128 v[198:201], v131 offset:17408
	ds_read_b128 v[202:205], v130 offset:16384
	ds_read_b128 v[206:209], v130 offset:17408
	s_waitcnt vmcnt(4)
	s_barrier
	s_waitcnt lgkmcnt(0)
	s_setprio 1
	s_waitcnt lgkmcnt(7)
	v_mfma_f32_16x16x32_bf16 v[62:65], v[70:73], v[138:141], v[62:65]
	s_waitcnt lgkmcnt(5)
	v_mfma_f32_16x16x32_bf16 v[50:53], v[86:89], v[156:159], v[50:53]
	s_waitcnt lgkmcnt(3)
	v_mfma_f32_16x16x32_bf16 v[46:49], v[194:197], v[138:141], v[46:49]
	v_mfma_f32_16x16x32_bf16 v[62:65], v[74:77], v[142:145], v[62:65]
	v_mfma_f32_16x16x32_bf16 v[58:61], v[70:73], v[156:159], v[58:61]
	v_mfma_f32_16x16x32_bf16 v[54:57], v[86:89], v[138:141], v[54:57]
	v_mfma_f32_16x16x32_bf16 v[50:53], v[190:193], v[150:153], v[50:53]
	s_waitcnt lgkmcnt(2)
	v_mfma_f32_16x16x32_bf16 v[46:49], v[198:201], v[142:145], v[46:49]
	v_mfma_f32_16x16x32_bf16 v[42:45], v[194:197], v[156:159], v[42:45]
	s_waitcnt lgkmcnt(1)
	v_mfma_f32_16x16x32_bf16 v[38:41], v[202:205], v[138:141], v[38:41]
	v_mfma_f32_16x16x32_bf16 v[34:37], v[202:205], v[156:159], v[34:37]
	v_mfma_f32_16x16x32_bf16 v[222:225], v[74:77], v[150:153], v[58:61]
	v_mfma_f32_16x16x32_bf16 v[226:229], v[190:193], v[142:145], v[54:57]
	v_mfma_f32_16x16x32_bf16 v[230:233], v[198:201], v[150:153], v[42:45]
	s_waitcnt lgkmcnt(0)
	v_mfma_f32_16x16x32_bf16 v[138:141], v[206:209], v[142:145], v[38:41]
	v_mfma_f32_16x16x32_bf16 v[142:145], v[206:209], v[150:153], v[34:37]
	s_setprio 0
	s_setprio 1
	v_mfma_f32_16x16x32_bf16 v[0:3], v[202:205], v[218:221], v[0:3]
	v_mfma_f32_16x16x32_bf16 v[28:31], v[70:73], v[210:213], v[28:31]
	v_mfma_f32_16x16x32_bf16 v[24:27], v[70:73], v[218:221], v[24:27]
	v_mfma_f32_16x16x32_bf16 v[20:23], v[86:89], v[210:213], v[20:23]
	v_mfma_f32_16x16x32_bf16 v[16:19], v[86:89], v[218:221], v[16:19]
	v_mfma_f32_16x16x32_bf16 v[12:15], v[194:197], v[210:213], v[12:15]
	v_mfma_f32_16x16x32_bf16 v[8:11], v[194:197], v[218:221], v[8:11]
	v_mfma_f32_16x16x32_bf16 v[4:7], v[202:205], v[210:213], v[4:7]
	v_mfma_f32_16x16x32_bf16 v[0:3], v[206:209], v[146:149], v[0:3]
	v_mfma_f32_16x16x32_bf16 v[150:153], v[74:77], v[214:217], v[28:31]
	v_mfma_f32_16x16x32_bf16 v[154:157], v[74:77], v[146:149], v[24:27]
	v_mfma_f32_16x16x32_bf16 v[158:161], v[190:193], v[214:217], v[20:23]
	v_mfma_f32_16x16x32_bf16 v[190:193], v[190:193], v[146:149], v[16:19]
	v_mfma_f32_16x16x32_bf16 v[234:237], v[198:201], v[214:217], v[12:15]
	v_mfma_f32_16x16x32_bf16 v[194:197], v[198:201], v[146:149], v[8:11]
	v_mfma_f32_16x16x32_bf16 v[198:201], v[206:209], v[214:217], v[4:7]
	s_setprio 0
	s_barrier
; #define LDA(dst, b, h) _Pragma("unroll") for (int m = 0; m < 4; ++m) _Pragma("unroll") for (int k = 0; k < 2; ++k) \
;     dst[m][k] = *reinterpret_cast<const bf16x8*>((char*)SA(b, h) + lds_byte(wr * 64 + m * 16 + fr, k * 32 + fq * 8))
; #define LDB(dst, b, h) _Pragma("unroll") for (int n = 0; n < 2; ++n) _Pragma("unroll") for (int k = 0; k < 2; ++k) \
;     dst[n][k] = *reinterpret_cast<const bf16x8*>((char*)SB(b, h) + lds_byte(wc * 32 + n * 16 + fr, k * 32 + fq * 8))
; #define MMA(ai, bj, At, Bt_) do { __builtin_amdgcn_s_setprio(1); \
;     _Pragma("unroll") for (int m = 0; m < 4; ++m) _Pragma("unroll") for (int n = 0; n < 2; ++n) _Pragma("unroll") for (int k = 0; k < 2; ++k) \
;       acc[ai][bj][m][n] = __builtin_amdgcn_mfma_f32_16x16x32_bf16(At[m][k], Bt_[n][k], acc[ai][bj][m][n], 0, 0, 0); \
;     __builtin_amdgcn_s_setprio(0); } while (0)
; #define WAIT_V(n) asm volatile("s_waitcnt vmcnt(" #n ")" ::: "memory")
; #define WAIT_L(n) asm volatile("s_waitcnt lgkmcnt(" #n ")" ::: "memory")
; #define BAR __builtin_amdgcn_s_barrier()
; template <class Epi> ...
;     ...
;   { LDB(B0, 1, 0); LDA(At, 1, 0); WAIT_V(2); BAR; WAIT_L(0); MMA(0, 0, At, B0); BAR;
;     LDB(B1, 1, 1); WAIT_V(0); BAR; WAIT_L(0); MMA(0, 1, At, B1); BAR;
;     LDA(At, 1, 1); BAR; WAIT_L(0); MMA(1, 0, At, B0); MMA(1, 1, At, B1); BAR; }
;   if (wr == 0) BAR;
	ds_read_b128 v[146:149], v137
	ds_read_b128 v[202:205], v137 offset:1024
	ds_read_b128 v[206:209], v137 offset:2048
	ds_read_b128 v[210:213], v137 offset:3072
	ds_read_b128 v[38:41], v133 offset:32768
	ds_read_b128 v[42:45], v133 offset:33792
	ds_read_b128 v[54:57], v132 offset:32768
	ds_read_b128 v[58:61], v132 offset:33792
	ds_read_b128 v[214:217], v131 offset:32768
	ds_read_b128 v[218:221], v131 offset:33792
	ds_read_b128 v[238:241], v130 offset:32768
	ds_read_b128 v[242:245], v130 offset:33792
	s_waitcnt vmcnt(2)
	s_barrier
	s_waitcnt lgkmcnt(0)
	s_setprio 1
	s_waitcnt lgkmcnt(7)
	v_mfma_f32_16x16x32_bf16 v[4:7], v[38:41], v[146:149], v[126:129]
	s_waitcnt lgkmcnt(6)
	v_mfma_f32_16x16x32_bf16 v[28:31], v[42:45], v[202:205], v[4:7]
	v_mfma_f32_16x16x32_bf16 v[4:7], v[38:41], v[206:209], v[122:125]
	v_mfma_f32_16x16x32_bf16 v[34:37], v[42:45], v[210:213], v[4:7]
	s_waitcnt lgkmcnt(5)
	v_mfma_f32_16x16x32_bf16 v[4:7], v[54:57], v[146:149], v[118:121]
	s_waitcnt lgkmcnt(4)
	v_mfma_f32_16x16x32_bf16 v[20:23], v[58:61], v[202:205], v[4:7]
	v_mfma_f32_16x16x32_bf16 v[4:7], v[54:57], v[206:209], v[114:117]
	v_mfma_f32_16x16x32_bf16 v[24:27], v[58:61], v[210:213], v[4:7]
	s_waitcnt lgkmcnt(3)
	v_mfma_f32_16x16x32_bf16 v[4:7], v[214:217], v[146:149], v[110:113]
	s_waitcnt lgkmcnt(2)
	v_mfma_f32_16x16x32_bf16 v[12:15], v[218:221], v[202:205], v[4:7]
	v_mfma_f32_16x16x32_bf16 v[4:7], v[214:217], v[206:209], v[106:109]
	v_mfma_f32_16x16x32_bf16 v[16:19], v[218:221], v[210:213], v[4:7]
	s_waitcnt lgkmcnt(1)
	v_mfma_f32_16x16x32_bf16 v[4:7], v[238:241], v[146:149], v[102:105]
	v_mfma_f32_16x16x32_bf16 v[8:11], v[238:241], v[206:209], v[98:101]
	s_waitcnt lgkmcnt(0)
	v_mfma_f32_16x16x32_bf16 v[4:7], v[242:245], v[202:205], v[4:7]
	v_mfma_f32_16x16x32_bf16 v[8:11], v[242:245], v[210:213], v[8:11]
	s_setprio 0
	s_barrier
	ds_read_b128 v[102:105], v136
	ds_read_b128 v[246:249], v136 offset:1024
	ds_read_b128 v[250:253], v136 offset:2048
	ds_read_b128 v[134:137], v136 offset:3072
	s_waitcnt vmcnt(0)
	s_barrier
	s_waitcnt lgkmcnt(0)
	s_setprio 1
	s_waitcnt lgkmcnt(3)
	v_mfma_f32_16x16x32_bf16 v[70:73], v[38:41], v[102:105], v[94:97]
	s_waitcnt lgkmcnt(1)
	v_mfma_f32_16x16x32_bf16 v[38:41], v[38:41], v[250:253], v[90:93]
	s_waitcnt lgkmcnt(0)
	v_mfma_f32_16x16x32_bf16 v[90:93], v[42:45], v[134:137], v[38:41]
	v_mfma_f32_16x16x32_bf16 v[38:41], v[54:57], v[102:105], v[166:169]
	v_mfma_f32_16x16x32_bf16 v[86:89], v[42:45], v[246:249], v[70:73]
	v_mfma_f32_16x16x32_bf16 v[70:73], v[58:61], v[246:249], v[38:41]
	v_mfma_f32_16x16x32_bf16 v[38:41], v[54:57], v[250:253], v[82:85]
	v_mfma_f32_16x16x32_bf16 v[74:77], v[58:61], v[134:137], v[38:41]
	v_mfma_f32_16x16x32_bf16 v[38:41], v[214:217], v[102:105], v[78:81]
	v_mfma_f32_16x16x32_bf16 v[54:57], v[218:221], v[246:249], v[38:41]
	v_mfma_f32_16x16x32_bf16 v[38:41], v[214:217], v[250:253], v[170:173]
	v_mfma_f32_16x16x32_bf16 v[58:61], v[218:221], v[134:137], v[38:41]
	v_mfma_f32_16x16x32_bf16 v[38:41], v[238:241], v[102:105], v[186:189]
	v_mfma_f32_16x16x32_bf16 v[42:45], v[238:241], v[250:253], v[66:69]
	v_mfma_f32_16x16x32_bf16 v[38:41], v[242:245], v[246:249], v[38:41]
	v_mfma_f32_16x16x32_bf16 v[42:45], v[242:245], v[134:137], v[42:45]
	s_setprio 0
	s_barrier
	ds_read_b128 v[106:109], v133 offset:49152
	ds_read_b128 v[110:113], v133 offset:50176
	ds_read_b128 v[118:121], v132 offset:49152
	ds_read_b128 v[166:169], v132 offset:50176
	ds_read_b128 v[170:173], v131 offset:49152
	ds_read_b128 v[186:189], v131 offset:50176
	ds_read_b128 v[214:217], v130 offset:49152
	ds_read_b128 v[130:133], v130 offset:50176
	s_barrier
	s_waitcnt lgkmcnt(0)
	s_setprio 1
	s_waitcnt lgkmcnt(7)
	v_mfma_f32_16x16x32_bf16 v[62:65], v[106:109], v[146:149], v[62:65]
	s_waitcnt lgkmcnt(6)
	v_mfma_f32_16x16x32_bf16 v[94:97], v[110:113], v[202:205], v[62:65]
	v_mfma_f32_16x16x32_bf16 v[62:65], v[106:109], v[206:209], v[222:225]
	v_mfma_f32_16x16x32_bf16 v[98:101], v[110:113], v[210:213], v[62:65]
	s_waitcnt lgkmcnt(5)
	v_mfma_f32_16x16x32_bf16 v[62:65], v[118:121], v[146:149], v[226:229]
	s_waitcnt lgkmcnt(3)
	v_mfma_f32_16x16x32_bf16 v[46:49], v[170:173], v[146:149], v[46:49]
	v_mfma_f32_16x16x32_bf16 v[78:81], v[166:169], v[202:205], v[62:65]
	v_mfma_f32_16x16x32_bf16 v[50:53], v[118:121], v[206:209], v[50:53]
	s_waitcnt lgkmcnt(2)
	v_mfma_f32_16x16x32_bf16 v[62:65], v[186:189], v[202:205], v[46:49]
	v_mfma_f32_16x16x32_bf16 v[46:49], v[170:173], v[206:209], v[230:233]
	v_mfma_f32_16x16x32_bf16 v[82:85], v[166:169], v[210:213], v[50:53]
	v_mfma_f32_16x16x32_bf16 v[66:69], v[186:189], v[210:213], v[46:49]
	s_waitcnt lgkmcnt(1)
	v_mfma_f32_16x16x32_bf16 v[46:49], v[214:217], v[146:149], v[138:141]
	v_mfma_f32_16x16x32_bf16 v[50:53], v[214:217], v[206:209], v[142:145]
	s_waitcnt lgkmcnt(0)
	v_mfma_f32_16x16x32_bf16 v[46:49], v[130:133], v[202:205], v[46:49]
	v_mfma_f32_16x16x32_bf16 v[50:53], v[130:133], v[210:213], v[50:53]
	s_setprio 0
	s_setprio 1
	v_mfma_f32_16x16x32_bf16 v[114:117], v[106:109], v[102:105], v[150:153]
	v_mfma_f32_16x16x32_bf16 v[106:109], v[106:109], v[250:253], v[154:157]
	v_mfma_f32_16x16x32_bf16 v[126:129], v[110:113], v[134:137], v[106:109]
	v_mfma_f32_16x16x32_bf16 v[106:109], v[118:121], v[102:105], v[158:161]
	v_mfma_f32_16x16x32_bf16 v[122:125], v[110:113], v[246:249], v[114:117]
	v_mfma_f32_16x16x32_bf16 v[114:117], v[166:169], v[246:249], v[106:109]
	v_mfma_f32_16x16x32_bf16 v[106:109], v[118:121], v[250:253], v[190:193]
	v_mfma_f32_16x16x32_bf16 v[118:121], v[166:169], v[134:137], v[106:109]
	v_mfma_f32_16x16x32_bf16 v[106:109], v[170:173], v[102:105], v[234:237]
	v_mfma_f32_16x16x32_bf16 v[110:113], v[170:173], v[250:253], v[194:197]
	v_mfma_f32_16x16x32_bf16 v[102:105], v[214:217], v[102:105], v[198:201]
	v_mfma_f32_16x16x32_bf16 v[0:3], v[214:217], v[250:253], v[0:3]
	v_mfma_f32_16x16x32_bf16 v[106:109], v[186:189], v[246:249], v[106:109]
	v_mfma_f32_16x16x32_bf16 v[110:113], v[186:189], v[134:137], v[110:113]
	v_mfma_f32_16x16x32_bf16 v[102:105], v[130:133], v[246:249], v[102:105]
	v_mfma_f32_16x16x32_bf16 v[0:3], v[130:133], v[134:137], v[0:3]
	s_setprio 0
	v_cmp_gt_u32_e32 vcc, s59, v32
	s_barrier
	s_and_saveexec_b64 s[4:5], vcc
	s_cbranch_execz .LBB0_1660
	s_barrier

; #define STAGE(P, BASE, br, kt) do { int _so = ((br) * K + (kt) * BK) * 2; \
;     __builtin_amdgcn_raw_ptr_buffer_load_lds(rs_##BASE, (__attribute__((address_space(3))) void*)((char*)(P) + tx * 16), 16, voff0, _so, 0, 0); \
;     __builtin_amdgcn_raw_ptr_buffer_load_lds(rs_##BASE, (__attribute__((address_space(3))) void*)((char*)(P) + tx * 16 + 8192), 16, voff1, _so, 0, 0); } while (0)
; #define LDA(dst, b, h) _Pragma("unroll") for (int m = 0; m < 4; ++m) _Pragma("unroll") for (int k = 0; k < 2; ++k) \
;     dst[m][k] = *reinterpret_cast<const bf16x8*>((char*)SA(b, h) + lds_byte(wr * 64 + m * 16 + fr, k * 32 + fq * 8))
; #define LDB(dst, b, h) _Pragma("unroll") for (int n = 0; n < 2; ++n) _Pragma("unroll") for (int k = 0; k < 2; ++k) \
;     dst[n][k] = *reinterpret_cast<const bf16x8*>((char*)SB(b, h) + lds_byte(wc * 32 + n * 16 + fr, k * 32 + fq * 8))
; #define WAIT_V(n) asm volatile("s_waitcnt vmcnt(" #n ")" ::: "memory")
; #define WAIT_L(n) asm volatile("s_waitcnt lgkmcnt(" #n ")" ::: "memory")
; #define BAR __builtin_amdgcn_s_barrier()
; #define SCHED __builtin_amdgcn_sched_barrier(0)
; template <class Epi> ...
;     ...
;   int wid = tx >> 6, lane = tx & 63, wr = wid >> 2, wc = wid & 3, fr = lane & 15, fq = lane >> 4;
;   f32x4 acc[2][2][4][2] = {};
;   bf16x8 At[4][2], B0[2][2], B1[2][2];
;   int nt = K / BK;
;   int voff0, voff1;
;   { int _r, _c; stage_rc(tx * 16, _r, _c); voff0 = (_r * K + _c) * 2; stage_rc(tx * 16 + 8192, _r, _c); voff1 = (_r * K + _c) * 2; }
;   __amdgpu_buffer_rsrc_t rs_A = __builtin_amdgcn_make_buffer_rsrc((void*)A, 0, 0x7fffffff, 0x00020000);
;   __amdgpu_buffer_rsrc_t rs_Bt = __builtin_amdgcn_make_buffer_rsrc((void*)Bt, 0, 0x7fffffff, 0x00020000);
;   if (!pre) {
;     STAGE(SB(0, 0), Bt, bcol, 0); STAGE(SA(0, 0), A, brow, 0);
;     STAGE(SB(0, 1), Bt, bcol + HALF, 0); STAGE(SA(0, 1), A, brow + HALF, 0);
;   }
;   if (wr == 1) BAR;
;   if (pre) { WAIT_V(0); } else { WAIT_V(4); }
;   BAR;
;   STAGE(SB(1, 0), Bt, bcol, 1); STAGE(SA(1, 0), A, brow, 1); STAGE(SB(1, 1), Bt, bcol + HALF, 1);
;   WAIT_V(6); BAR;
;   for (int t = 0; t < nt - 2; t += 2) {
;     LDB(B0, 0, 0); SCHED; LDA(At, 0, 0); STAGE(SA(1, 1), A, brow + HALF, t + 1);
;     WAIT_L(8); BAR; WAIT_L(0); MMA(0, 0, At, B0); BAR; SCHED;
;     LDB(B1, 0, 1); STAGE(SB(0, 0), Bt, bcol, t + 2);
;     BAR; WAIT_L(0); MMA(0, 1, At, B1); BAR;
.LBB0_1681:
	v_readlane_b32 s29, v254, 30
	s_lshl_b32 s18, s28, 11
	s_or_b32 s6, s18, 0x80
	v_add_u32_e32 v146, s29, v0
	v_add_u32_e32 v147, 0x2000, v146
	v_readfirstlane_b32 s7, v146
	s_mov_b32 m0, s7
	v_readfirstlane_b32 s7, v147
	v_add_u32_e32 v148, 0x8000, v136
	s_barrier
	buffer_load_dwordx4 v32, s[76:79], s6 offen lds
	s_mov_b32 m0, s7
	s_lshl_b32 s19, s27, 11
	v_readfirstlane_b32 s28, v148
	v_add_u32_e32 v150, 0xa000, v136
	v_readlane_b32 s30, v254, 31
	buffer_load_dwordx4 v130, s[76:79], s6 offen lds
	s_or_b32 s27, s19, 0x80
	s_mov_b32 s6, s78
	s_mov_b32 s7, s79
	s_mov_b32 m0, s28
	v_readfirstlane_b32 s28, v150
	v_add_u32_e32 v153, s30, v0
	buffer_load_dwordx4 v32, s[4:7], s27 offen lds
	s_mov_b32 m0, s28
	v_readfirstlane_b32 s28, v153
	v_add_u32_e32 v154, 0x2000, v153
	buffer_load_dwordx4 v130, s[4:7], s27 offen lds
	s_add_i32 s27, s18, 0x40080
	s_mov_b32 m0, s28
	v_readfirstlane_b32 s28, v154
	buffer_load_dwordx4 v32, s[76:79], s27 offen lds
	s_mov_b32 m0, s28
	v_and_b32_e32 v2, 15, v133
	buffer_load_dwordx4 v130, s[76:79], s27 offen lds
	v_lshlrev_b32_e32 v0, 6, v2
	v_lshlrev_b32_e32 v2, 2, v133
	v_and_b32_e32 v3, 48, v133
	v_and_b32_e32 v2, 32, v2
	v_bitop3_b32 v0, v0, v2, v3 bitop3:0x36
	s_waitcnt vmcnt(11)
	v_lshlrev_b32_e32 v8, 6, v133
	s_movk_i32 s27, 0x3c0
	s_waitcnt vmcnt(6)
	v_add_u32_e32 v4, s71, v0
	v_add_u32_e32 v5, s73, v0
	v_add_u32_e32 v6, s29, v0
	v_add_u32_e32 v7, s30, v0
	v_lshlrev_b32_e32 v1, 13, v1
	v_add_u32_e32 v10, 0, v0
	v_and_or_b32 v0, v8, s27, v3
	v_and_b32_e32 v9, 0x3000, v8
	v_xad_u32 v2, v0, v2, 0
	v_or_b32_e32 v3, 0x800, v1
	v_or_b32_e32 v8, 0x1000, v1
	v_or_b32_e32 v11, 0x1800, v1
	v_add_u32_e32 v152, 0xc000, v136
	v_add_u32_e32 v151, 0xe000, v136
	v_add_u32_e32 v139, 0x2000, v137
	v_add_u32_e32 v138, 0x2000, v134
	s_mov_b32 s27, -2
	s_mov_b32 s28, 0
	v_add_u32_e32 v155, v4, v9
	v_add_u32_e32 v143, v10, v1
	v_add_u32_e32 v142, v2, v3
	v_add_u32_e32 v141, v2, v8
	v_add_u32_e32 v140, v2, v11
	v_add_u32_e32 v149, v5, v9
	v_add_u32_e32 v145, v6, v9
	v_add_u32_e32 v144, v7, v9
	s_waitcnt vmcnt(10)
	s_barrier
.Lpk3:
	ds_read_b128 v[156:159], v155
	ds_read_b128 v[166:169], v155 offset:1024
	ds_read_b128 v[170:173], v155 offset:2048
	ds_read_b128 v[186:189], v155 offset:3072
	s_add_i32 s29, s19, s28
	v_readfirstlane_b32 s31, v152
	s_add_i32 s30, s29, 0x40080
	s_mov_b32 m0, s31
	v_readfirstlane_b32 s31, v151
	ds_read_b128 v[190:193], v143
	ds_read_b128 v[194:197], v143 offset:1024
	ds_read_b128 v[198:201], v142
	ds_read_b128 v[202:205], v142 offset:1024
	ds_read_b128 v[206:209], v141
	ds_read_b128 v[210:213], v141 offset:1024
	ds_read_b128 v[214:217], v140
	ds_read_b128 v[218:221], v140 offset:1024
	buffer_load_dwordx4 v32, s[4:7], s30 offen lds
	s_mov_b32 m0, s31
	s_nop 0
	buffer_load_dwordx4 v130, s[4:7], s30 offen lds
	s_waitcnt lgkmcnt(8)
	s_barrier
	s_waitcnt lgkmcnt(0)
	s_setprio 1
	s_waitcnt lgkmcnt(7)
	v_mfma_f32_16x16x32_bf16 v[126:129], v[190:193], v[156:159], 0
	v_mfma_f32_16x16x32_bf16 v[122:125], v[190:193], v[170:173], 0
	s_waitcnt lgkmcnt(5)
	v_mfma_f32_16x16x32_bf16 v[118:121], v[198:201], v[156:159], 0
	v_mfma_f32_16x16x32_bf16 v[114:117], v[198:201], v[170:173], 0
	s_waitcnt lgkmcnt(3)
	v_mfma_f32_16x16x32_bf16 v[110:113], v[206:209], v[156:159], 0
	v_mfma_f32_16x16x32_bf16 v[106:109], v[206:209], v[170:173], 0
	s_waitcnt lgkmcnt(1)
	v_mfma_f32_16x16x32_bf16 v[102:105], v[214:217], v[156:159], 0
	v_mfma_f32_16x16x32_bf16 v[98:101], v[214:217], v[170:173], 0
	v_mfma_f32_16x16x32_bf16 v[126:129], v[194:197], v[166:169], v[126:129]
	v_mfma_f32_16x16x32_bf16 v[122:125], v[194:197], v[186:189], v[122:125]
	v_mfma_f32_16x16x32_bf16 v[118:121], v[202:205], v[166:169], v[118:121]
	v_mfma_f32_16x16x32_bf16 v[114:117], v[202:205], v[186:189], v[114:117]
	v_mfma_f32_16x16x32_bf16 v[110:113], v[210:213], v[166:169], v[110:113]
	v_mfma_f32_16x16x32_bf16 v[106:109], v[210:213], v[186:189], v[106:109]
	s_waitcnt lgkmcnt(0)
	v_mfma_f32_16x16x32_bf16 v[102:105], v[218:221], v[166:169], v[102:105]
	v_mfma_f32_16x16x32_bf16 v[98:101], v[218:221], v[186:189], v[98:101]
	s_setprio 0
	s_barrier
	s_add_i32 s30, s18, s28
	v_readfirstlane_b32 s34, v137
	s_add_i32 s31, s30, 0x100
	s_mov_b32 m0, s34
	v_readfirstlane_b32 s34, v139
	ds_read_b128 v[222:225], v149
	ds_read_b128 v[226:229], v149 offset:1024
	ds_read_b128 v[230:233], v149 offset:2048
	ds_read_b128 v[234:237], v149 offset:3072
	buffer_load_dwordx4 v32, s[76:79], s31 offen lds
	s_mov_b32 m0, s34
	s_nop 0
	buffer_load_dwordx4 v130, s[76:79], s31 offen lds
	s_barrier
	s_waitcnt lgkmcnt(0)
	s_setprio 1
	s_waitcnt lgkmcnt(3)
	v_mfma_f32_16x16x32_bf16 v[94:97], v[190:193], v[222:225], 0
	s_waitcnt lgkmcnt(1)
	v_mfma_f32_16x16x32_bf16 v[90:93], v[190:193], v[230:233], 0
	v_mfma_f32_16x16x32_bf16 v[86:89], v[198:201], v[222:225], 0
	v_mfma_f32_16x16x32_bf16 v[82:85], v[198:201], v[230:233], 0
	v_mfma_f32_16x16x32_bf16 v[78:81], v[206:209], v[222:225], 0
	v_mfma_f32_16x16x32_bf16 v[74:77], v[206:209], v[230:233], 0
	v_mfma_f32_16x16x32_bf16 v[70:73], v[214:217], v[222:225], 0
	v_mfma_f32_16x16x32_bf16 v[66:69], v[214:217], v[230:233], 0
	v_mfma_f32_16x16x32_bf16 v[94:97], v[194:197], v[226:229], v[94:97]
	s_waitcnt lgkmcnt(0)
	v_mfma_f32_16x16x32_bf16 v[90:93], v[194:197], v[234:237], v[90:93]
	v_mfma_f32_16x16x32_bf16 v[86:89], v[202:205], v[226:229], v[86:89]
	v_mfma_f32_16x16x32_bf16 v[82:85], v[202:205], v[234:237], v[82:85]
	v_mfma_f32_16x16x32_bf16 v[78:81], v[210:213], v[226:229], v[78:81]
	v_mfma_f32_16x16x32_bf16 v[74:77], v[210:213], v[234:237], v[74:77]
	v_mfma_f32_16x16x32_bf16 v[70:73], v[218:221], v[226:229], v[70:73]
	v_mfma_f32_16x16x32_bf16 v[66:69], v[218:221], v[234:237], v[66:69]
	s_setprio 0
	v_readfirstlane_b32 s34, v136
	s_add_i32 s31, s29, 0x100
	s_mov_b32 m0, s34
	v_readfirstlane_b32 s34, v135
	s_barrier
; #define STAGE(P, BASE, br, kt) do { int _so = ((br) * K + (kt) * BK) * 2; \
;     __builtin_amdgcn_raw_ptr_buffer_load_lds(rs_##BASE, (__attribute__((address_space(3))) void*)((char*)(P) + tx * 16), 16, voff0, _so, 0, 0); \
;     __builtin_amdgcn_raw_ptr_buffer_load_lds(rs_##BASE, (__attribute__((address_space(3))) void*)((char*)(P) + tx * 16 + 8192), 16, voff1, _so, 0, 0); } while (0)
; #define LDA(dst, b, h) _Pragma("unroll") for (int m = 0; m < 4; ++m) _Pragma("unroll") for (int k = 0; k < 2; ++k) \
;     dst[m][k] = *reinterpret_cast<const bf16x8*>((char*)SA(b, h) + lds_byte(wr * 64 + m * 16 + fr, k * 32 + fq * 8))
; #define LDB(dst, b, h) _Pragma("unroll") for (int n = 0; n < 2; ++n) _Pragma("unroll") for (int k = 0; k < 2; ++k) \
;     dst[n][k] = *reinterpret_cast<const bf16x8*>((char*)SB(b, h) + lds_byte(wc * 32 + n * 16 + fr, k * 32 + fq * 8))
; #define MMA(ai, bj, At, Bt_) do { __builtin_amdgcn_s_setprio(1); \
;     _Pragma("unroll") for (int m = 0; m < 4; ++m) _Pragma("unroll") for (int n = 0; n < 2; ++n) _Pragma("unroll") for (int k = 0; k < 2; ++k) \
;       acc[ai][bj][m][n] = __builtin_amdgcn_mfma_f32_16x16x32_bf16(At[m][k], Bt_[n][k], acc[ai][bj][m][n], 0, 0, 0); \
;     __builtin_amdgcn_s_setprio(0); } while (0)
; #define WAIT_V(n) asm volatile("s_waitcnt vmcnt(" #n ")" ::: "memory")
; #define WAIT_L(n) asm volatile("s_waitcnt lgkmcnt(" #n ")" ::: "memory")
; #define BAR __builtin_amdgcn_s_barrier()
; #define SCHED __builtin_amdgcn_sched_barrier(0)
; template <class Epi> ...
;     ...
;     LDA(At, 0, 1); STAGE(SA(0, 0), A, brow, t + 2);
;     BAR; WAIT_L(0); MMA(1, 0, At, B0); BAR; SCHED;
;     STAGE(SB(0, 1), Bt, bcol + HALF, t + 2);
;     WAIT_V(6); BAR; MMA(1, 1, At, B1); BAR;
;     LDB(B0, 1, 0); SCHED; LDA(At, 1, 0); STAGE(SA(0, 1), A, brow + HALF, t + 2);
;     WAIT_L(8); BAR; WAIT_L(0); MMA(0, 0, At, B0); BAR; SCHED;
	ds_read_b128 v[190:193], v143 offset:16384
	ds_read_b128 v[194:197], v143 offset:17408
	ds_read_b128 v[198:201], v142 offset:16384
	ds_read_b128 v[202:205], v142 offset:17408
	ds_read_b128 v[206:209], v141 offset:16384
	ds_read_b128 v[210:213], v141 offset:17408
	ds_read_b128 v[214:217], v140 offset:16384
	ds_read_b128 v[218:221], v140 offset:17408
	buffer_load_dwordx4 v32, s[4:7], s31 offen lds
	s_mov_b32 m0, s34
	s_nop 0
	buffer_load_dwordx4 v130, s[4:7], s31 offen lds
	s_barrier
	s_waitcnt lgkmcnt(0)
	s_setprio 1
	s_waitcnt lgkmcnt(7)
	v_mfma_f32_16x16x32_bf16 v[62:65], v[190:193], v[156:159], 0
	v_mfma_f32_16x16x32_bf16 v[58:61], v[190:193], v[170:173], 0
	s_waitcnt lgkmcnt(5)
	v_mfma_f32_16x16x32_bf16 v[54:57], v[198:201], v[156:159], 0
	v_mfma_f32_16x16x32_bf16 v[50:53], v[198:201], v[170:173], 0
	s_waitcnt lgkmcnt(3)
	v_mfma_f32_16x16x32_bf16 v[46:49], v[206:209], v[156:159], 0
	v_mfma_f32_16x16x32_bf16 v[42:45], v[206:209], v[170:173], 0
	s_waitcnt lgkmcnt(1)
	v_mfma_f32_16x16x32_bf16 v[38:41], v[214:217], v[156:159], 0
	v_mfma_f32_16x16x32_bf16 v[34:37], v[214:217], v[170:173], 0
	v_mfma_f32_16x16x32_bf16 v[62:65], v[194:197], v[166:169], v[62:65]
	v_mfma_f32_16x16x32_bf16 v[58:61], v[194:197], v[186:189], v[58:61]
	v_mfma_f32_16x16x32_bf16 v[54:57], v[202:205], v[166:169], v[54:57]
	v_mfma_f32_16x16x32_bf16 v[50:53], v[202:205], v[186:189], v[50:53]
	v_mfma_f32_16x16x32_bf16 v[46:49], v[210:213], v[166:169], v[46:49]
	v_mfma_f32_16x16x32_bf16 v[42:45], v[210:213], v[186:189], v[42:45]
	s_waitcnt lgkmcnt(0)
	v_mfma_f32_16x16x32_bf16 v[38:41], v[218:221], v[166:169], v[38:41]
	v_mfma_f32_16x16x32_bf16 v[34:37], v[218:221], v[186:189], v[34:37]
	s_setprio 0
	s_barrier
	v_readfirstlane_b32 s34, v134
	s_add_i32 s31, s30, 0x40100
	s_mov_b32 m0, s34
	v_readfirstlane_b32 s34, v138
	buffer_load_dwordx4 v32, s[76:79], s31 offen lds
	s_mov_b32 m0, s34
	s_nop 0
	buffer_load_dwordx4 v130, s[76:79], s31 offen lds
	s_waitcnt vmcnt(6)
	s_barrier
	s_setprio 1
	v_mfma_f32_16x16x32_bf16 v[28:31], v[190:193], v[222:225], 0
	v_mfma_f32_16x16x32_bf16 v[24:27], v[190:193], v[230:233], 0
	v_mfma_f32_16x16x32_bf16 v[20:23], v[198:201], v[222:225], 0
	v_mfma_f32_16x16x32_bf16 v[16:19], v[198:201], v[230:233], 0
	v_mfma_f32_16x16x32_bf16 v[12:15], v[206:209], v[222:225], 0
	v_mfma_f32_16x16x32_bf16 v[8:11], v[206:209], v[230:233], 0
	v_mfma_f32_16x16x32_bf16 v[4:7], v[214:217], v[222:225], 0
	v_mfma_f32_16x16x32_bf16 v[0:3], v[214:217], v[230:233], 0
	v_mfma_f32_16x16x32_bf16 v[28:31], v[194:197], v[226:229], v[28:31]
	v_mfma_f32_16x16x32_bf16 v[24:27], v[194:197], v[234:237], v[24:27]
	v_mfma_f32_16x16x32_bf16 v[20:23], v[202:205], v[226:229], v[20:23]
	v_mfma_f32_16x16x32_bf16 v[16:19], v[202:205], v[234:237], v[16:19]
	v_mfma_f32_16x16x32_bf16 v[12:15], v[210:213], v[226:229], v[12:15]
	v_mfma_f32_16x16x32_bf16 v[8:11], v[210:213], v[234:237], v[8:11]
	v_mfma_f32_16x16x32_bf16 v[4:7], v[218:221], v[226:229], v[4:7]
	v_mfma_f32_16x16x32_bf16 v[0:3], v[218:221], v[234:237], v[0:3]
	s_setprio 0
	s_barrier
	ds_read_b128 v[156:159], v145
	ds_read_b128 v[166:169], v145 offset:1024
	ds_read_b128 v[170:173], v145 offset:2048
	ds_read_b128 v[186:189], v145 offset:3072
	v_readfirstlane_b32 s34, v132
	s_add_i32 s31, s29, 0x40100
	s_mov_b32 m0, s34
	v_readfirstlane_b32 s34, v131
	ds_read_b128 v[190:193], v143 offset:32768
	ds_read_b128 v[194:197], v143 offset:33792
	ds_read_b128 v[198:201], v142 offset:32768
	ds_read_b128 v[202:205], v142 offset:33792
	ds_read_b128 v[206:209], v141 offset:32768
	ds_read_b128 v[210:213], v141 offset:33792
	ds_read_b128 v[214:217], v140 offset:32768
	ds_read_b128 v[218:221], v140 offset:33792
	buffer_load_dwordx4 v32, s[4:7], s31 offen lds
	s_mov_b32 m0, s34
	s_nop 0
	buffer_load_dwordx4 v130, s[4:7], s31 offen lds
	s_waitcnt lgkmcnt(8)
	s_barrier
	s_waitcnt lgkmcnt(0)
	s_setprio 1
	s_waitcnt lgkmcnt(7)
	v_mfma_f32_16x16x32_bf16 v[126:129], v[190:193], v[156:159], v[126:129]
	v_mfma_f32_16x16x32_bf16 v[122:125], v[190:193], v[170:173], v[122:125]
	s_waitcnt lgkmcnt(5)
	v_mfma_f32_16x16x32_bf16 v[118:121], v[198:201], v[156:159], v[118:121]
	v_mfma_f32_16x16x32_bf16 v[114:117], v[198:201], v[170:173], v[114:117]
	s_waitcnt lgkmcnt(3)
	v_mfma_f32_16x16x32_bf16 v[110:113], v[206:209], v[156:159], v[110:113]
	v_mfma_f32_16x16x32_bf16 v[106:109], v[206:209], v[170:173], v[106:109]
	s_waitcnt lgkmcnt(1)
	v_mfma_f32_16x16x32_bf16 v[102:105], v[214:217], v[156:159], v[102:105]
	v_mfma_f32_16x16x32_bf16 v[98:101], v[214:217], v[170:173], v[98:101]
	v_mfma_f32_16x16x32_bf16 v[126:129], v[194:197], v[166:169], v[126:129]
	v_mfma_f32_16x16x32_bf16 v[122:125], v[194:197], v[186:189], v[122:125]
	v_mfma_f32_16x16x32_bf16 v[118:121], v[202:205], v[166:169], v[118:121]
	v_mfma_f32_16x16x32_bf16 v[114:117], v[202:205], v[186:189], v[114:117]
	v_mfma_f32_16x16x32_bf16 v[110:113], v[210:213], v[166:169], v[110:113]
	v_mfma_f32_16x16x32_bf16 v[106:109], v[210:213], v[186:189], v[106:109]
	s_waitcnt lgkmcnt(0)
	v_mfma_f32_16x16x32_bf16 v[102:105], v[218:221], v[166:169], v[102:105]
	v_mfma_f32_16x16x32_bf16 v[98:101], v[218:221], v[186:189], v[98:101]
	s_setprio 0
	s_barrier
; #define STAGE(P, BASE, br, kt) do { int _so = ((br) * K + (kt) * BK) * 2; \
;     __builtin_amdgcn_raw_ptr_buffer_load_lds(rs_##BASE, (__attribute__((address_space(3))) void*)((char*)(P) + tx * 16), 16, voff0, _so, 0, 0); \
;     __builtin_amdgcn_raw_ptr_buffer_load_lds(rs_##BASE, (__attribute__((address_space(3))) void*)((char*)(P) + tx * 16 + 8192), 16, voff1, _so, 0, 0); } while (0)
; #define LDA(dst, b, h) _Pragma("unroll") for (int m = 0; m < 4; ++m) _Pragma("unroll") for (int k = 0; k < 2; ++k) \
;     dst[m][k] = *reinterpret_cast<const bf16x8*>((char*)SA(b, h) + lds_byte(wr * 64 + m * 16 + fr, k * 32 + fq * 8))
; #define LDB(dst, b, h) _Pragma("unroll") for (int n = 0; n < 2; ++n) _Pragma("unroll") for (int k = 0; k < 2; ++k) \
;     dst[n][k] = *reinterpret_cast<const bf16x8*>((char*)SB(b, h) + lds_byte(wc * 32 + n * 16 + fr, k * 32 + fq * 8))
; #define MMA(ai, bj, At, Bt_) do { __builtin_amdgcn_s_setprio(1); \
;     _Pragma("unroll") for (int m = 0; m < 4; ++m) _Pragma("unroll") for (int n = 0; n < 2; ++n) _Pragma("unroll") for (int k = 0; k < 2; ++k) \
;       acc[ai][bj][m][n] = __builtin_amdgcn_mfma_f32_16x16x32_bf16(At[m][k], Bt_[n][k], acc[ai][bj][m][n], 0, 0, 0); \
;     __builtin_amdgcn_s_setprio(0); } while (0)
; #define WAIT_V(n) asm volatile("s_waitcnt vmcnt(" #n ")" ::: "memory")
; #define WAIT_L(n) asm volatile("s_waitcnt lgkmcnt(" #n ")" ::: "memory")
; #define BAR __builtin_amdgcn_s_barrier()
; #define SCHED __builtin_amdgcn_sched_barrier(0)
; template <class Epi> ...
;     ...
;   for (int t = 0; t < nt - 2; t += 2) {
;     ...
;     LDB(B1, 1, 1); STAGE(SB(1, 0), Bt, bcol, t + 3);
;     BAR; WAIT_L(0); MMA(0, 1, At, B1); BAR;
;     LDA(At, 1, 1); STAGE(SA(1, 0), A, brow, t + 3);
;     BAR; WAIT_L(0); MMA(1, 0, At, B0); BAR; SCHED;
;     STAGE(SB(1, 1), Bt, bcol + HALF, t + 3);
;     WAIT_V(6); BAR; MMA(1, 1, At, B1); BAR;
;   }
	v_readfirstlane_b32 s34, v146
	s_add_i32 s31, s30, 0x180
	s_mov_b32 m0, s34
	v_readfirstlane_b32 s34, v147
	ds_read_b128 v[222:225], v144
	ds_read_b128 v[226:229], v144 offset:1024
	ds_read_b128 v[230:233], v144 offset:2048
	ds_read_b128 v[234:237], v144 offset:3072
	buffer_load_dwordx4 v32, s[76:79], s31 offen lds
	s_mov_b32 m0, s34
	s_nop 0
	buffer_load_dwordx4 v130, s[76:79], s31 offen lds
	s_barrier
	s_waitcnt lgkmcnt(0)
	s_setprio 1
	s_waitcnt lgkmcnt(3)
	v_mfma_f32_16x16x32_bf16 v[94:97], v[190:193], v[222:225], v[94:97]
	s_waitcnt lgkmcnt(1)
	v_mfma_f32_16x16x32_bf16 v[90:93], v[190:193], v[230:233], v[90:93]
	v_mfma_f32_16x16x32_bf16 v[86:89], v[198:201], v[222:225], v[86:89]
	v_mfma_f32_16x16x32_bf16 v[82:85], v[198:201], v[230:233], v[82:85]
	v_mfma_f32_16x16x32_bf16 v[78:81], v[206:209], v[222:225], v[78:81]
	v_mfma_f32_16x16x32_bf16 v[74:77], v[206:209], v[230:233], v[74:77]
	v_mfma_f32_16x16x32_bf16 v[70:73], v[214:217], v[222:225], v[70:73]
	v_mfma_f32_16x16x32_bf16 v[66:69], v[214:217], v[230:233], v[66:69]
	v_mfma_f32_16x16x32_bf16 v[94:97], v[194:197], v[226:229], v[94:97]
	s_waitcnt lgkmcnt(0)
	v_mfma_f32_16x16x32_bf16 v[90:93], v[194:197], v[234:237], v[90:93]
	v_mfma_f32_16x16x32_bf16 v[86:89], v[202:205], v[226:229], v[86:89]
	v_mfma_f32_16x16x32_bf16 v[82:85], v[202:205], v[234:237], v[82:85]
	v_mfma_f32_16x16x32_bf16 v[78:81], v[210:213], v[226:229], v[78:81]
	v_mfma_f32_16x16x32_bf16 v[74:77], v[210:213], v[234:237], v[74:77]
	v_mfma_f32_16x16x32_bf16 v[70:73], v[218:221], v[226:229], v[70:73]
	v_mfma_f32_16x16x32_bf16 v[66:69], v[218:221], v[234:237], v[66:69]
	s_setprio 0
	v_readfirstlane_b32 s31, v148
	s_addk_i32 s29, 0x180
	s_mov_b32 m0, s31
	v_readfirstlane_b32 s31, v150
	s_barrier
	ds_read_b128 v[190:193], v143 offset:49152
	ds_read_b128 v[194:197], v143 offset:50176
	ds_read_b128 v[198:201], v142 offset:49152
	ds_read_b128 v[202:205], v142 offset:50176
	ds_read_b128 v[206:209], v141 offset:49152
	ds_read_b128 v[210:213], v141 offset:50176
	ds_read_b128 v[214:217], v140 offset:49152
	ds_read_b128 v[218:221], v140 offset:50176
	buffer_load_dwordx4 v32, s[4:7], s29 offen lds
	s_mov_b32 m0, s31
	s_nop 0
	buffer_load_dwordx4 v130, s[4:7], s29 offen lds
	s_barrier
	s_waitcnt lgkmcnt(0)
	s_setprio 1
	s_waitcnt lgkmcnt(7)
	v_mfma_f32_16x16x32_bf16 v[62:65], v[190:193], v[156:159], v[62:65]
	v_mfma_f32_16x16x32_bf16 v[58:61], v[190:193], v[170:173], v[58:61]
	s_waitcnt lgkmcnt(5)
	v_mfma_f32_16x16x32_bf16 v[54:57], v[198:201], v[156:159], v[54:57]
	v_mfma_f32_16x16x32_bf16 v[50:53], v[198:201], v[170:173], v[50:53]
	s_waitcnt lgkmcnt(3)
	v_mfma_f32_16x16x32_bf16 v[46:49], v[206:209], v[156:159], v[46:49]
	v_mfma_f32_16x16x32_bf16 v[42:45], v[206:209], v[170:173], v[42:45]
	s_waitcnt lgkmcnt(1)
	v_mfma_f32_16x16x32_bf16 v[38:41], v[214:217], v[156:159], v[38:41]
	v_mfma_f32_16x16x32_bf16 v[34:37], v[214:217], v[170:173], v[34:37]
	v_mfma_f32_16x16x32_bf16 v[62:65], v[194:197], v[166:169], v[62:65]
	v_mfma_f32_16x16x32_bf16 v[58:61], v[194:197], v[186:189], v[58:61]
	v_mfma_f32_16x16x32_bf16 v[54:57], v[202:205], v[166:169], v[54:57]
	v_mfma_f32_16x16x32_bf16 v[50:53], v[202:205], v[186:189], v[50:53]
	v_mfma_f32_16x16x32_bf16 v[46:49], v[210:213], v[166:169], v[46:49]
	v_mfma_f32_16x16x32_bf16 v[42:45], v[210:213], v[186:189], v[42:45]
	s_waitcnt lgkmcnt(0)
	v_mfma_f32_16x16x32_bf16 v[38:41], v[218:221], v[166:169], v[38:41]
	v_mfma_f32_16x16x32_bf16 v[34:37], v[218:221], v[186:189], v[34:37]
	s_setprio 0
	s_barrier
	v_readfirstlane_b32 s29, v153
	s_add_i32 s30, s30, 0x40180
	s_mov_b32 m0, s29
	v_readfirstlane_b32 s29, v154
	buffer_load_dwordx4 v32, s[76:79], s30 offen lds
	s_mov_b32 m0, s29
	s_nop 0
	buffer_load_dwordx4 v130, s[76:79], s30 offen lds
	s_waitcnt vmcnt(6)
	s_barrier
	s_setprio 1
	v_mfma_f32_16x16x32_bf16 v[28:31], v[190:193], v[222:225], v[28:31]
	v_mfma_f32_16x16x32_bf16 v[24:27], v[190:193], v[230:233], v[24:27]
	v_mfma_f32_16x16x32_bf16 v[20:23], v[198:201], v[222:225], v[20:23]
	v_mfma_f32_16x16x32_bf16 v[16:19], v[198:201], v[230:233], v[16:19]
	v_mfma_f32_16x16x32_bf16 v[12:15], v[206:209], v[222:225], v[12:15]
	v_mfma_f32_16x16x32_bf16 v[8:11], v[206:209], v[230:233], v[8:11]
	v_mfma_f32_16x16x32_bf16 v[4:7], v[214:217], v[222:225], v[4:7]
	v_mfma_f32_16x16x32_bf16 v[0:3], v[214:217], v[230:233], v[0:3]
	v_mfma_f32_16x16x32_bf16 v[28:31], v[194:197], v[226:229], v[28:31]
	v_mfma_f32_16x16x32_bf16 v[24:27], v[194:197], v[234:237], v[24:27]
	v_mfma_f32_16x16x32_bf16 v[20:23], v[202:205], v[226:229], v[20:23]
	v_mfma_f32_16x16x32_bf16 v[16:19], v[202:205], v[234:237], v[16:19]
	v_mfma_f32_16x16x32_bf16 v[12:15], v[210:213], v[226:229], v[12:15]
	v_mfma_f32_16x16x32_bf16 v[8:11], v[210:213], v[234:237], v[8:11]
	v_mfma_f32_16x16x32_bf16 v[4:7], v[218:221], v[226:229], v[4:7]
	v_mfma_f32_16x16x32_bf16 v[0:3], v[218:221], v[234:237], v[0:3]
	s_setprio 0
	s_add_i32 s27, s27, 2
	s_addk_i32 s28, 0x100
	s_cmp_lt_u32 s27, 12
	s_barrier
	s_cbranch_scc1 .LBB0_1682
	s_branch .Lpx3

; #define STAGE(P, BASE, br, kt) do { int _so = ((br) * K + (kt) * BK) * 2; \
;     __builtin_amdgcn_raw_ptr_buffer_load_lds(rs_##BASE, (__attribute__((address_space(3))) void*)((char*)(P) + tx * 16), 16, voff0, _so, 0, 0); \
;     __builtin_amdgcn_raw_ptr_buffer_load_lds(rs_##BASE, (__attribute__((address_space(3))) void*)((char*)(P) + tx * 16 + 8192), 16, voff1, _so, 0, 0); } while (0)
; #define LDA(dst, b, h) _Pragma("unroll") for (int m = 0; m < 4; ++m) _Pragma("unroll") for (int k = 0; k < 2; ++k) \
;     dst[m][k] = *reinterpret_cast<const bf16x8*>((char*)SA(b, h) + lds_byte(wr * 64 + m * 16 + fr, k * 32 + fq * 8))
; #define LDB(dst, b, h) _Pragma("unroll") for (int n = 0; n < 2; ++n) _Pragma("unroll") for (int k = 0; k < 2; ++k) \
;     dst[n][k] = *reinterpret_cast<const bf16x8*>((char*)SB(b, h) + lds_byte(wc * 32 + n * 16 + fr, k * 32 + fq * 8))
; #define MMA(ai, bj, At, Bt_) do { __builtin_amdgcn_s_setprio(1); \
;     _Pragma("unroll") for (int m = 0; m < 4; ++m) _Pragma("unroll") for (int n = 0; n < 2; ++n) _Pragma("unroll") for (int k = 0; k < 2; ++k) \
;       acc[ai][bj][m][n] = __builtin_amdgcn_mfma_f32_16x16x32_bf16(At[m][k], Bt_[n][k], acc[ai][bj][m][n], 0, 0, 0); \
;     __builtin_amdgcn_s_setprio(0); } while (0)
; #define WAIT_V(n) asm volatile("s_waitcnt vmcnt(" #n ")" ::: "memory")
; #define WAIT_L(n) asm volatile("s_waitcnt lgkmcnt(" #n ")" ::: "memory")
; #define BAR __builtin_amdgcn_s_barrier()
; template <class Epi> ...
;     ...
;   { LDB(B0, 0, 0); LDA(At, 0, 0); STAGE(SA(1, 1), A, brow + HALF, nt - 1);
;     BAR; WAIT_L(0); MMA(0, 0, At, B0); BAR;
;     LDB(B1, 0, 1); BAR; WAIT_L(0); MMA(0, 1, At, B1); BAR;
;     LDA(At, 0, 1); WAIT_V(4); BAR; WAIT_L(0); MMA(1, 0, At, B0); MMA(1, 1, At, B1); BAR; }
.Lpx3:
	v_readfirstlane_b32 s18, v152
	s_add_i32 s19, s19, 0x40780
	s_mov_b32 s6, s78
	s_mov_b32 s7, s79
	s_mov_b32 m0, s18
	v_readfirstlane_b32 s18, v151
	ds_read_b128 v[156:159], v155
	ds_read_b128 v[166:169], v155 offset:1024
	ds_read_b128 v[170:173], v155 offset:2048
	ds_read_b128 v[186:189], v155 offset:3072
	ds_read_b128 v[190:193], v143
	ds_read_b128 v[194:197], v143 offset:1024
	ds_read_b128 v[198:201], v142
	ds_read_b128 v[202:205], v142 offset:1024
	ds_read_b128 v[206:209], v141
	ds_read_b128 v[210:213], v141 offset:1024
	ds_read_b128 v[214:217], v140
	ds_read_b128 v[218:221], v140 offset:1024
	buffer_load_dwordx4 v32, s[4:7], s19 offen lds
	s_mov_b32 m0, s18
	s_nop 0
	buffer_load_dwordx4 v130, s[4:7], s19 offen lds
	s_barrier
	s_waitcnt lgkmcnt(0)
	s_setprio 1
	s_waitcnt lgkmcnt(7)
	v_mfma_f32_16x16x32_bf16 v[126:129], v[190:193], v[156:159], v[126:129]
	v_mfma_f32_16x16x32_bf16 v[122:125], v[190:193], v[170:173], v[122:125]
	s_waitcnt lgkmcnt(5)
	v_mfma_f32_16x16x32_bf16 v[118:121], v[198:201], v[156:159], v[118:121]
	v_mfma_f32_16x16x32_bf16 v[114:117], v[198:201], v[170:173], v[114:117]
	s_waitcnt lgkmcnt(3)
	v_mfma_f32_16x16x32_bf16 v[110:113], v[206:209], v[156:159], v[110:113]
	v_mfma_f32_16x16x32_bf16 v[126:129], v[194:197], v[166:169], v[126:129]
	v_mfma_f32_16x16x32_bf16 v[122:125], v[194:197], v[186:189], v[122:125]
	v_mfma_f32_16x16x32_bf16 v[118:121], v[202:205], v[166:169], v[118:121]
	v_mfma_f32_16x16x32_bf16 v[114:117], v[202:205], v[186:189], v[114:117]
	s_waitcnt lgkmcnt(2)
	v_mfma_f32_16x16x32_bf16 v[110:113], v[210:213], v[166:169], v[110:113]
	v_mfma_f32_16x16x32_bf16 v[106:109], v[206:209], v[170:173], v[106:109]
	s_waitcnt lgkmcnt(1)
	v_mfma_f32_16x16x32_bf16 v[102:105], v[214:217], v[156:159], v[102:105]
	v_mfma_f32_16x16x32_bf16 v[98:101], v[214:217], v[170:173], v[98:101]
	v_mfma_f32_16x16x32_bf16 v[150:153], v[210:213], v[186:189], v[106:109]
	s_waitcnt lgkmcnt(0)
	v_mfma_f32_16x16x32_bf16 v[222:225], v[218:221], v[166:169], v[102:105]
	v_mfma_f32_16x16x32_bf16 v[226:229], v[218:221], v[186:189], v[98:101]
	s_setprio 0
	s_barrier
	s_nop 1
	ds_read_b128 v[98:101], v149
	ds_read_b128 v[102:105], v149 offset:1024
	ds_read_b128 v[106:109], v149 offset:2048
	ds_read_b128 v[146:149], v149 offset:3072
	s_barrier
	s_waitcnt lgkmcnt(0)
	s_setprio 1
	s_waitcnt lgkmcnt(3)
	v_mfma_f32_16x16x32_bf16 v[94:97], v[190:193], v[98:101], v[94:97]
	s_waitcnt lgkmcnt(1)
	v_mfma_f32_16x16x32_bf16 v[90:93], v[190:193], v[106:109], v[90:93]
	v_mfma_f32_16x16x32_bf16 v[86:89], v[198:201], v[98:101], v[86:89]
	v_mfma_f32_16x16x32_bf16 v[82:85], v[198:201], v[106:109], v[82:85]
	v_mfma_f32_16x16x32_bf16 v[94:97], v[194:197], v[102:105], v[94:97]
	s_waitcnt lgkmcnt(0)
	v_mfma_f32_16x16x32_bf16 v[90:93], v[194:197], v[146:149], v[90:93]
	v_mfma_f32_16x16x32_bf16 v[86:89], v[202:205], v[102:105], v[86:89]
	v_mfma_f32_16x16x32_bf16 v[82:85], v[202:205], v[146:149], v[82:85]
	v_mfma_f32_16x16x32_bf16 v[78:81], v[206:209], v[98:101], v[78:81]
	v_mfma_f32_16x16x32_bf16 v[74:77], v[206:209], v[106:109], v[74:77]
	v_mfma_f32_16x16x32_bf16 v[70:73], v[214:217], v[98:101], v[70:73]
	v_mfma_f32_16x16x32_bf16 v[66:69], v[214:217], v[106:109], v[66:69]
	v_mfma_f32_16x16x32_bf16 v[190:193], v[210:213], v[102:105], v[78:81]
	v_mfma_f32_16x16x32_bf16 v[194:197], v[210:213], v[146:149], v[74:77]
	v_mfma_f32_16x16x32_bf16 v[198:201], v[218:221], v[102:105], v[70:73]
	v_mfma_f32_16x16x32_bf16 v[202:205], v[218:221], v[146:149], v[66:69]
	s_setprio 0
	s_barrier
	s_nop 1
	ds_read_b128 v[66:69], v143 offset:16384
	ds_read_b128 v[70:73], v143 offset:17408
	ds_read_b128 v[74:77], v142 offset:16384
	ds_read_b128 v[78:81], v142 offset:17408
	ds_read_b128 v[206:209], v141 offset:16384
	ds_read_b128 v[210:213], v141 offset:17408
	ds_read_b128 v[214:217], v140 offset:16384
	ds_read_b128 v[218:221], v140 offset:17408
	s_waitcnt vmcnt(4)
	s_barrier
	s_waitcnt lgkmcnt(0)
	s_setprio 1
	s_waitcnt lgkmcnt(7)
	v_mfma_f32_16x16x32_bf16 v[62:65], v[66:69], v[156:159], v[62:65]
	v_mfma_f32_16x16x32_bf16 v[58:61], v[66:69], v[170:173], v[58:61]
	s_waitcnt lgkmcnt(5)
	v_mfma_f32_16x16x32_bf16 v[54:57], v[74:77], v[156:159], v[54:57]
	v_mfma_f32_16x16x32_bf16 v[50:53], v[74:77], v[170:173], v[50:53]
	v_mfma_f32_16x16x32_bf16 v[62:65], v[70:73], v[166:169], v[62:65]
	v_mfma_f32_16x16x32_bf16 v[58:61], v[70:73], v[186:189], v[58:61]
	s_waitcnt lgkmcnt(4)
	v_mfma_f32_16x16x32_bf16 v[54:57], v[78:81], v[166:169], v[54:57]
	v_mfma_f32_16x16x32_bf16 v[50:53], v[78:81], v[186:189], v[50:53]
	s_waitcnt lgkmcnt(3)
	v_mfma_f32_16x16x32_bf16 v[46:49], v[206:209], v[156:159], v[46:49]
	v_mfma_f32_16x16x32_bf16 v[42:45], v[206:209], v[170:173], v[42:45]
	s_waitcnt lgkmcnt(1)
	v_mfma_f32_16x16x32_bf16 v[38:41], v[214:217], v[156:159], v[38:41]
	v_mfma_f32_16x16x32_bf16 v[34:37], v[214:217], v[170:173], v[34:37]
	v_mfma_f32_16x16x32_bf16 v[230:233], v[210:213], v[166:169], v[46:49]
	v_mfma_f32_16x16x32_bf16 v[234:237], v[210:213], v[186:189], v[42:45]
	s_waitcnt lgkmcnt(0)
	v_mfma_f32_16x16x32_bf16 v[154:157], v[218:221], v[166:169], v[38:41]
	v_mfma_f32_16x16x32_bf16 v[158:161], v[218:221], v[186:189], v[34:37]
	s_setprio 0
	s_setprio 1
	v_mfma_f32_16x16x32_bf16 v[28:31], v[66:69], v[98:101], v[28:31]
	v_mfma_f32_16x16x32_bf16 v[24:27], v[66:69], v[106:109], v[24:27]
	v_mfma_f32_16x16x32_bf16 v[20:23], v[74:77], v[98:101], v[20:23]
	v_mfma_f32_16x16x32_bf16 v[12:15], v[206:209], v[98:101], v[12:15]
	v_mfma_f32_16x16x32_bf16 v[28:31], v[70:73], v[102:105], v[28:31]
	v_mfma_f32_16x16x32_bf16 v[24:27], v[70:73], v[146:149], v[24:27]
	v_mfma_f32_16x16x32_bf16 v[20:23], v[78:81], v[102:105], v[20:23]
	v_mfma_f32_16x16x32_bf16 v[16:19], v[74:77], v[106:109], v[16:19]
	v_mfma_f32_16x16x32_bf16 v[12:15], v[210:213], v[102:105], v[12:15]
	v_mfma_f32_16x16x32_bf16 v[8:11], v[206:209], v[106:109], v[8:11]
	v_mfma_f32_16x16x32_bf16 v[4:7], v[214:217], v[98:101], v[4:7]
	v_mfma_f32_16x16x32_bf16 v[0:3], v[214:217], v[106:109], v[0:3]
	v_mfma_f32_16x16x32_bf16 v[166:169], v[78:81], v[146:149], v[16:19]
	v_mfma_f32_16x16x32_bf16 v[170:173], v[210:213], v[146:149], v[8:11]
	v_mfma_f32_16x16x32_bf16 v[186:189], v[218:221], v[102:105], v[4:7]
	v_mfma_f32_16x16x32_bf16 v[146:149], v[218:221], v[146:149], v[0:3]
	s_setprio 0
	s_barrier
; #define LDA(dst, b, h) _Pragma("unroll") for (int m = 0; m < 4; ++m) _Pragma("unroll") for (int k = 0; k < 2; ++k) \
;     dst[m][k] = *reinterpret_cast<const bf16x8*>((char*)SA(b, h) + lds_byte(wr * 64 + m * 16 + fr, k * 32 + fq * 8))
; #define LDB(dst, b, h) _Pragma("unroll") for (int n = 0; n < 2; ++n) _Pragma("unroll") for (int k = 0; k < 2; ++k) \
;     dst[n][k] = *reinterpret_cast<const bf16x8*>((char*)SB(b, h) + lds_byte(wc * 32 + n * 16 + fr, k * 32 + fq * 8))
; #define MMA(ai, bj, At, Bt_) do { __builtin_amdgcn_s_setprio(1); \
;     _Pragma("unroll") for (int m = 0; m < 4; ++m) _Pragma("unroll") for (int n = 0; n < 2; ++n) _Pragma("unroll") for (int k = 0; k < 2; ++k) \
;       acc[ai][bj][m][n] = __builtin_amdgcn_mfma_f32_16x16x32_bf16(At[m][k], Bt_[n][k], acc[ai][bj][m][n], 0, 0, 0); \
;     __builtin_amdgcn_s_setprio(0); } while (0)
; #define WAIT_V(n) asm volatile("s_waitcnt vmcnt(" #n ")" ::: "memory")
; #define WAIT_L(n) asm volatile("s_waitcnt lgkmcnt(" #n ")" ::: "memory")
; #define BAR __builtin_amdgcn_s_barrier()
; template <class Epi> ...
;     ...
;   { LDB(B0, 1, 0); LDA(At, 1, 0); WAIT_V(2); BAR; WAIT_L(0); MMA(0, 0, At, B0); BAR;
;     LDB(B1, 1, 1); WAIT_V(0); BAR; WAIT_L(0); MMA(0, 1, At, B1); BAR;
;     LDA(At, 1, 1); BAR; WAIT_L(0); MMA(1, 0, At, B0); MMA(1, 1, At, B1); BAR; }
;   if (wr == 0) BAR;
	ds_read_b128 v[206:209], v145
	ds_read_b128 v[210:213], v145 offset:1024
	ds_read_b128 v[214:217], v145 offset:2048
	ds_read_b128 v[218:221], v145 offset:3072
	ds_read_b128 v[0:3], v143 offset:32768
	ds_read_b128 v[4:7], v143 offset:33792
	ds_read_b128 v[8:11], v142 offset:32768
	ds_read_b128 v[42:45], v142 offset:33792
	ds_read_b128 v[46:49], v141 offset:32768
	ds_read_b128 v[238:241], v141 offset:33792
	ds_read_b128 v[242:245], v140 offset:32768
	ds_read_b128 v[246:249], v140 offset:33792
	s_waitcnt vmcnt(2)
	s_barrier
	s_waitcnt lgkmcnt(0)
	s_setprio 1
	s_waitcnt lgkmcnt(7)
	v_mfma_f32_16x16x32_bf16 v[16:19], v[0:3], v[206:209], v[126:129]
	s_waitcnt lgkmcnt(6)
	v_mfma_f32_16x16x32_bf16 v[98:101], v[4:7], v[210:213], v[16:19]
	v_mfma_f32_16x16x32_bf16 v[16:19], v[0:3], v[214:217], v[122:125]
	v_mfma_f32_16x16x32_bf16 v[66:69], v[4:7], v[218:221], v[16:19]
	s_waitcnt lgkmcnt(5)
	v_mfma_f32_16x16x32_bf16 v[16:19], v[8:11], v[206:209], v[118:121]
	s_waitcnt lgkmcnt(4)
	v_mfma_f32_16x16x32_bf16 v[102:105], v[42:45], v[210:213], v[16:19]
	v_mfma_f32_16x16x32_bf16 v[16:19], v[8:11], v[214:217], v[114:117]
	v_mfma_f32_16x16x32_bf16 v[70:73], v[42:45], v[218:221], v[16:19]
	s_waitcnt lgkmcnt(3)
	v_mfma_f32_16x16x32_bf16 v[16:19], v[46:49], v[206:209], v[110:113]
	s_waitcnt lgkmcnt(2)
	v_mfma_f32_16x16x32_bf16 v[106:109], v[238:241], v[210:213], v[16:19]
	v_mfma_f32_16x16x32_bf16 v[16:19], v[46:49], v[214:217], v[150:153]
	v_mfma_f32_16x16x32_bf16 v[74:77], v[238:241], v[218:221], v[16:19]
	s_waitcnt lgkmcnt(1)
	v_mfma_f32_16x16x32_bf16 v[16:19], v[242:245], v[206:209], v[222:225]
	s_waitcnt lgkmcnt(0)
	v_mfma_f32_16x16x32_bf16 v[110:113], v[246:249], v[210:213], v[16:19]
	v_mfma_f32_16x16x32_bf16 v[16:19], v[242:245], v[214:217], v[226:229]
	v_mfma_f32_16x16x32_bf16 v[78:81], v[246:249], v[218:221], v[16:19]
	s_setprio 0
	s_barrier
	ds_read_b128 v[150:153], v144
	ds_read_b128 v[222:225], v144 offset:1024
	ds_read_b128 v[226:229], v144 offset:2048
	ds_read_b128 v[250:253], v144 offset:3072
	s_waitcnt vmcnt(0)
	s_barrier
	s_waitcnt lgkmcnt(0)
	s_setprio 1
	s_waitcnt lgkmcnt(3)
	v_mfma_f32_16x16x32_bf16 v[16:19], v[0:3], v[150:153], v[94:97]
	s_waitcnt lgkmcnt(1)
	v_mfma_f32_16x16x32_bf16 v[0:3], v[0:3], v[226:229], v[90:93]
	v_mfma_f32_16x16x32_bf16 v[34:37], v[4:7], v[222:225], v[16:19]
	s_waitcnt lgkmcnt(0)
	v_mfma_f32_16x16x32_bf16 v[16:19], v[4:7], v[250:253], v[0:3]
	v_mfma_f32_16x16x32_bf16 v[0:3], v[8:11], v[150:153], v[86:89]
	v_mfma_f32_16x16x32_bf16 v[38:41], v[42:45], v[222:225], v[0:3]
	v_mfma_f32_16x16x32_bf16 v[0:3], v[8:11], v[226:229], v[82:85]
	v_mfma_f32_16x16x32_bf16 v[8:11], v[42:45], v[250:253], v[0:3]
	v_mfma_f32_16x16x32_bf16 v[0:3], v[46:49], v[150:153], v[190:193]
	v_mfma_f32_16x16x32_bf16 v[42:45], v[238:241], v[222:225], v[0:3]
	v_mfma_f32_16x16x32_bf16 v[0:3], v[46:49], v[226:229], v[194:197]
	v_mfma_f32_16x16x32_bf16 v[4:7], v[238:241], v[250:253], v[0:3]
	v_mfma_f32_16x16x32_bf16 v[0:3], v[242:245], v[150:153], v[198:201]
	v_mfma_f32_16x16x32_bf16 v[46:49], v[246:249], v[222:225], v[0:3]
	v_mfma_f32_16x16x32_bf16 v[0:3], v[242:245], v[226:229], v[202:205]
	v_mfma_f32_16x16x32_bf16 v[0:3], v[246:249], v[250:253], v[0:3]
	s_setprio 0
	s_barrier
	ds_read_b128 v[190:193], v143 offset:49152
	ds_read_b128 v[194:197], v143 offset:50176
	ds_read_b128 v[198:201], v142 offset:49152
	ds_read_b128 v[142:145], v142 offset:50176
	ds_read_b128 v[202:205], v141 offset:49152
	ds_read_b128 v[238:241], v141 offset:50176
	ds_read_b128 v[242:245], v140 offset:49152
	ds_read_b128 v[246:249], v140 offset:50176
	s_barrier
	s_waitcnt lgkmcnt(0)
	s_setprio 1
	s_waitcnt lgkmcnt(5)
	v_mfma_f32_16x16x32_bf16 v[50:53], v[198:201], v[214:217], v[50:53]
	s_waitcnt lgkmcnt(4)
	v_mfma_f32_16x16x32_bf16 v[86:89], v[142:145], v[218:221], v[50:53]
	s_waitcnt lgkmcnt(3)
	v_mfma_f32_16x16x32_bf16 v[50:53], v[202:205], v[206:209], v[230:233]
	s_waitcnt lgkmcnt(2)
	v_mfma_f32_16x16x32_bf16 v[122:125], v[238:241], v[210:213], v[50:53]
	v_mfma_f32_16x16x32_bf16 v[50:53], v[202:205], v[214:217], v[234:237]
	v_mfma_f32_16x16x32_bf16 v[90:93], v[238:241], v[218:221], v[50:53]
	s_waitcnt lgkmcnt(1)
	v_mfma_f32_16x16x32_bf16 v[50:53], v[242:245], v[206:209], v[154:157]
	v_mfma_f32_16x16x32_bf16 v[62:65], v[190:193], v[206:209], v[62:65]
	v_mfma_f32_16x16x32_bf16 v[58:61], v[190:193], v[214:217], v[58:61]
	v_mfma_f32_16x16x32_bf16 v[54:57], v[198:201], v[206:209], v[54:57]
	s_waitcnt lgkmcnt(0)
	v_mfma_f32_16x16x32_bf16 v[126:129], v[246:249], v[210:213], v[50:53]
	v_mfma_f32_16x16x32_bf16 v[50:53], v[242:245], v[214:217], v[158:161]
	v_mfma_f32_16x16x32_bf16 v[114:117], v[194:197], v[210:213], v[62:65]
	v_mfma_f32_16x16x32_bf16 v[82:85], v[194:197], v[218:221], v[58:61]
	v_mfma_f32_16x16x32_bf16 v[118:121], v[142:145], v[210:213], v[54:57]
	v_mfma_f32_16x16x32_bf16 v[94:97], v[246:249], v[218:221], v[50:53]
	s_setprio 0
	s_setprio 1
	v_mfma_f32_16x16x32_bf16 v[20:23], v[198:201], v[150:153], v[20:23]
	v_mfma_f32_16x16x32_bf16 v[12:15], v[202:205], v[150:153], v[12:15]
	v_mfma_f32_16x16x32_bf16 v[28:31], v[190:193], v[150:153], v[28:31]
	v_mfma_f32_16x16x32_bf16 v[24:27], v[190:193], v[226:229], v[24:27]
	v_mfma_f32_16x16x32_bf16 v[54:57], v[142:145], v[222:225], v[20:23]
	v_mfma_f32_16x16x32_bf16 v[20:23], v[198:201], v[226:229], v[166:169]
	v_mfma_f32_16x16x32_bf16 v[58:61], v[238:241], v[222:225], v[12:15]
	v_mfma_f32_16x16x32_bf16 v[12:15], v[202:205], v[226:229], v[170:173]
	v_mfma_f32_16x16x32_bf16 v[50:53], v[194:197], v[222:225], v[28:31]
	v_mfma_f32_16x16x32_bf16 v[28:31], v[194:197], v[250:253], v[24:27]
	v_mfma_f32_16x16x32_bf16 v[24:27], v[142:145], v[250:253], v[20:23]
	v_mfma_f32_16x16x32_bf16 v[20:23], v[238:241], v[250:253], v[12:15]
	v_mfma_f32_16x16x32_bf16 v[12:15], v[242:245], v[150:153], v[186:189]
	v_mfma_f32_16x16x32_bf16 v[62:65], v[246:249], v[222:225], v[12:15]
	v_mfma_f32_16x16x32_bf16 v[12:15], v[242:245], v[226:229], v[146:149]
	v_mfma_f32_16x16x32_bf16 v[12:15], v[246:249], v[250:253], v[12:15]
	s_setprio 0
	v_cmp_gt_u32_e32 vcc, s59, v133
	s_barrier
	s_and_saveexec_b64 s[4:5], vcc
	s_cbranch_execz .LBB0_1685
	s_barrier

; #define STAGE(P, BASE, br, kt) do { int _so = ((br) * K + (kt) * BK) * 2; \
;     __builtin_amdgcn_raw_ptr_buffer_load_lds(rs_##BASE, (__attribute__((address_space(3))) void*)((char*)(P) + tx * 16), 16, voff0, _so, 0, 0); \
;     __builtin_amdgcn_raw_ptr_buffer_load_lds(rs_##BASE, (__attribute__((address_space(3))) void*)((char*)(P) + tx * 16 + 8192), 16, voff1, _so, 0, 0); } while (0)
; #define LDA(dst, b, h) _Pragma("unroll") for (int m = 0; m < 4; ++m) _Pragma("unroll") for (int k = 0; k < 2; ++k) \
;     dst[m][k] = *reinterpret_cast<const bf16x8*>((char*)SA(b, h) + lds_byte(wr * 64 + m * 16 + fr, k * 32 + fq * 8))
; #define LDB(dst, b, h) _Pragma("unroll") for (int n = 0; n < 2; ++n) _Pragma("unroll") for (int k = 0; k < 2; ++k) \
;     dst[n][k] = *reinterpret_cast<const bf16x8*>((char*)SB(b, h) + lds_byte(wc * 32 + n * 16 + fr, k * 32 + fq * 8))
; #define MMA(ai, bj, At, Bt_) do { __builtin_amdgcn_s_setprio(1); \
;     _Pragma("unroll") for (int m = 0; m < 4; ++m) _Pragma("unroll") for (int n = 0; n < 2; ++n) _Pragma("unroll") for (int k = 0; k < 2; ++k) \
;       acc[ai][bj][m][n] = __builtin_amdgcn_mfma_f32_16x16x32_bf16(At[m][k], Bt_[n][k], acc[ai][bj][m][n], 0, 0, 0); \
;     __builtin_amdgcn_s_setprio(0); } while (0)
; #define WAIT_V(n) asm volatile("s_waitcnt vmcnt(" #n ")" ::: "memory")
; #define WAIT_L(n) asm volatile("s_waitcnt lgkmcnt(" #n ")" ::: "memory")
; template <class Epi> ...
;     ...
;   { int _r, _c; stage_rc(tx * 16, _r, _c); voff0 = (_r * K + _c) * 2; stage_rc(tx * 16 + 8192, _r, _c); voff1 = (_r * K + _c) * 2; }
;   __amdgpu_buffer_rsrc_t rs_A = __builtin_amdgcn_make_buffer_rsrc((void*)A, 0, 0x7fffffff, 0x00020000);
;   __amdgpu_buffer_rsrc_t rs_Bt = __builtin_amdgcn_make_buffer_rsrc((void*)Bt, 0, 0x7fffffff, 0x00020000);
;   if (!pre) {
;     STAGE(SB(0, 0), Bt, bcol, 0); STAGE(SA(0, 0), A, brow, 0);
;     STAGE(SB(0, 1), Bt, bcol + HALF, 0); STAGE(SA(0, 1), A, brow + HALF, 0);
;   }
;   if (wr == 1) BAR;
;   if (pre) { WAIT_V(0); } else { WAIT_V(4); }
;   BAR;
;   STAGE(SB(1, 0), Bt, bcol, 1); STAGE(SA(1, 0), A, brow, 1); STAGE(SB(1, 1), Bt, bcol + HALF, 1);
;   WAIT_V(6); BAR;
;     ...
;     LDB(B0, 0, 0); SCHED; LDA(At, 0, 0); STAGE(SA(1, 1), A, brow + HALF, t + 1);
;     WAIT_L(8); BAR; WAIT_L(0); MMA(0, 0, At, B0); BAR; SCHED;
;     LDB(B1, 0, 1); STAGE(SB(0, 0), Bt, bcol, t + 2);
;     BAR; WAIT_L(0); MMA(0, 1, At, B1); BAR;
.LBB0_1926:
	v_readlane_b32 s25, v254, 30
	s_lshl_b32 s16, s20, 11
	s_or_b32 s10, s16, 0x80
	v_add_u32_e32 v146, s25, v0
	v_add_u32_e32 v147, 0x2000, v146
	v_readfirstlane_b32 s11, v146
	s_mov_b32 m0, s11
	v_readfirstlane_b32 s11, v147
	v_add_u32_e32 v148, 0x8000, v136
	s_barrier
	buffer_load_dwordx4 v32, s[76:79], s10 offen lds
	s_mov_b32 m0, s11
	s_lshl_b32 s17, s19, 11
	v_readfirstlane_b32 s24, v148
	v_add_u32_e32 v150, 0xa000, v136
	v_readlane_b32 s26, v254, 31
	buffer_load_dwordx4 v131, s[76:79], s10 offen lds
	s_or_b32 s23, s17, 0x80
	s_mov_b32 s10, s78
	s_mov_b32 s11, s79
	s_mov_b32 m0, s24
	v_readfirstlane_b32 s24, v150
	v_add_u32_e32 v153, s26, v0
	buffer_load_dwordx4 v32, s[8:11], s23 offen lds
	s_mov_b32 m0, s24
	v_readfirstlane_b32 s24, v153
	v_add_u32_e32 v154, 0x2000, v153
	buffer_load_dwordx4 v131, s[8:11], s23 offen lds
	s_add_i32 s23, s16, 0x40080
	s_mov_b32 m0, s24
	v_readfirstlane_b32 s24, v154
	buffer_load_dwordx4 v32, s[76:79], s23 offen lds
	s_mov_b32 m0, s24
	v_and_b32_e32 v2, 15, v130
	buffer_load_dwordx4 v131, s[76:79], s23 offen lds
	v_lshlrev_b32_e32 v0, 6, v2
	v_lshlrev_b32_e32 v2, 2, v130
	v_and_b32_e32 v3, 48, v130
	v_and_b32_e32 v2, 32, v2
	v_bitop3_b32 v0, v0, v2, v3 bitop3:0x36
	s_waitcnt vmcnt(11)
	v_lshlrev_b32_e32 v8, 6, v130
	s_movk_i32 s23, 0x3c0
	s_waitcnt vmcnt(6)
	v_add_u32_e32 v4, s71, v0
	v_add_u32_e32 v5, s73, v0
	v_add_u32_e32 v6, s25, v0
	v_add_u32_e32 v7, s26, v0
	v_lshlrev_b32_e32 v1, 13, v1
	v_add_u32_e32 v10, 0, v0
	v_and_or_b32 v0, v8, s23, v3
	v_and_b32_e32 v9, 0x3000, v8
	v_xad_u32 v2, v0, v2, 0
	v_or_b32_e32 v3, 0x800, v1
	v_or_b32_e32 v8, 0x1000, v1
	v_or_b32_e32 v11, 0x1800, v1
	v_add_u32_e32 v152, 0xc000, v136
	v_add_u32_e32 v151, 0xe000, v136
	v_add_u32_e32 v139, 0x2000, v137
	v_add_u32_e32 v138, 0x2000, v134
	s_mov_b32 s23, -2
	s_mov_b32 s24, 0
	v_add_u32_e32 v155, v4, v9
	v_add_u32_e32 v143, v10, v1
	v_add_u32_e32 v142, v2, v3
	v_add_u32_e32 v141, v2, v8
	v_add_u32_e32 v140, v2, v11
	v_add_u32_e32 v149, v5, v9
	v_add_u32_e32 v145, v6, v9
	v_add_u32_e32 v144, v7, v9
	s_waitcnt vmcnt(10)
	s_barrier
.Lpk4:
	ds_read_b128 v[156:159], v155
	ds_read_b128 v[166:169], v155 offset:1024
	ds_read_b128 v[170:173], v155 offset:2048
	ds_read_b128 v[174:177], v155 offset:3072
	s_add_i32 s25, s17, s24
	v_readfirstlane_b32 s27, v152
	s_add_i32 s26, s25, 0x40080
	s_mov_b32 m0, s27
	v_readfirstlane_b32 s27, v151
	ds_read_b128 v[186:189], v143
	ds_read_b128 v[190:193], v143 offset:1024
	ds_read_b128 v[194:197], v142
	ds_read_b128 v[198:201], v142 offset:1024
	ds_read_b128 v[202:205], v141
	ds_read_b128 v[206:209], v141 offset:1024
	ds_read_b128 v[210:213], v140
	ds_read_b128 v[214:217], v140 offset:1024
	buffer_load_dwordx4 v32, s[8:11], s26 offen lds
	s_mov_b32 m0, s27
	s_nop 0
	buffer_load_dwordx4 v131, s[8:11], s26 offen lds
	s_waitcnt lgkmcnt(8)
	s_barrier
	s_waitcnt lgkmcnt(0)
	s_setprio 1
	s_waitcnt lgkmcnt(7)
	v_mfma_f32_16x16x32_bf16 v[126:129], v[186:189], v[156:159], 0
	v_mfma_f32_16x16x32_bf16 v[122:125], v[186:189], v[170:173], 0
	s_waitcnt lgkmcnt(5)
	v_mfma_f32_16x16x32_bf16 v[118:121], v[194:197], v[156:159], 0
	v_mfma_f32_16x16x32_bf16 v[114:117], v[194:197], v[170:173], 0
	s_waitcnt lgkmcnt(3)
	v_mfma_f32_16x16x32_bf16 v[110:113], v[202:205], v[156:159], 0
	v_mfma_f32_16x16x32_bf16 v[106:109], v[202:205], v[170:173], 0
	s_waitcnt lgkmcnt(1)
	v_mfma_f32_16x16x32_bf16 v[102:105], v[210:213], v[156:159], 0
	v_mfma_f32_16x16x32_bf16 v[98:101], v[210:213], v[170:173], 0
	v_mfma_f32_16x16x32_bf16 v[126:129], v[190:193], v[166:169], v[126:129]
	v_mfma_f32_16x16x32_bf16 v[122:125], v[190:193], v[174:177], v[122:125]
	v_mfma_f32_16x16x32_bf16 v[118:121], v[198:201], v[166:169], v[118:121]
	v_mfma_f32_16x16x32_bf16 v[114:117], v[198:201], v[174:177], v[114:117]
	v_mfma_f32_16x16x32_bf16 v[110:113], v[206:209], v[166:169], v[110:113]
	v_mfma_f32_16x16x32_bf16 v[106:109], v[206:209], v[174:177], v[106:109]
	s_waitcnt lgkmcnt(0)
	v_mfma_f32_16x16x32_bf16 v[102:105], v[214:217], v[166:169], v[102:105]
	v_mfma_f32_16x16x32_bf16 v[98:101], v[214:217], v[174:177], v[98:101]
	s_setprio 0
	s_barrier
	s_add_i32 s26, s16, s24
	v_readfirstlane_b32 s28, v137
	s_add_i32 s27, s26, 0x100
	s_mov_b32 m0, s28
	v_readfirstlane_b32 s28, v139
	ds_read_b128 v[218:221], v149
	ds_read_b128 v[222:225], v149 offset:1024
	ds_read_b128 v[226:229], v149 offset:2048
	ds_read_b128 v[230:233], v149 offset:3072
	buffer_load_dwordx4 v32, s[76:79], s27 offen lds
	s_mov_b32 m0, s28
	s_nop 0
	buffer_load_dwordx4 v131, s[76:79], s27 offen lds
	s_barrier
	s_waitcnt lgkmcnt(0)
	s_setprio 1
	s_waitcnt lgkmcnt(3)
	v_mfma_f32_16x16x32_bf16 v[94:97], v[186:189], v[218:221], 0
	s_waitcnt lgkmcnt(1)
	v_mfma_f32_16x16x32_bf16 v[90:93], v[186:189], v[226:229], 0
	v_mfma_f32_16x16x32_bf16 v[86:89], v[194:197], v[218:221], 0
	v_mfma_f32_16x16x32_bf16 v[82:85], v[194:197], v[226:229], 0
	v_mfma_f32_16x16x32_bf16 v[78:81], v[202:205], v[218:221], 0
	v_mfma_f32_16x16x32_bf16 v[74:77], v[202:205], v[226:229], 0
	v_mfma_f32_16x16x32_bf16 v[70:73], v[210:213], v[218:221], 0
	v_mfma_f32_16x16x32_bf16 v[66:69], v[210:213], v[226:229], 0
	v_mfma_f32_16x16x32_bf16 v[94:97], v[190:193], v[222:225], v[94:97]
	s_waitcnt lgkmcnt(0)
	v_mfma_f32_16x16x32_bf16 v[90:93], v[190:193], v[230:233], v[90:93]
	v_mfma_f32_16x16x32_bf16 v[86:89], v[198:201], v[222:225], v[86:89]
	v_mfma_f32_16x16x32_bf16 v[82:85], v[198:201], v[230:233], v[82:85]
	v_mfma_f32_16x16x32_bf16 v[78:81], v[206:209], v[222:225], v[78:81]
	v_mfma_f32_16x16x32_bf16 v[74:77], v[206:209], v[230:233], v[74:77]
	v_mfma_f32_16x16x32_bf16 v[70:73], v[214:217], v[222:225], v[70:73]
	v_mfma_f32_16x16x32_bf16 v[66:69], v[214:217], v[230:233], v[66:69]
	s_setprio 0
	v_readfirstlane_b32 s28, v136
	s_add_i32 s27, s25, 0x100
	s_mov_b32 m0, s28
	v_readfirstlane_b32 s28, v135
	s_barrier
; #define STAGE(P, BASE, br, kt) do { int _so = ((br) * K + (kt) * BK) * 2; \
;     __builtin_amdgcn_raw_ptr_buffer_load_lds(rs_##BASE, (__attribute__((address_space(3))) void*)((char*)(P) + tx * 16), 16, voff0, _so, 0, 0); \
;     __builtin_amdgcn_raw_ptr_buffer_load_lds(rs_##BASE, (__attribute__((address_space(3))) void*)((char*)(P) + tx * 16 + 8192), 16, voff1, _so, 0, 0); } while (0)
; #define LDA(dst, b, h) _Pragma("unroll") for (int m = 0; m < 4; ++m) _Pragma("unroll") for (int k = 0; k < 2; ++k) \
;     dst[m][k] = *reinterpret_cast<const bf16x8*>((char*)SA(b, h) + lds_byte(wr * 64 + m * 16 + fr, k * 32 + fq * 8))
; #define LDB(dst, b, h) _Pragma("unroll") for (int n = 0; n < 2; ++n) _Pragma("unroll") for (int k = 0; k < 2; ++k) \
;     dst[n][k] = *reinterpret_cast<const bf16x8*>((char*)SB(b, h) + lds_byte(wc * 32 + n * 16 + fr, k * 32 + fq * 8))
; #define MMA(ai, bj, At, Bt_) do { __builtin_amdgcn_s_setprio(1); \
;     _Pragma("unroll") for (int m = 0; m < 4; ++m) _Pragma("unroll") for (int n = 0; n < 2; ++n) _Pragma("unroll") for (int k = 0; k < 2; ++k) \
;       acc[ai][bj][m][n] = __builtin_amdgcn_mfma_f32_16x16x32_bf16(At[m][k], Bt_[n][k], acc[ai][bj][m][n], 0, 0, 0); \
;     __builtin_amdgcn_s_setprio(0); } while (0)
; #define WAIT_V(n) asm volatile("s_waitcnt vmcnt(" #n ")" ::: "memory")
; #define WAIT_L(n) asm volatile("s_waitcnt lgkmcnt(" #n ")" ::: "memory")
; #define BAR __builtin_amdgcn_s_barrier()
; #define SCHED __builtin_amdgcn_sched_barrier(0)
; template <class Epi> ...
;     ...
;     LDA(At, 0, 1); STAGE(SA(0, 0), A, brow, t + 2);
;     BAR; WAIT_L(0); MMA(1, 0, At, B0); BAR; SCHED;
;     STAGE(SB(0, 1), Bt, bcol + HALF, t + 2);
;     WAIT_V(6); BAR; MMA(1, 1, At, B1); BAR;
;     LDB(B0, 1, 0); SCHED; LDA(At, 1, 0); STAGE(SA(0, 1), A, brow + HALF, t + 2);
;     WAIT_L(8); BAR; WAIT_L(0); MMA(0, 0, At, B0); BAR; SCHED;
	ds_read_b128 v[186:189], v143 offset:16384
	ds_read_b128 v[190:193], v143 offset:17408
	ds_read_b128 v[194:197], v142 offset:16384
	ds_read_b128 v[198:201], v142 offset:17408
	ds_read_b128 v[202:205], v141 offset:16384
	ds_read_b128 v[206:209], v141 offset:17408
	ds_read_b128 v[210:213], v140 offset:16384
	ds_read_b128 v[214:217], v140 offset:17408
	buffer_load_dwordx4 v32, s[8:11], s27 offen lds
	s_mov_b32 m0, s28
	s_nop 0
	buffer_load_dwordx4 v131, s[8:11], s27 offen lds
	s_barrier
	s_waitcnt lgkmcnt(0)
	s_setprio 1
	s_waitcnt lgkmcnt(7)
	v_mfma_f32_16x16x32_bf16 v[62:65], v[186:189], v[156:159], 0
	v_mfma_f32_16x16x32_bf16 v[58:61], v[186:189], v[170:173], 0
	s_waitcnt lgkmcnt(5)
	v_mfma_f32_16x16x32_bf16 v[54:57], v[194:197], v[156:159], 0
	v_mfma_f32_16x16x32_bf16 v[50:53], v[194:197], v[170:173], 0
	s_waitcnt lgkmcnt(3)
	v_mfma_f32_16x16x32_bf16 v[46:49], v[202:205], v[156:159], 0
	v_mfma_f32_16x16x32_bf16 v[42:45], v[202:205], v[170:173], 0
	s_waitcnt lgkmcnt(1)
	v_mfma_f32_16x16x32_bf16 v[38:41], v[210:213], v[156:159], 0
	v_mfma_f32_16x16x32_bf16 v[34:37], v[210:213], v[170:173], 0
	v_mfma_f32_16x16x32_bf16 v[62:65], v[190:193], v[166:169], v[62:65]
	v_mfma_f32_16x16x32_bf16 v[58:61], v[190:193], v[174:177], v[58:61]
	v_mfma_f32_16x16x32_bf16 v[54:57], v[198:201], v[166:169], v[54:57]
	v_mfma_f32_16x16x32_bf16 v[50:53], v[198:201], v[174:177], v[50:53]
	v_mfma_f32_16x16x32_bf16 v[46:49], v[206:209], v[166:169], v[46:49]
	v_mfma_f32_16x16x32_bf16 v[42:45], v[206:209], v[174:177], v[42:45]
	s_waitcnt lgkmcnt(0)
	v_mfma_f32_16x16x32_bf16 v[38:41], v[214:217], v[166:169], v[38:41]
	v_mfma_f32_16x16x32_bf16 v[34:37], v[214:217], v[174:177], v[34:37]
	s_setprio 0
	s_barrier
	v_readfirstlane_b32 s28, v134
	s_add_i32 s27, s26, 0x40100
	s_mov_b32 m0, s28
	v_readfirstlane_b32 s28, v138
	buffer_load_dwordx4 v32, s[76:79], s27 offen lds
	s_mov_b32 m0, s28
	s_nop 0
	buffer_load_dwordx4 v131, s[76:79], s27 offen lds
	s_waitcnt vmcnt(6)
	s_barrier
	s_setprio 1
	v_mfma_f32_16x16x32_bf16 v[28:31], v[186:189], v[218:221], 0
	v_mfma_f32_16x16x32_bf16 v[24:27], v[186:189], v[226:229], 0
	v_mfma_f32_16x16x32_bf16 v[20:23], v[194:197], v[218:221], 0
	v_mfma_f32_16x16x32_bf16 v[16:19], v[194:197], v[226:229], 0
	v_mfma_f32_16x16x32_bf16 v[12:15], v[202:205], v[218:221], 0
	v_mfma_f32_16x16x32_bf16 v[8:11], v[202:205], v[226:229], 0
	v_mfma_f32_16x16x32_bf16 v[4:7], v[210:213], v[218:221], 0
	v_mfma_f32_16x16x32_bf16 v[0:3], v[210:213], v[226:229], 0
	v_mfma_f32_16x16x32_bf16 v[28:31], v[190:193], v[222:225], v[28:31]
	v_mfma_f32_16x16x32_bf16 v[24:27], v[190:193], v[230:233], v[24:27]
	v_mfma_f32_16x16x32_bf16 v[20:23], v[198:201], v[222:225], v[20:23]
	v_mfma_f32_16x16x32_bf16 v[16:19], v[198:201], v[230:233], v[16:19]
	v_mfma_f32_16x16x32_bf16 v[12:15], v[206:209], v[222:225], v[12:15]
	v_mfma_f32_16x16x32_bf16 v[8:11], v[206:209], v[230:233], v[8:11]
	v_mfma_f32_16x16x32_bf16 v[4:7], v[214:217], v[222:225], v[4:7]
	v_mfma_f32_16x16x32_bf16 v[0:3], v[214:217], v[230:233], v[0:3]
	s_setprio 0
	s_barrier
	ds_read_b128 v[156:159], v145
	ds_read_b128 v[166:169], v145 offset:1024
	ds_read_b128 v[170:173], v145 offset:2048
	ds_read_b128 v[174:177], v145 offset:3072
	v_readfirstlane_b32 s28, v133
	s_add_i32 s27, s25, 0x40100
	s_mov_b32 m0, s28
	v_readfirstlane_b32 s28, v132
	ds_read_b128 v[186:189], v143 offset:32768
	ds_read_b128 v[190:193], v143 offset:33792
	ds_read_b128 v[194:197], v142 offset:32768
	ds_read_b128 v[198:201], v142 offset:33792
	ds_read_b128 v[202:205], v141 offset:32768
	ds_read_b128 v[206:209], v141 offset:33792
	ds_read_b128 v[210:213], v140 offset:32768
	ds_read_b128 v[214:217], v140 offset:33792
	buffer_load_dwordx4 v32, s[8:11], s27 offen lds
	s_mov_b32 m0, s28
	s_nop 0
	buffer_load_dwordx4 v131, s[8:11], s27 offen lds
	s_waitcnt lgkmcnt(8)
	s_barrier
	s_waitcnt lgkmcnt(0)
	s_setprio 1
	s_waitcnt lgkmcnt(7)
	v_mfma_f32_16x16x32_bf16 v[126:129], v[186:189], v[156:159], v[126:129]
	v_mfma_f32_16x16x32_bf16 v[122:125], v[186:189], v[170:173], v[122:125]
	s_waitcnt lgkmcnt(5)
	v_mfma_f32_16x16x32_bf16 v[118:121], v[194:197], v[156:159], v[118:121]
	v_mfma_f32_16x16x32_bf16 v[114:117], v[194:197], v[170:173], v[114:117]
	s_waitcnt lgkmcnt(3)
	v_mfma_f32_16x16x32_bf16 v[110:113], v[202:205], v[156:159], v[110:113]
	v_mfma_f32_16x16x32_bf16 v[106:109], v[202:205], v[170:173], v[106:109]
	s_waitcnt lgkmcnt(1)
	v_mfma_f32_16x16x32_bf16 v[102:105], v[210:213], v[156:159], v[102:105]
	v_mfma_f32_16x16x32_bf16 v[98:101], v[210:213], v[170:173], v[98:101]
	v_mfma_f32_16x16x32_bf16 v[126:129], v[190:193], v[166:169], v[126:129]
	v_mfma_f32_16x16x32_bf16 v[122:125], v[190:193], v[174:177], v[122:125]
	v_mfma_f32_16x16x32_bf16 v[118:121], v[198:201], v[166:169], v[118:121]
	v_mfma_f32_16x16x32_bf16 v[114:117], v[198:201], v[174:177], v[114:117]
	v_mfma_f32_16x16x32_bf16 v[110:113], v[206:209], v[166:169], v[110:113]
	v_mfma_f32_16x16x32_bf16 v[106:109], v[206:209], v[174:177], v[106:109]
	s_waitcnt lgkmcnt(0)
	v_mfma_f32_16x16x32_bf16 v[102:105], v[214:217], v[166:169], v[102:105]
	v_mfma_f32_16x16x32_bf16 v[98:101], v[214:217], v[174:177], v[98:101]
	s_setprio 0
	s_barrier
; #define STAGE(P, BASE, br, kt) do { int _so = ((br) * K + (kt) * BK) * 2; \
;     __builtin_amdgcn_raw_ptr_buffer_load_lds(rs_##BASE, (__attribute__((address_space(3))) void*)((char*)(P) + tx * 16), 16, voff0, _so, 0, 0); \
;     __builtin_amdgcn_raw_ptr_buffer_load_lds(rs_##BASE, (__attribute__((address_space(3))) void*)((char*)(P) + tx * 16 + 8192), 16, voff1, _so, 0, 0); } while (0)
; #define LDA(dst, b, h) _Pragma("unroll") for (int m = 0; m < 4; ++m) _Pragma("unroll") for (int k = 0; k < 2; ++k) \
;     dst[m][k] = *reinterpret_cast<const bf16x8*>((char*)SA(b, h) + lds_byte(wr * 64 + m * 16 + fr, k * 32 + fq * 8))
; #define LDB(dst, b, h) _Pragma("unroll") for (int n = 0; n < 2; ++n) _Pragma("unroll") for (int k = 0; k < 2; ++k) \
;     dst[n][k] = *reinterpret_cast<const bf16x8*>((char*)SB(b, h) + lds_byte(wc * 32 + n * 16 + fr, k * 32 + fq * 8))
; #define MMA(ai, bj, At, Bt_) do { __builtin_amdgcn_s_setprio(1); \
;     _Pragma("unroll") for (int m = 0; m < 4; ++m) _Pragma("unroll") for (int n = 0; n < 2; ++n) _Pragma("unroll") for (int k = 0; k < 2; ++k) \
;       acc[ai][bj][m][n] = __builtin_amdgcn_mfma_f32_16x16x32_bf16(At[m][k], Bt_[n][k], acc[ai][bj][m][n], 0, 0, 0); \
;     __builtin_amdgcn_s_setprio(0); } while (0)
; #define WAIT_V(n) asm volatile("s_waitcnt vmcnt(" #n ")" ::: "memory")
; #define WAIT_L(n) asm volatile("s_waitcnt lgkmcnt(" #n ")" ::: "memory")
; #define BAR __builtin_amdgcn_s_barrier()
; #define SCHED __builtin_amdgcn_sched_barrier(0)
; template <class Epi> ...
;     ...
;   for (int t = 0; t < nt - 2; t += 2) {
;     ...
;     LDB(B1, 1, 1); STAGE(SB(1, 0), Bt, bcol, t + 3);
;     BAR; WAIT_L(0); MMA(0, 1, At, B1); BAR;
;     LDA(At, 1, 1); STAGE(SA(1, 0), A, brow, t + 3);
;     BAR; WAIT_L(0); MMA(1, 0, At, B0); BAR; SCHED;
;     STAGE(SB(1, 1), Bt, bcol + HALF, t + 3);
;     WAIT_V(6); BAR; MMA(1, 1, At, B1); BAR;
;   }
	v_readfirstlane_b32 s28, v146
	s_add_i32 s27, s26, 0x180
	s_mov_b32 m0, s28
	v_readfirstlane_b32 s28, v147
	ds_read_b128 v[218:221], v144
	ds_read_b128 v[222:225], v144 offset:1024
	ds_read_b128 v[226:229], v144 offset:2048
	ds_read_b128 v[230:233], v144 offset:3072
	buffer_load_dwordx4 v32, s[76:79], s27 offen lds
	s_mov_b32 m0, s28
	s_nop 0
	buffer_load_dwordx4 v131, s[76:79], s27 offen lds
	s_barrier
	s_waitcnt lgkmcnt(0)
	s_setprio 1
	s_waitcnt lgkmcnt(3)
	v_mfma_f32_16x16x32_bf16 v[94:97], v[186:189], v[218:221], v[94:97]
	s_waitcnt lgkmcnt(1)
	v_mfma_f32_16x16x32_bf16 v[90:93], v[186:189], v[226:229], v[90:93]
	v_mfma_f32_16x16x32_bf16 v[86:89], v[194:197], v[218:221], v[86:89]
	v_mfma_f32_16x16x32_bf16 v[82:85], v[194:197], v[226:229], v[82:85]
	v_mfma_f32_16x16x32_bf16 v[78:81], v[202:205], v[218:221], v[78:81]
	v_mfma_f32_16x16x32_bf16 v[74:77], v[202:205], v[226:229], v[74:77]
	v_mfma_f32_16x16x32_bf16 v[70:73], v[210:213], v[218:221], v[70:73]
	v_mfma_f32_16x16x32_bf16 v[66:69], v[210:213], v[226:229], v[66:69]
	v_mfma_f32_16x16x32_bf16 v[94:97], v[190:193], v[222:225], v[94:97]
	s_waitcnt lgkmcnt(0)
	v_mfma_f32_16x16x32_bf16 v[90:93], v[190:193], v[230:233], v[90:93]
	v_mfma_f32_16x16x32_bf16 v[86:89], v[198:201], v[222:225], v[86:89]
	v_mfma_f32_16x16x32_bf16 v[82:85], v[198:201], v[230:233], v[82:85]
	v_mfma_f32_16x16x32_bf16 v[78:81], v[206:209], v[222:225], v[78:81]
	v_mfma_f32_16x16x32_bf16 v[74:77], v[206:209], v[230:233], v[74:77]
	v_mfma_f32_16x16x32_bf16 v[70:73], v[214:217], v[222:225], v[70:73]
	v_mfma_f32_16x16x32_bf16 v[66:69], v[214:217], v[230:233], v[66:69]
	s_setprio 0
	v_readfirstlane_b32 s27, v148
	s_addk_i32 s25, 0x180
	s_mov_b32 m0, s27
	v_readfirstlane_b32 s27, v150
	s_barrier
	ds_read_b128 v[186:189], v143 offset:49152
	ds_read_b128 v[190:193], v143 offset:50176
	ds_read_b128 v[194:197], v142 offset:49152
	ds_read_b128 v[198:201], v142 offset:50176
	ds_read_b128 v[202:205], v141 offset:49152
	ds_read_b128 v[206:209], v141 offset:50176
	ds_read_b128 v[210:213], v140 offset:49152
	ds_read_b128 v[214:217], v140 offset:50176
	buffer_load_dwordx4 v32, s[8:11], s25 offen lds
	s_mov_b32 m0, s27
	s_nop 0
	buffer_load_dwordx4 v131, s[8:11], s25 offen lds
	s_barrier
	s_waitcnt lgkmcnt(0)
	s_setprio 1
	s_waitcnt lgkmcnt(7)
	v_mfma_f32_16x16x32_bf16 v[62:65], v[186:189], v[156:159], v[62:65]
	v_mfma_f32_16x16x32_bf16 v[58:61], v[186:189], v[170:173], v[58:61]
	s_waitcnt lgkmcnt(5)
	v_mfma_f32_16x16x32_bf16 v[54:57], v[194:197], v[156:159], v[54:57]
	v_mfma_f32_16x16x32_bf16 v[50:53], v[194:197], v[170:173], v[50:53]
	s_waitcnt lgkmcnt(3)
	v_mfma_f32_16x16x32_bf16 v[46:49], v[202:205], v[156:159], v[46:49]
	v_mfma_f32_16x16x32_bf16 v[42:45], v[202:205], v[170:173], v[42:45]
	s_waitcnt lgkmcnt(1)
	v_mfma_f32_16x16x32_bf16 v[38:41], v[210:213], v[156:159], v[38:41]
	v_mfma_f32_16x16x32_bf16 v[34:37], v[210:213], v[170:173], v[34:37]
	v_mfma_f32_16x16x32_bf16 v[62:65], v[190:193], v[166:169], v[62:65]
	v_mfma_f32_16x16x32_bf16 v[58:61], v[190:193], v[174:177], v[58:61]
	v_mfma_f32_16x16x32_bf16 v[54:57], v[198:201], v[166:169], v[54:57]
	v_mfma_f32_16x16x32_bf16 v[50:53], v[198:201], v[174:177], v[50:53]
	v_mfma_f32_16x16x32_bf16 v[46:49], v[206:209], v[166:169], v[46:49]
	v_mfma_f32_16x16x32_bf16 v[42:45], v[206:209], v[174:177], v[42:45]
	s_waitcnt lgkmcnt(0)
	v_mfma_f32_16x16x32_bf16 v[38:41], v[214:217], v[166:169], v[38:41]
	v_mfma_f32_16x16x32_bf16 v[34:37], v[214:217], v[174:177], v[34:37]
	s_setprio 0
	s_barrier
	v_readfirstlane_b32 s25, v153
	s_add_i32 s26, s26, 0x40180
	s_mov_b32 m0, s25
	v_readfirstlane_b32 s25, v154
	buffer_load_dwordx4 v32, s[76:79], s26 offen lds
	s_mov_b32 m0, s25
	s_nop 0
	buffer_load_dwordx4 v131, s[76:79], s26 offen lds
	s_waitcnt vmcnt(6)
	s_barrier
	s_setprio 1
	v_mfma_f32_16x16x32_bf16 v[28:31], v[186:189], v[218:221], v[28:31]
	v_mfma_f32_16x16x32_bf16 v[24:27], v[186:189], v[226:229], v[24:27]
	v_mfma_f32_16x16x32_bf16 v[20:23], v[194:197], v[218:221], v[20:23]
	v_mfma_f32_16x16x32_bf16 v[16:19], v[194:197], v[226:229], v[16:19]
	v_mfma_f32_16x16x32_bf16 v[12:15], v[202:205], v[218:221], v[12:15]
	v_mfma_f32_16x16x32_bf16 v[8:11], v[202:205], v[226:229], v[8:11]
	v_mfma_f32_16x16x32_bf16 v[4:7], v[210:213], v[218:221], v[4:7]
	v_mfma_f32_16x16x32_bf16 v[0:3], v[210:213], v[226:229], v[0:3]
	v_mfma_f32_16x16x32_bf16 v[28:31], v[190:193], v[222:225], v[28:31]
	v_mfma_f32_16x16x32_bf16 v[24:27], v[190:193], v[230:233], v[24:27]
	v_mfma_f32_16x16x32_bf16 v[20:23], v[198:201], v[222:225], v[20:23]
	v_mfma_f32_16x16x32_bf16 v[16:19], v[198:201], v[230:233], v[16:19]
	v_mfma_f32_16x16x32_bf16 v[12:15], v[206:209], v[222:225], v[12:15]
	v_mfma_f32_16x16x32_bf16 v[8:11], v[206:209], v[230:233], v[8:11]
	v_mfma_f32_16x16x32_bf16 v[4:7], v[214:217], v[222:225], v[4:7]
	v_mfma_f32_16x16x32_bf16 v[0:3], v[214:217], v[230:233], v[0:3]
	s_setprio 0
	s_add_i32 s23, s23, 2
	s_addk_i32 s24, 0x100
	s_cmp_lt_u32 s23, 12
	s_barrier
	s_cbranch_scc1 .LBB0_1927
	s_branch .Lpx4

; #define STAGE(P, BASE, br, kt) do { int _so = ((br) * K + (kt) * BK) * 2; \
;     __builtin_amdgcn_raw_ptr_buffer_load_lds(rs_##BASE, (__attribute__((address_space(3))) void*)((char*)(P) + tx * 16), 16, voff0, _so, 0, 0); \
;     __builtin_amdgcn_raw_ptr_buffer_load_lds(rs_##BASE, (__attribute__((address_space(3))) void*)((char*)(P) + tx * 16 + 8192), 16, voff1, _so, 0, 0); } while (0)
; #define LDA(dst, b, h) _Pragma("unroll") for (int m = 0; m < 4; ++m) _Pragma("unroll") for (int k = 0; k < 2; ++k) \
;     dst[m][k] = *reinterpret_cast<const bf16x8*>((char*)SA(b, h) + lds_byte(wr * 64 + m * 16 + fr, k * 32 + fq * 8))
; #define LDB(dst, b, h) _Pragma("unroll") for (int n = 0; n < 2; ++n) _Pragma("unroll") for (int k = 0; k < 2; ++k) \
;     dst[n][k] = *reinterpret_cast<const bf16x8*>((char*)SB(b, h) + lds_byte(wc * 32 + n * 16 + fr, k * 32 + fq * 8))
; #define MMA(ai, bj, At, Bt_) do { __builtin_amdgcn_s_setprio(1); \
;     _Pragma("unroll") for (int m = 0; m < 4; ++m) _Pragma("unroll") for (int n = 0; n < 2; ++n) _Pragma("unroll") for (int k = 0; k < 2; ++k) \
;       acc[ai][bj][m][n] = __builtin_amdgcn_mfma_f32_16x16x32_bf16(At[m][k], Bt_[n][k], acc[ai][bj][m][n], 0, 0, 0); \
;     __builtin_amdgcn_s_setprio(0); } while (0)
; #define WAIT_V(n) asm volatile("s_waitcnt vmcnt(" #n ")" ::: "memory")
; #define WAIT_L(n) asm volatile("s_waitcnt lgkmcnt(" #n ")" ::: "memory")
; #define BAR __builtin_amdgcn_s_barrier()
; template <class Epi> ...
;     ...
;   { LDB(B0, 0, 0); LDA(At, 0, 0); STAGE(SA(1, 1), A, brow + HALF, nt - 1);
;     BAR; WAIT_L(0); MMA(0, 0, At, B0); BAR;
;     LDB(B1, 0, 1); BAR; WAIT_L(0); MMA(0, 1, At, B1); BAR;
;     LDA(At, 0, 1); WAIT_V(4); BAR; WAIT_L(0); MMA(1, 0, At, B0); MMA(1, 1, At, B1); BAR; }
.Lpx4:
	s_or_b32 s16, s17, 0x40780
	v_readfirstlane_b32 s17, v152
	s_mov_b32 s10, s78
	s_mov_b32 s11, s79
	s_mov_b32 m0, s17
	v_readfirstlane_b32 s17, v151
	ds_read_b128 v[156:159], v155
	ds_read_b128 v[166:169], v155 offset:1024
	ds_read_b128 v[170:173], v155 offset:2048
	ds_read_b128 v[174:177], v155 offset:3072
	ds_read_b128 v[186:189], v143
	ds_read_b128 v[190:193], v143 offset:1024
	ds_read_b128 v[194:197], v142
	ds_read_b128 v[198:201], v142 offset:1024
	ds_read_b128 v[202:205], v141
	ds_read_b128 v[206:209], v141 offset:1024
	ds_read_b128 v[210:213], v140
	ds_read_b128 v[214:217], v140 offset:1024
	buffer_load_dwordx4 v32, s[8:11], s16 offen lds
	s_mov_b32 m0, s17
	s_nop 0
	buffer_load_dwordx4 v131, s[8:11], s16 offen lds
	s_barrier
	s_waitcnt lgkmcnt(0)
	s_setprio 1
	s_waitcnt lgkmcnt(7)
	v_mfma_f32_16x16x32_bf16 v[126:129], v[186:189], v[156:159], v[126:129]
	v_mfma_f32_16x16x32_bf16 v[122:125], v[186:189], v[170:173], v[122:125]
	s_waitcnt lgkmcnt(5)
	v_mfma_f32_16x16x32_bf16 v[118:121], v[194:197], v[156:159], v[118:121]
	v_mfma_f32_16x16x32_bf16 v[114:117], v[194:197], v[170:173], v[114:117]
	s_waitcnt lgkmcnt(3)
	v_mfma_f32_16x16x32_bf16 v[110:113], v[202:205], v[156:159], v[110:113]
	v_mfma_f32_16x16x32_bf16 v[106:109], v[202:205], v[170:173], v[106:109]
	s_waitcnt lgkmcnt(1)
	v_mfma_f32_16x16x32_bf16 v[102:105], v[210:213], v[156:159], v[102:105]
	v_mfma_f32_16x16x32_bf16 v[98:101], v[210:213], v[170:173], v[98:101]
	v_mfma_f32_16x16x32_bf16 v[126:129], v[190:193], v[166:169], v[126:129]
	v_mfma_f32_16x16x32_bf16 v[122:125], v[190:193], v[174:177], v[122:125]
	v_mfma_f32_16x16x32_bf16 v[118:121], v[198:201], v[166:169], v[118:121]
	v_mfma_f32_16x16x32_bf16 v[114:117], v[198:201], v[174:177], v[114:117]
	v_mfma_f32_16x16x32_bf16 v[110:113], v[206:209], v[166:169], v[110:113]
	v_mfma_f32_16x16x32_bf16 v[106:109], v[206:209], v[174:177], v[106:109]
	s_waitcnt lgkmcnt(0)
	v_mfma_f32_16x16x32_bf16 v[102:105], v[214:217], v[166:169], v[102:105]
	v_mfma_f32_16x16x32_bf16 v[98:101], v[214:217], v[174:177], v[98:101]
	s_setprio 0
	s_barrier
	ds_read_b128 v[150:153], v149
	ds_read_b128 v[218:221], v149 offset:1024
	ds_read_b128 v[222:225], v149 offset:2048
	ds_read_b128 v[146:149], v149 offset:3072
	s_barrier
	s_waitcnt lgkmcnt(0)
	s_setprio 1
	s_waitcnt lgkmcnt(3)
	v_mfma_f32_16x16x32_bf16 v[78:81], v[202:205], v[150:153], v[78:81]
	s_waitcnt lgkmcnt(1)
	v_mfma_f32_16x16x32_bf16 v[74:77], v[202:205], v[222:225], v[74:77]
	v_mfma_f32_16x16x32_bf16 v[70:73], v[210:213], v[150:153], v[70:73]
	v_mfma_f32_16x16x32_bf16 v[66:69], v[210:213], v[222:225], v[66:69]
	v_mfma_f32_16x16x32_bf16 v[94:97], v[186:189], v[150:153], v[94:97]
	v_mfma_f32_16x16x32_bf16 v[90:93], v[186:189], v[222:225], v[90:93]
	v_mfma_f32_16x16x32_bf16 v[86:89], v[194:197], v[150:153], v[86:89]
	v_mfma_f32_16x16x32_bf16 v[82:85], v[194:197], v[222:225], v[82:85]
	v_mfma_f32_16x16x32_bf16 v[78:81], v[206:209], v[218:221], v[78:81]
	s_waitcnt lgkmcnt(0)
	v_mfma_f32_16x16x32_bf16 v[74:77], v[206:209], v[146:149], v[74:77]
	v_mfma_f32_16x16x32_bf16 v[70:73], v[214:217], v[218:221], v[70:73]
	v_mfma_f32_16x16x32_bf16 v[66:69], v[214:217], v[146:149], v[66:69]
	v_mfma_f32_16x16x32_bf16 v[226:229], v[190:193], v[218:221], v[94:97]
	v_mfma_f32_16x16x32_bf16 v[186:189], v[190:193], v[146:149], v[90:93]
	v_mfma_f32_16x16x32_bf16 v[190:193], v[198:201], v[218:221], v[86:89]
	v_mfma_f32_16x16x32_bf16 v[194:197], v[198:201], v[146:149], v[82:85]
	s_setprio 0
	s_barrier
	s_nop 0
	ds_read_b128 v[82:85], v143 offset:16384
	ds_read_b128 v[86:89], v143 offset:17408
	ds_read_b128 v[90:93], v142 offset:16384
	ds_read_b128 v[94:97], v142 offset:17408
	ds_read_b128 v[198:201], v141 offset:16384
	ds_read_b128 v[202:205], v141 offset:17408
	ds_read_b128 v[206:209], v140 offset:16384
	ds_read_b128 v[210:213], v140 offset:17408
	s_waitcnt vmcnt(4)
	s_barrier
	s_waitcnt lgkmcnt(0)
	s_setprio 1
	s_waitcnt lgkmcnt(3)
	v_mfma_f32_16x16x32_bf16 v[46:49], v[198:201], v[156:159], v[46:49]
	v_mfma_f32_16x16x32_bf16 v[42:45], v[198:201], v[170:173], v[42:45]
	s_waitcnt lgkmcnt(1)
	v_mfma_f32_16x16x32_bf16 v[38:41], v[206:209], v[156:159], v[38:41]
	v_mfma_f32_16x16x32_bf16 v[34:37], v[206:209], v[170:173], v[34:37]
	v_mfma_f32_16x16x32_bf16 v[62:65], v[82:85], v[156:159], v[62:65]
	v_mfma_f32_16x16x32_bf16 v[58:61], v[82:85], v[170:173], v[58:61]
	v_mfma_f32_16x16x32_bf16 v[54:57], v[90:93], v[156:159], v[54:57]
	v_mfma_f32_16x16x32_bf16 v[50:53], v[90:93], v[170:173], v[50:53]
	v_mfma_f32_16x16x32_bf16 v[46:49], v[202:205], v[166:169], v[46:49]
	v_mfma_f32_16x16x32_bf16 v[42:45], v[202:205], v[174:177], v[42:45]
	s_waitcnt lgkmcnt(0)
	v_mfma_f32_16x16x32_bf16 v[38:41], v[210:213], v[166:169], v[38:41]
	v_mfma_f32_16x16x32_bf16 v[34:37], v[210:213], v[174:177], v[34:37]
	v_mfma_f32_16x16x32_bf16 v[214:217], v[86:89], v[166:169], v[62:65]
	v_mfma_f32_16x16x32_bf16 v[230:233], v[86:89], v[174:177], v[58:61]
	v_mfma_f32_16x16x32_bf16 v[234:237], v[94:97], v[166:169], v[54:57]
	v_mfma_f32_16x16x32_bf16 v[238:241], v[94:97], v[174:177], v[50:53]
	s_setprio 0
	s_setprio 1
	v_mfma_f32_16x16x32_bf16 v[0:3], v[206:209], v[222:225], v[0:3]
	v_mfma_f32_16x16x32_bf16 v[28:31], v[82:85], v[150:153], v[28:31]
	v_mfma_f32_16x16x32_bf16 v[24:27], v[82:85], v[222:225], v[24:27]
	v_mfma_f32_16x16x32_bf16 v[20:23], v[90:93], v[150:153], v[20:23]
	v_mfma_f32_16x16x32_bf16 v[16:19], v[90:93], v[222:225], v[16:19]
	v_mfma_f32_16x16x32_bf16 v[12:15], v[198:201], v[150:153], v[12:15]
	v_mfma_f32_16x16x32_bf16 v[8:11], v[198:201], v[222:225], v[8:11]
	v_mfma_f32_16x16x32_bf16 v[4:7], v[206:209], v[150:153], v[4:7]
	v_mfma_f32_16x16x32_bf16 v[0:3], v[210:213], v[146:149], v[0:3]
	v_mfma_f32_16x16x32_bf16 v[154:157], v[86:89], v[218:221], v[28:31]
	v_mfma_f32_16x16x32_bf16 v[158:161], v[86:89], v[146:149], v[24:27]
	v_mfma_f32_16x16x32_bf16 v[166:169], v[94:97], v[218:221], v[20:23]
	v_mfma_f32_16x16x32_bf16 v[170:173], v[94:97], v[146:149], v[16:19]
	v_mfma_f32_16x16x32_bf16 v[174:177], v[202:205], v[218:221], v[12:15]
	v_mfma_f32_16x16x32_bf16 v[198:201], v[202:205], v[146:149], v[8:11]
	v_mfma_f32_16x16x32_bf16 v[150:153], v[210:213], v[218:221], v[4:7]
	s_setprio 0
	s_barrier
; #define LDA(dst, b, h) _Pragma("unroll") for (int m = 0; m < 4; ++m) _Pragma("unroll") for (int k = 0; k < 2; ++k) \
;     dst[m][k] = *reinterpret_cast<const bf16x8*>((char*)SA(b, h) + lds_byte(wr * 64 + m * 16 + fr, k * 32 + fq * 8))
; #define LDB(dst, b, h) _Pragma("unroll") for (int n = 0; n < 2; ++n) _Pragma("unroll") for (int k = 0; k < 2; ++k) \
;     dst[n][k] = *reinterpret_cast<const bf16x8*>((char*)SB(b, h) + lds_byte(wc * 32 + n * 16 + fr, k * 32 + fq * 8))
; #define MMA(ai, bj, At, Bt_) do { __builtin_amdgcn_s_setprio(1); \
;     _Pragma("unroll") for (int m = 0; m < 4; ++m) _Pragma("unroll") for (int n = 0; n < 2; ++n) _Pragma("unroll") for (int k = 0; k < 2; ++k) \
;       acc[ai][bj][m][n] = __builtin_amdgcn_mfma_f32_16x16x32_bf16(At[m][k], Bt_[n][k], acc[ai][bj][m][n], 0, 0, 0); \
;     __builtin_amdgcn_s_setprio(0); } while (0)
; #define WAIT_V(n) asm volatile("s_waitcnt vmcnt(" #n ")" ::: "memory")
; #define WAIT_L(n) asm volatile("s_waitcnt lgkmcnt(" #n ")" ::: "memory")
; #define BAR __builtin_amdgcn_s_barrier()
; template <class Epi> ...
;     ...
;   { LDB(B0, 1, 0); LDA(At, 1, 0); WAIT_V(2); BAR; WAIT_L(0); MMA(0, 0, At, B0); BAR;
;     LDB(B1, 1, 1); WAIT_V(0); BAR; WAIT_L(0); MMA(0, 1, At, B1); BAR;
;     LDA(At, 1, 1); BAR; WAIT_L(0); MMA(1, 0, At, B0); MMA(1, 1, At, B1); BAR; }
;   if (wr == 0) BAR;
	s_nop 0
	ds_read_b128 v[4:7], v145
	ds_read_b128 v[8:11], v145 offset:1024
	ds_read_b128 v[12:15], v145 offset:2048
	ds_read_b128 v[146:149], v145 offset:3072
	ds_read_b128 v[16:19], v143 offset:32768
	ds_read_b128 v[20:23], v143 offset:33792
	ds_read_b128 v[24:27], v142 offset:32768
	ds_read_b128 v[50:53], v142 offset:33792
	ds_read_b128 v[202:205], v141 offset:32768
	ds_read_b128 v[206:209], v141 offset:33792
	ds_read_b128 v[210:213], v140 offset:32768
	ds_read_b128 v[218:221], v140 offset:33792
	s_waitcnt vmcnt(2)
	s_barrier
	s_waitcnt lgkmcnt(0)
	s_setprio 1
	s_waitcnt lgkmcnt(7)
	v_mfma_f32_16x16x32_bf16 v[28:31], v[16:19], v[4:7], v[126:129]
	s_waitcnt lgkmcnt(6)
	v_mfma_f32_16x16x32_bf16 v[126:129], v[20:23], v[8:11], v[28:31]
	v_mfma_f32_16x16x32_bf16 v[28:31], v[16:19], v[12:15], v[122:125]
	v_mfma_f32_16x16x32_bf16 v[94:97], v[20:23], v[146:149], v[28:31]
	s_waitcnt lgkmcnt(5)
	v_mfma_f32_16x16x32_bf16 v[28:31], v[24:27], v[4:7], v[118:121]
	s_waitcnt lgkmcnt(4)
	v_mfma_f32_16x16x32_bf16 v[122:125], v[50:53], v[8:11], v[28:31]
	v_mfma_f32_16x16x32_bf16 v[28:31], v[24:27], v[12:15], v[114:117]
	v_mfma_f32_16x16x32_bf16 v[90:93], v[50:53], v[146:149], v[28:31]
	s_waitcnt lgkmcnt(3)
	v_mfma_f32_16x16x32_bf16 v[28:31], v[202:205], v[4:7], v[110:113]
	s_waitcnt lgkmcnt(2)
	v_mfma_f32_16x16x32_bf16 v[118:121], v[206:209], v[8:11], v[28:31]
	v_mfma_f32_16x16x32_bf16 v[28:31], v[202:205], v[12:15], v[106:109]
	v_mfma_f32_16x16x32_bf16 v[86:89], v[206:209], v[146:149], v[28:31]
	s_waitcnt lgkmcnt(1)
	v_mfma_f32_16x16x32_bf16 v[28:31], v[210:213], v[4:7], v[102:105]
	s_waitcnt lgkmcnt(0)
	v_mfma_f32_16x16x32_bf16 v[114:117], v[218:221], v[8:11], v[28:31]
	v_mfma_f32_16x16x32_bf16 v[28:31], v[210:213], v[12:15], v[98:101]
	v_mfma_f32_16x16x32_bf16 v[82:85], v[218:221], v[146:149], v[28:31]
	s_setprio 0
	s_barrier
	ds_read_b128 v[222:225], v144
	ds_read_b128 v[242:245], v144 offset:1024
	ds_read_b128 v[246:249], v144 offset:2048
	ds_read_b128 v[250:253], v144 offset:3072
	s_waitcnt vmcnt(0)
	s_barrier
	s_waitcnt lgkmcnt(0)
	s_setprio 1
	s_waitcnt lgkmcnt(3)
	v_mfma_f32_16x16x32_bf16 v[28:31], v[16:19], v[222:225], v[226:229]
	s_waitcnt lgkmcnt(1)
	v_mfma_f32_16x16x32_bf16 v[16:19], v[16:19], v[246:249], v[186:189]
	v_mfma_f32_16x16x32_bf16 v[62:65], v[20:23], v[242:245], v[28:31]
	s_waitcnt lgkmcnt(0)
	v_mfma_f32_16x16x32_bf16 v[28:31], v[20:23], v[250:253], v[16:19]
	v_mfma_f32_16x16x32_bf16 v[16:19], v[24:27], v[222:225], v[190:193]
	v_mfma_f32_16x16x32_bf16 v[58:61], v[50:53], v[242:245], v[16:19]
	v_mfma_f32_16x16x32_bf16 v[16:19], v[24:27], v[246:249], v[194:197]
	v_mfma_f32_16x16x32_bf16 v[24:27], v[50:53], v[250:253], v[16:19]
	v_mfma_f32_16x16x32_bf16 v[16:19], v[202:205], v[222:225], v[78:81]
	v_mfma_f32_16x16x32_bf16 v[54:57], v[206:209], v[242:245], v[16:19]
	v_mfma_f32_16x16x32_bf16 v[16:19], v[202:205], v[246:249], v[74:77]
	v_mfma_f32_16x16x32_bf16 v[20:23], v[206:209], v[250:253], v[16:19]
	v_mfma_f32_16x16x32_bf16 v[16:19], v[210:213], v[222:225], v[70:73]
	v_mfma_f32_16x16x32_bf16 v[50:53], v[218:221], v[242:245], v[16:19]
	v_mfma_f32_16x16x32_bf16 v[16:19], v[210:213], v[246:249], v[66:69]
	v_mfma_f32_16x16x32_bf16 v[16:19], v[218:221], v[250:253], v[16:19]
	s_setprio 0
	s_barrier
	ds_read_b128 v[186:189], v143 offset:49152
	ds_read_b128 v[190:193], v143 offset:50176
	ds_read_b128 v[194:197], v142 offset:49152
	ds_read_b128 v[142:145], v142 offset:50176
	ds_read_b128 v[202:205], v141 offset:49152
	ds_read_b128 v[206:209], v141 offset:50176
	ds_read_b128 v[210:213], v140 offset:49152
	ds_read_b128 v[218:221], v140 offset:50176
	s_barrier
	s_waitcnt lgkmcnt(0)
	s_setprio 1
	s_waitcnt lgkmcnt(7)
	v_mfma_f32_16x16x32_bf16 v[66:69], v[186:189], v[4:7], v[214:217]
	s_waitcnt lgkmcnt(6)
	v_mfma_f32_16x16x32_bf16 v[110:113], v[190:193], v[8:11], v[66:69]
	v_mfma_f32_16x16x32_bf16 v[66:69], v[186:189], v[12:15], v[230:233]
	v_mfma_f32_16x16x32_bf16 v[78:81], v[190:193], v[146:149], v[66:69]
	s_waitcnt lgkmcnt(5)
	v_mfma_f32_16x16x32_bf16 v[66:69], v[194:197], v[4:7], v[234:237]
	s_waitcnt lgkmcnt(3)
	v_mfma_f32_16x16x32_bf16 v[46:49], v[202:205], v[4:7], v[46:49]
	s_waitcnt lgkmcnt(1)
	v_mfma_f32_16x16x32_bf16 v[4:7], v[210:213], v[4:7], v[38:41]
	v_mfma_f32_16x16x32_bf16 v[106:109], v[142:145], v[8:11], v[66:69]
	v_mfma_f32_16x16x32_bf16 v[66:69], v[194:197], v[12:15], v[238:241]
	v_mfma_f32_16x16x32_bf16 v[42:45], v[202:205], v[12:15], v[42:45]
	s_waitcnt lgkmcnt(0)
	v_mfma_f32_16x16x32_bf16 v[98:101], v[218:221], v[8:11], v[4:7]
	v_mfma_f32_16x16x32_bf16 v[4:7], v[210:213], v[12:15], v[34:37]
	v_mfma_f32_16x16x32_bf16 v[74:77], v[142:145], v[146:149], v[66:69]
	v_mfma_f32_16x16x32_bf16 v[102:105], v[206:209], v[8:11], v[46:49]
	v_mfma_f32_16x16x32_bf16 v[70:73], v[206:209], v[146:149], v[42:45]
	v_mfma_f32_16x16x32_bf16 v[66:69], v[218:221], v[146:149], v[4:7]
	s_setprio 0
	s_setprio 1
	v_mfma_f32_16x16x32_bf16 v[4:7], v[186:189], v[222:225], v[154:157]
	v_mfma_f32_16x16x32_bf16 v[46:49], v[190:193], v[242:245], v[4:7]
	v_mfma_f32_16x16x32_bf16 v[4:7], v[186:189], v[246:249], v[158:161]
	v_mfma_f32_16x16x32_bf16 v[12:15], v[190:193], v[250:253], v[4:7]
	v_mfma_f32_16x16x32_bf16 v[4:7], v[194:197], v[222:225], v[166:169]
	v_mfma_f32_16x16x32_bf16 v[42:45], v[142:145], v[242:245], v[4:7]
	v_mfma_f32_16x16x32_bf16 v[4:7], v[194:197], v[246:249], v[170:173]
	v_mfma_f32_16x16x32_bf16 v[8:11], v[142:145], v[250:253], v[4:7]
	v_mfma_f32_16x16x32_bf16 v[4:7], v[202:205], v[222:225], v[174:177]
	v_mfma_f32_16x16x32_bf16 v[38:41], v[206:209], v[242:245], v[4:7]
	v_mfma_f32_16x16x32_bf16 v[4:7], v[202:205], v[246:249], v[198:201]
	v_mfma_f32_16x16x32_bf16 v[34:37], v[210:213], v[222:225], v[150:153]
	v_mfma_f32_16x16x32_bf16 v[0:3], v[210:213], v[246:249], v[0:3]
	v_mfma_f32_16x16x32_bf16 v[4:7], v[206:209], v[250:253], v[4:7]
	v_mfma_f32_16x16x32_bf16 v[34:37], v[218:221], v[242:245], v[34:37]
	v_mfma_f32_16x16x32_bf16 v[0:3], v[218:221], v[250:253], v[0:3]
	s_setprio 0
	v_cmp_gt_u32_e32 vcc, s59, v130
	s_barrier
	s_and_saveexec_b64 s[10:11], vcc
	s_cbranch_execz .LBB0_1930
	s_barrier

; #define STAGE(P, BASE, br, kt) do { int _so = ((br) * K + (kt) * BK) * 2; \
;     __builtin_amdgcn_raw_ptr_buffer_load_lds(rs_##BASE, (__attribute__((address_space(3))) void*)((char*)(P) + tx * 16), 16, voff0, _so, 0, 0); \
;     __builtin_amdgcn_raw_ptr_buffer_load_lds(rs_##BASE, (__attribute__((address_space(3))) void*)((char*)(P) + tx * 16 + 8192), 16, voff1, _so, 0, 0); } while (0)
; #define LDA(dst, b, h) _Pragma("unroll") for (int m = 0; m < 4; ++m) _Pragma("unroll") for (int k = 0; k < 2; ++k) \
;     dst[m][k] = *reinterpret_cast<const bf16x8*>((char*)SA(b, h) + lds_byte(wr * 64 + m * 16 + fr, k * 32 + fq * 8))
; #define LDB(dst, b, h) _Pragma("unroll") for (int n = 0; n < 2; ++n) _Pragma("unroll") for (int k = 0; k < 2; ++k) \
;     dst[n][k] = *reinterpret_cast<const bf16x8*>((char*)SB(b, h) + lds_byte(wc * 32 + n * 16 + fr, k * 32 + fq * 8))
; #define MMA(ai, bj, At, Bt_) do { __builtin_amdgcn_s_setprio(1); \
;     _Pragma("unroll") for (int m = 0; m < 4; ++m) _Pragma("unroll") for (int n = 0; n < 2; ++n) _Pragma("unroll") for (int k = 0; k < 2; ++k) \
;       acc[ai][bj][m][n] = __builtin_amdgcn_mfma_f32_16x16x32_bf16(At[m][k], Bt_[n][k], acc[ai][bj][m][n], 0, 0, 0); \
;     __builtin_amdgcn_s_setprio(0); } while (0)
; #define WAIT_V(n) asm volatile("s_waitcnt vmcnt(" #n ")" ::: "memory")
; #define WAIT_L(n) asm volatile("s_waitcnt lgkmcnt(" #n ")" ::: "memory")
; #define BAR __builtin_amdgcn_s_barrier()
; template <class Epi> ...
;     ...
;   { LDB(B0, 0, 0); LDA(At, 0, 0); STAGE(SA(1, 1), A, brow + HALF, nt - 1);
;     BAR; WAIT_L(0); MMA(0, 0, At, B0); BAR;
;     LDB(B1, 0, 1); BAR; WAIT_L(0); MMA(0, 1, At, B1); BAR;
;     LDA(At, 0, 1); WAIT_V(4); BAR; WAIT_L(0); MMA(1, 0, At, B0); MMA(1, 1, At, B1); BAR; }
.Lpx5:
	s_or_b32 s16, s17, 0x40780
	v_readfirstlane_b32 s17, v152
	s_mov_b32 s10, s78
	s_mov_b32 s11, s79
	s_mov_b32 m0, s17
	v_readfirstlane_b32 s17, v151
	ds_read_b128 v[156:159], v155
	ds_read_b128 v[166:169], v155 offset:1024
	ds_read_b128 v[170:173], v155 offset:2048
	ds_read_b128 v[174:177], v155 offset:3072
	ds_read_b128 v[186:189], v143
	ds_read_b128 v[190:193], v143 offset:1024
	ds_read_b128 v[194:197], v142
	ds_read_b128 v[198:201], v142 offset:1024
	ds_read_b128 v[202:205], v141
	ds_read_b128 v[206:209], v141 offset:1024
	ds_read_b128 v[210:213], v140
	ds_read_b128 v[214:217], v140 offset:1024
	buffer_load_dwordx4 v32, s[8:11], s16 offen lds
	s_mov_b32 m0, s17
	s_nop 0
	buffer_load_dwordx4 v131, s[8:11], s16 offen lds
	s_barrier
	s_waitcnt lgkmcnt(0)
	s_setprio 1
	s_waitcnt lgkmcnt(7)
	v_mfma_f32_16x16x32_bf16 v[126:129], v[186:189], v[156:159], v[126:129]
	v_mfma_f32_16x16x32_bf16 v[122:125], v[186:189], v[170:173], v[122:125]
	s_waitcnt lgkmcnt(5)
	v_mfma_f32_16x16x32_bf16 v[118:121], v[194:197], v[156:159], v[118:121]
	v_mfma_f32_16x16x32_bf16 v[114:117], v[194:197], v[170:173], v[114:117]
	v_mfma_f32_16x16x32_bf16 v[126:129], v[190:193], v[166:169], v[126:129]
	v_mfma_f32_16x16x32_bf16 v[122:125], v[190:193], v[174:177], v[122:125]
	s_waitcnt lgkmcnt(4)
	v_mfma_f32_16x16x32_bf16 v[118:121], v[198:201], v[166:169], v[118:121]
	v_mfma_f32_16x16x32_bf16 v[114:117], v[198:201], v[174:177], v[114:117]
	s_waitcnt lgkmcnt(3)
	v_mfma_f32_16x16x32_bf16 v[110:113], v[202:205], v[156:159], v[110:113]
	v_mfma_f32_16x16x32_bf16 v[106:109], v[202:205], v[170:173], v[106:109]
	s_waitcnt lgkmcnt(1)
	v_mfma_f32_16x16x32_bf16 v[102:105], v[210:213], v[156:159], v[102:105]
	v_mfma_f32_16x16x32_bf16 v[98:101], v[210:213], v[170:173], v[98:101]
	v_mfma_f32_16x16x32_bf16 v[150:153], v[206:209], v[166:169], v[110:113]
	v_mfma_f32_16x16x32_bf16 v[218:221], v[206:209], v[174:177], v[106:109]
	s_waitcnt lgkmcnt(0)
	v_mfma_f32_16x16x32_bf16 v[222:225], v[214:217], v[166:169], v[102:105]
	v_mfma_f32_16x16x32_bf16 v[226:229], v[214:217], v[174:177], v[98:101]
	s_setprio 0
	s_barrier
	s_nop 0
	ds_read_b128 v[98:101], v149
	ds_read_b128 v[102:105], v149 offset:1024
	ds_read_b128 v[106:109], v149 offset:2048
	ds_read_b128 v[110:113], v149 offset:3072
	s_barrier
	s_waitcnt lgkmcnt(0)
	s_setprio 1
	s_waitcnt lgkmcnt(3)
	v_mfma_f32_16x16x32_bf16 v[94:97], v[186:189], v[98:101], v[94:97]
	s_waitcnt lgkmcnt(1)
	v_mfma_f32_16x16x32_bf16 v[90:93], v[186:189], v[106:109], v[90:93]
	v_mfma_f32_16x16x32_bf16 v[86:89], v[194:197], v[98:101], v[86:89]
	v_mfma_f32_16x16x32_bf16 v[82:85], v[194:197], v[106:109], v[82:85]
	v_mfma_f32_16x16x32_bf16 v[94:97], v[190:193], v[102:105], v[94:97]
	s_waitcnt lgkmcnt(0)
	v_mfma_f32_16x16x32_bf16 v[90:93], v[190:193], v[110:113], v[90:93]
	v_mfma_f32_16x16x32_bf16 v[86:89], v[198:201], v[102:105], v[86:89]
	v_mfma_f32_16x16x32_bf16 v[82:85], v[198:201], v[110:113], v[82:85]
	v_mfma_f32_16x16x32_bf16 v[78:81], v[202:205], v[98:101], v[78:81]
	v_mfma_f32_16x16x32_bf16 v[74:77], v[202:205], v[106:109], v[74:77]
	v_mfma_f32_16x16x32_bf16 v[70:73], v[210:213], v[98:101], v[70:73]
	v_mfma_f32_16x16x32_bf16 v[66:69], v[210:213], v[106:109], v[66:69]
	v_mfma_f32_16x16x32_bf16 v[146:149], v[206:209], v[102:105], v[78:81]
	v_mfma_f32_16x16x32_bf16 v[186:189], v[206:209], v[110:113], v[74:77]
	v_mfma_f32_16x16x32_bf16 v[190:193], v[214:217], v[102:105], v[70:73]
	v_mfma_f32_16x16x32_bf16 v[194:197], v[214:217], v[110:113], v[66:69]
	s_setprio 0
	s_barrier
	s_nop 1
	ds_read_b128 v[66:69], v143 offset:16384
	ds_read_b128 v[70:73], v143 offset:17408
	ds_read_b128 v[74:77], v142 offset:16384
	ds_read_b128 v[78:81], v142 offset:17408
	ds_read_b128 v[198:201], v141 offset:16384
	ds_read_b128 v[202:205], v141 offset:17408
	ds_read_b128 v[206:209], v140 offset:16384
	ds_read_b128 v[210:213], v140 offset:17408
	s_waitcnt vmcnt(4)
	s_barrier
	s_waitcnt lgkmcnt(0)
	s_setprio 1
	s_waitcnt lgkmcnt(7)
	v_mfma_f32_16x16x32_bf16 v[62:65], v[66:69], v[156:159], v[62:65]
	v_mfma_f32_16x16x32_bf16 v[58:61], v[66:69], v[170:173], v[58:61]
	s_waitcnt lgkmcnt(5)
	v_mfma_f32_16x16x32_bf16 v[54:57], v[74:77], v[156:159], v[54:57]
	v_mfma_f32_16x16x32_bf16 v[50:53], v[74:77], v[170:173], v[50:53]
	v_mfma_f32_16x16x32_bf16 v[62:65], v[70:73], v[166:169], v[62:65]
	v_mfma_f32_16x16x32_bf16 v[58:61], v[70:73], v[174:177], v[58:61]
	s_waitcnt lgkmcnt(4)
	v_mfma_f32_16x16x32_bf16 v[54:57], v[78:81], v[166:169], v[54:57]
	v_mfma_f32_16x16x32_bf16 v[50:53], v[78:81], v[174:177], v[50:53]
	s_waitcnt lgkmcnt(3)
	v_mfma_f32_16x16x32_bf16 v[46:49], v[198:201], v[156:159], v[46:49]
	v_mfma_f32_16x16x32_bf16 v[42:45], v[198:201], v[170:173], v[42:45]
	s_waitcnt lgkmcnt(1)
	v_mfma_f32_16x16x32_bf16 v[38:41], v[206:209], v[156:159], v[38:41]
	v_mfma_f32_16x16x32_bf16 v[34:37], v[206:209], v[170:173], v[34:37]
	v_mfma_f32_16x16x32_bf16 v[214:217], v[202:205], v[166:169], v[46:49]
	v_mfma_f32_16x16x32_bf16 v[230:233], v[202:205], v[174:177], v[42:45]
	s_waitcnt lgkmcnt(0)
	v_mfma_f32_16x16x32_bf16 v[154:157], v[210:213], v[166:169], v[38:41]
	v_mfma_f32_16x16x32_bf16 v[158:161], v[210:213], v[174:177], v[34:37]
	s_setprio 0
	s_setprio 1
	v_mfma_f32_16x16x32_bf16 v[28:31], v[66:69], v[98:101], v[28:31]
	v_mfma_f32_16x16x32_bf16 v[24:27], v[66:69], v[106:109], v[24:27]
	v_mfma_f32_16x16x32_bf16 v[20:23], v[74:77], v[98:101], v[20:23]
	v_mfma_f32_16x16x32_bf16 v[16:19], v[74:77], v[106:109], v[16:19]
	v_mfma_f32_16x16x32_bf16 v[28:31], v[70:73], v[102:105], v[28:31]
	v_mfma_f32_16x16x32_bf16 v[24:27], v[70:73], v[110:113], v[24:27]
	v_mfma_f32_16x16x32_bf16 v[20:23], v[78:81], v[102:105], v[20:23]
	v_mfma_f32_16x16x32_bf16 v[16:19], v[78:81], v[110:113], v[16:19]
	v_mfma_f32_16x16x32_bf16 v[12:15], v[198:201], v[98:101], v[12:15]
	v_mfma_f32_16x16x32_bf16 v[8:11], v[198:201], v[106:109], v[8:11]
	v_mfma_f32_16x16x32_bf16 v[4:7], v[206:209], v[98:101], v[4:7]
	v_mfma_f32_16x16x32_bf16 v[0:3], v[206:209], v[106:109], v[0:3]
	v_mfma_f32_16x16x32_bf16 v[166:169], v[202:205], v[102:105], v[12:15]
	v_mfma_f32_16x16x32_bf16 v[170:173], v[202:205], v[110:113], v[8:11]
	v_mfma_f32_16x16x32_bf16 v[174:177], v[210:213], v[102:105], v[4:7]
	v_mfma_f32_16x16x32_bf16 v[198:201], v[210:213], v[110:113], v[0:3]
	s_setprio 0
	s_barrier
; #define LDA(dst, b, h) _Pragma("unroll") for (int m = 0; m < 4; ++m) _Pragma("unroll") for (int k = 0; k < 2; ++k) \
;     dst[m][k] = *reinterpret_cast<const bf16x8*>((char*)SA(b, h) + lds_byte(wr * 64 + m * 16 + fr, k * 32 + fq * 8))
; #define LDB(dst, b, h) _Pragma("unroll") for (int n = 0; n < 2; ++n) _Pragma("unroll") for (int k = 0; k < 2; ++k) \
;     dst[n][k] = *reinterpret_cast<const bf16x8*>((char*)SB(b, h) + lds_byte(wc * 32 + n * 16 + fr, k * 32 + fq * 8))
; #define MMA(ai, bj, At, Bt_) do { __builtin_amdgcn_s_setprio(1); \
;     _Pragma("unroll") for (int m = 0; m < 4; ++m) _Pragma("unroll") for (int n = 0; n < 2; ++n) _Pragma("unroll") for (int k = 0; k < 2; ++k) \
;       acc[ai][bj][m][n] = __builtin_amdgcn_mfma_f32_16x16x32_bf16(At[m][k], Bt_[n][k], acc[ai][bj][m][n], 0, 0, 0); \
;     __builtin_amdgcn_s_setprio(0); } while (0)
; #define WAIT_V(n) asm volatile("s_waitcnt vmcnt(" #n ")" ::: "memory")
; #define WAIT_L(n) asm volatile("s_waitcnt lgkmcnt(" #n ")" ::: "memory")
; #define BAR __builtin_amdgcn_s_barrier()
; template <class Epi> ...
;     ...
;   { LDB(B0, 1, 0); LDA(At, 1, 0); WAIT_V(2); BAR; WAIT_L(0); MMA(0, 0, At, B0); BAR;
;     LDB(B1, 1, 1); WAIT_V(0); BAR; WAIT_L(0); MMA(0, 1, At, B1); BAR;
;     LDA(At, 1, 1); BAR; WAIT_L(0); MMA(1, 0, At, B0); MMA(1, 1, At, B1); BAR; }
;   if (wr == 0) BAR;
	ds_read_b128 v[202:205], v145
	ds_read_b128 v[206:209], v145 offset:1024
	ds_read_b128 v[210:213], v145 offset:2048
	ds_read_b128 v[234:237], v145 offset:3072
	ds_read_b128 v[0:3], v143 offset:32768
	ds_read_b128 v[4:7], v143 offset:33792
	ds_read_b128 v[8:11], v142 offset:32768
	ds_read_b128 v[34:37], v142 offset:33792
	ds_read_b128 v[238:241], v141 offset:32768
	ds_read_b128 v[242:245], v141 offset:33792
	ds_read_b128 v[246:249], v140 offset:32768
	ds_read_b128 v[250:253], v140 offset:33792
	s_waitcnt vmcnt(2)
	s_barrier
	s_waitcnt lgkmcnt(0)
	s_setprio 1
	s_waitcnt lgkmcnt(7)
	v_mfma_f32_16x16x32_bf16 v[12:15], v[0:3], v[202:205], v[126:129]
	s_waitcnt lgkmcnt(6)
	v_mfma_f32_16x16x32_bf16 v[110:113], v[4:7], v[206:209], v[12:15]
	v_mfma_f32_16x16x32_bf16 v[12:15], v[0:3], v[210:213], v[122:125]
	v_mfma_f32_16x16x32_bf16 v[78:81], v[4:7], v[234:237], v[12:15]
	s_waitcnt lgkmcnt(5)
	v_mfma_f32_16x16x32_bf16 v[12:15], v[8:11], v[202:205], v[118:121]
	s_waitcnt lgkmcnt(4)
	v_mfma_f32_16x16x32_bf16 v[106:109], v[34:37], v[206:209], v[12:15]
	v_mfma_f32_16x16x32_bf16 v[12:15], v[8:11], v[210:213], v[114:117]
	v_mfma_f32_16x16x32_bf16 v[74:77], v[34:37], v[234:237], v[12:15]
	s_waitcnt lgkmcnt(3)
	v_mfma_f32_16x16x32_bf16 v[12:15], v[238:241], v[202:205], v[150:153]
	s_waitcnt lgkmcnt(2)
	v_mfma_f32_16x16x32_bf16 v[102:105], v[242:245], v[206:209], v[12:15]
	v_mfma_f32_16x16x32_bf16 v[12:15], v[238:241], v[210:213], v[218:221]
	v_mfma_f32_16x16x32_bf16 v[70:73], v[242:245], v[234:237], v[12:15]
	s_waitcnt lgkmcnt(1)
	v_mfma_f32_16x16x32_bf16 v[12:15], v[246:249], v[202:205], v[222:225]
	s_waitcnt lgkmcnt(0)
	v_mfma_f32_16x16x32_bf16 v[98:101], v[250:253], v[206:209], v[12:15]
	v_mfma_f32_16x16x32_bf16 v[12:15], v[246:249], v[210:213], v[226:229]
	v_mfma_f32_16x16x32_bf16 v[66:69], v[250:253], v[234:237], v[12:15]
	s_setprio 0
	s_barrier
	ds_read_b128 v[150:153], v144
	ds_read_b128 v[218:221], v144 offset:1024
	ds_read_b128 v[222:225], v144 offset:2048
	ds_read_b128 v[226:229], v144 offset:3072
	s_waitcnt vmcnt(0)
	s_barrier
	s_waitcnt lgkmcnt(0)
	s_setprio 1
	s_waitcnt lgkmcnt(3)
	v_mfma_f32_16x16x32_bf16 v[12:15], v[0:3], v[150:153], v[94:97]
	s_waitcnt lgkmcnt(1)
	v_mfma_f32_16x16x32_bf16 v[0:3], v[0:3], v[222:225], v[90:93]
	v_mfma_f32_16x16x32_bf16 v[46:49], v[4:7], v[218:221], v[12:15]
	s_waitcnt lgkmcnt(0)
	v_mfma_f32_16x16x32_bf16 v[12:15], v[4:7], v[226:229], v[0:3]
	v_mfma_f32_16x16x32_bf16 v[0:3], v[8:11], v[150:153], v[86:89]
	v_mfma_f32_16x16x32_bf16 v[42:45], v[34:37], v[218:221], v[0:3]
	v_mfma_f32_16x16x32_bf16 v[0:3], v[8:11], v[222:225], v[82:85]
	v_mfma_f32_16x16x32_bf16 v[8:11], v[34:37], v[226:229], v[0:3]
	v_mfma_f32_16x16x32_bf16 v[0:3], v[238:241], v[150:153], v[146:149]
	v_mfma_f32_16x16x32_bf16 v[38:41], v[242:245], v[218:221], v[0:3]
	v_mfma_f32_16x16x32_bf16 v[0:3], v[238:241], v[222:225], v[186:189]
	v_mfma_f32_16x16x32_bf16 v[4:7], v[242:245], v[226:229], v[0:3]
	v_mfma_f32_16x16x32_bf16 v[0:3], v[246:249], v[150:153], v[190:193]
	v_mfma_f32_16x16x32_bf16 v[34:37], v[250:253], v[218:221], v[0:3]
	v_mfma_f32_16x16x32_bf16 v[0:3], v[246:249], v[222:225], v[194:197]
	v_mfma_f32_16x16x32_bf16 v[0:3], v[250:253], v[226:229], v[0:3]
	s_setprio 0
	s_barrier
	ds_read_b128 v[144:147], v143 offset:49152
	ds_read_b128 v[186:189], v143 offset:50176
	ds_read_b128 v[190:193], v142 offset:49152
	ds_read_b128 v[194:197], v142 offset:50176
	ds_read_b128 v[238:241], v141 offset:49152
	ds_read_b128 v[242:245], v141 offset:50176
	ds_read_b128 v[246:249], v140 offset:49152
	ds_read_b128 v[140:143], v140 offset:50176
	s_barrier
	s_waitcnt lgkmcnt(0)
	s_setprio 1
	s_waitcnt lgkmcnt(5)
	v_mfma_f32_16x16x32_bf16 v[50:53], v[190:193], v[210:213], v[50:53]
	s_waitcnt lgkmcnt(4)
	v_mfma_f32_16x16x32_bf16 v[90:93], v[194:197], v[234:237], v[50:53]
	s_waitcnt lgkmcnt(3)
	v_mfma_f32_16x16x32_bf16 v[50:53], v[238:241], v[202:205], v[214:217]
	s_waitcnt lgkmcnt(2)
	v_mfma_f32_16x16x32_bf16 v[118:121], v[242:245], v[206:209], v[50:53]
	v_mfma_f32_16x16x32_bf16 v[50:53], v[238:241], v[210:213], v[230:233]
	v_mfma_f32_16x16x32_bf16 v[86:89], v[242:245], v[234:237], v[50:53]
	s_waitcnt lgkmcnt(1)
	v_mfma_f32_16x16x32_bf16 v[50:53], v[246:249], v[202:205], v[154:157]
	v_mfma_f32_16x16x32_bf16 v[62:65], v[144:147], v[202:205], v[62:65]
	v_mfma_f32_16x16x32_bf16 v[58:61], v[144:147], v[210:213], v[58:61]
	v_mfma_f32_16x16x32_bf16 v[54:57], v[190:193], v[202:205], v[54:57]
	s_waitcnt lgkmcnt(0)
	v_mfma_f32_16x16x32_bf16 v[114:117], v[140:143], v[206:209], v[50:53]
	v_mfma_f32_16x16x32_bf16 v[50:53], v[246:249], v[210:213], v[158:161]
	v_mfma_f32_16x16x32_bf16 v[126:129], v[186:189], v[206:209], v[62:65]
	v_mfma_f32_16x16x32_bf16 v[94:97], v[186:189], v[234:237], v[58:61]
	v_mfma_f32_16x16x32_bf16 v[122:125], v[194:197], v[206:209], v[54:57]
	v_mfma_f32_16x16x32_bf16 v[82:85], v[140:143], v[234:237], v[50:53]
	s_setprio 0
	s_setprio 1
	v_mfma_f32_16x16x32_bf16 v[28:31], v[144:147], v[150:153], v[28:31]
	v_mfma_f32_16x16x32_bf16 v[24:27], v[144:147], v[222:225], v[24:27]
	v_mfma_f32_16x16x32_bf16 v[16:19], v[190:193], v[222:225], v[16:19]
	v_mfma_f32_16x16x32_bf16 v[62:65], v[186:189], v[218:221], v[28:31]
	v_mfma_f32_16x16x32_bf16 v[28:31], v[186:189], v[226:229], v[24:27]
	v_mfma_f32_16x16x32_bf16 v[24:27], v[194:197], v[226:229], v[16:19]
	v_mfma_f32_16x16x32_bf16 v[16:19], v[238:241], v[150:153], v[166:169]
	v_mfma_f32_16x16x32_bf16 v[20:23], v[190:193], v[150:153], v[20:23]
	v_mfma_f32_16x16x32_bf16 v[54:57], v[242:245], v[218:221], v[16:19]
	v_mfma_f32_16x16x32_bf16 v[16:19], v[238:241], v[222:225], v[170:173]
	v_mfma_f32_16x16x32_bf16 v[58:61], v[194:197], v[218:221], v[20:23]
	v_mfma_f32_16x16x32_bf16 v[20:23], v[242:245], v[226:229], v[16:19]
	v_mfma_f32_16x16x32_bf16 v[16:19], v[246:249], v[150:153], v[174:177]
	v_mfma_f32_16x16x32_bf16 v[50:53], v[140:143], v[218:221], v[16:19]
	v_mfma_f32_16x16x32_bf16 v[16:19], v[246:249], v[222:225], v[198:201]
	v_mfma_f32_16x16x32_bf16 v[16:19], v[140:143], v[226:229], v[16:19]
	s_setprio 0
	v_cmp_gt_u32_e32 vcc, s59, v130
	s_barrier
	s_and_saveexec_b64 s[10:11], vcc
	s_cbranch_execz .LBB0_2021
	s_barrier

; #define STAGE(P, BASE, br, kt) do { int _so = ((br) * K + (kt) * BK) * 2; \
;     __builtin_amdgcn_raw_ptr_buffer_load_lds(rs_##BASE, (__attribute__((address_space(3))) void*)((char*)(P) + tx * 16), 16, voff0, _so, 0, 0); \
;     __builtin_amdgcn_raw_ptr_buffer_load_lds(rs_##BASE, (__attribute__((address_space(3))) void*)((char*)(P) + tx * 16 + 8192), 16, voff1, _so, 0, 0); } while (0)
; #define WAIT_V(n) asm volatile("s_waitcnt vmcnt(" #n ")" ::: "memory")
; #define BAR __builtin_amdgcn_s_barrier()
; template <class Epi> ...
;     ...
;   { int _r, _c; stage_rc(tx * 16, _r, _c); voff0 = (_r * K + _c) * 2; stage_rc(tx * 16 + 8192, _r, _c); voff1 = (_r * K + _c) * 2; }
;   __amdgpu_buffer_rsrc_t rs_A = __builtin_amdgcn_make_buffer_rsrc((void*)A, 0, 0x7fffffff, 0x00020000);
;   __amdgpu_buffer_rsrc_t rs_Bt = __builtin_amdgcn_make_buffer_rsrc((void*)Bt, 0, 0x7fffffff, 0x00020000);
;   if (!pre) {
;     STAGE(SB(0, 0), Bt, bcol, 0); STAGE(SA(0, 0), A, brow, 0);
;     STAGE(SB(0, 1), Bt, bcol + HALF, 0); STAGE(SA(0, 1), A, brow + HALF, 0);
;   }
;   if (wr == 1) BAR;
;   if (pre) { WAIT_V(0); } else { WAIT_V(4); }
;   BAR;
;   STAGE(SB(1, 0), Bt, bcol, 1); STAGE(SA(1, 0), A, brow, 1); STAGE(SB(1, 1), Bt, bcol + HALF, 1);
;   WAIT_V(6); BAR;
.LBB0_2252:
	v_readlane_b32 s25, v254, 30
	s_lshl_b32 s16, s19, 11
	s_or_b32 s10, s16, 0x80
	v_add_u32_e32 v146, s25, v0
	v_add_u32_e32 v147, 0x2000, v146
	v_readfirstlane_b32 s11, v146
	s_mov_b32 m0, s11
	v_readfirstlane_b32 s11, v147
	v_add_u32_e32 v148, 0x8000, v136
	s_barrier
	buffer_load_dwordx4 v32, s[76:79], s10 offen lds
	s_mov_b32 m0, s11
	s_lshl_b32 s17, s20, 11
	v_readfirstlane_b32 s24, v148
	v_add_u32_e32 v150, 0xa000, v136
	v_readlane_b32 s26, v254, 31
	buffer_load_dwordx4 v131, s[76:79], s10 offen lds
	s_or_b32 s23, s17, 0x80
	s_mov_b32 s10, s78
	s_mov_b32 s11, s79
	s_mov_b32 m0, s24
	v_readfirstlane_b32 s24, v150
	v_add_u32_e32 v153, s26, v0
	buffer_load_dwordx4 v32, s[8:11], s23 offen lds
	s_mov_b32 m0, s24
	v_readfirstlane_b32 s24, v153
	v_add_u32_e32 v154, 0x2000, v153
	buffer_load_dwordx4 v131, s[8:11], s23 offen lds
	s_add_i32 s23, s16, 0x40080
	s_mov_b32 m0, s24
	v_readfirstlane_b32 s24, v154
	buffer_load_dwordx4 v32, s[76:79], s23 offen lds
	s_mov_b32 m0, s24
	v_and_b32_e32 v2, 15, v130
	buffer_load_dwordx4 v131, s[76:79], s23 offen lds
	v_lshlrev_b32_e32 v0, 6, v2
	v_lshlrev_b32_e32 v2, 2, v130
	v_and_b32_e32 v3, 48, v130
	v_and_b32_e32 v2, 32, v2
	v_bitop3_b32 v0, v0, v2, v3 bitop3:0x36
	s_waitcnt vmcnt(11)
	v_lshlrev_b32_e32 v8, 6, v130
	s_movk_i32 s23, 0x3c0
	s_waitcnt vmcnt(6)
	v_add_u32_e32 v4, s71, v0
	v_add_u32_e32 v5, s73, v0
	v_add_u32_e32 v6, s25, v0
	v_add_u32_e32 v7, s26, v0
	v_lshlrev_b32_e32 v1, 13, v1
	v_add_u32_e32 v10, 0, v0
	v_and_or_b32 v0, v8, s23, v3
	v_and_b32_e32 v9, 0x3000, v8
	v_xad_u32 v2, v0, v2, 0
	v_or_b32_e32 v3, 0x800, v1
	v_or_b32_e32 v8, 0x1000, v1
	v_or_b32_e32 v11, 0x1800, v1
	v_add_u32_e32 v152, 0xc000, v136
	v_add_u32_e32 v151, 0xe000, v136
	v_add_u32_e32 v139, 0x2000, v137
	v_add_u32_e32 v138, 0x2000, v134
	s_mov_b32 s23, -2
	s_mov_b32 s24, 0
	v_add_u32_e32 v155, v4, v9
	v_add_u32_e32 v143, v10, v1
	v_add_u32_e32 v142, v2, v3
	v_add_u32_e32 v141, v2, v8
	v_add_u32_e32 v140, v2, v11
	v_add_u32_e32 v149, v5, v9
	v_add_u32_e32 v145, v6, v9
	v_add_u32_e32 v144, v7, v9
	s_waitcnt vmcnt(10)
	s_barrier

; #define STAGE(P, BASE, br, kt) do { int _so = ((br) * K + (kt) * BK) * 2; \
;     __builtin_amdgcn_raw_ptr_buffer_load_lds(rs_##BASE, (__attribute__((address_space(3))) void*)((char*)(P) + tx * 16), 16, voff0, _so, 0, 0); \
;     __builtin_amdgcn_raw_ptr_buffer_load_lds(rs_##BASE, (__attribute__((address_space(3))) void*)((char*)(P) + tx * 16 + 8192), 16, voff1, _so, 0, 0); } while (0)
; #define LDA(dst, b, h) _Pragma("unroll") for (int m = 0; m < 4; ++m) _Pragma("unroll") for (int k = 0; k < 2; ++k) \
;     dst[m][k] = *reinterpret_cast<const bf16x8*>((char*)SA(b, h) + lds_byte(wr * 64 + m * 16 + fr, k * 32 + fq * 8))
; #define LDB(dst, b, h) _Pragma("unroll") for (int n = 0; n < 2; ++n) _Pragma("unroll") for (int k = 0; k < 2; ++k) \
;     dst[n][k] = *reinterpret_cast<const bf16x8*>((char*)SB(b, h) + lds_byte(wc * 32 + n * 16 + fr, k * 32 + fq * 8))
; #define MMA(ai, bj, At, Bt_) do { __builtin_amdgcn_s_setprio(1); \
;     _Pragma("unroll") for (int m = 0; m < 4; ++m) _Pragma("unroll") for (int n = 0; n < 2; ++n) _Pragma("unroll") for (int k = 0; k < 2; ++k) \
;       acc[ai][bj][m][n] = __builtin_amdgcn_mfma_f32_16x16x32_bf16(At[m][k], Bt_[n][k], acc[ai][bj][m][n], 0, 0, 0); \
;     __builtin_amdgcn_s_setprio(0); } while (0)
; #define WAIT_V(n) asm volatile("s_waitcnt vmcnt(" #n ")" ::: "memory")
; #define WAIT_L(n) asm volatile("s_waitcnt lgkmcnt(" #n ")" ::: "memory")
; #define BAR __builtin_amdgcn_s_barrier()
; template <class Epi> ...
;     ...
;   { LDB(B0, 0, 0); LDA(At, 0, 0); STAGE(SA(1, 1), A, brow + HALF, nt - 1);
;     BAR; WAIT_L(0); MMA(0, 0, At, B0); BAR;
;     LDB(B1, 0, 1); BAR; WAIT_L(0); MMA(0, 1, At, B1); BAR;
;     LDA(At, 0, 1); WAIT_V(4); BAR; WAIT_L(0); MMA(1, 0, At, B0); MMA(1, 1, At, B1); BAR; }
.Lpx7:
	s_or_b32 s16, s17, 0x40780
	v_readfirstlane_b32 s17, v152
	s_mov_b32 s10, s78
	s_mov_b32 s11, s79
	s_mov_b32 m0, s17
	v_readfirstlane_b32 s17, v151
	ds_read_b128 v[156:159], v155
	ds_read_b128 v[166:169], v155 offset:1024
	ds_read_b128 v[170:173], v155 offset:2048
	ds_read_b128 v[174:177], v155 offset:3072
	ds_read_b128 v[186:189], v143
	ds_read_b128 v[190:193], v143 offset:1024
	ds_read_b128 v[194:197], v142
	ds_read_b128 v[198:201], v142 offset:1024
	ds_read_b128 v[202:205], v141
	ds_read_b128 v[206:209], v141 offset:1024
	ds_read_b128 v[210:213], v140
	ds_read_b128 v[214:217], v140 offset:1024
	buffer_load_dwordx4 v32, s[8:11], s16 offen lds
	s_mov_b32 m0, s17
	s_nop 0
	buffer_load_dwordx4 v131, s[8:11], s16 offen lds
	s_barrier
	s_waitcnt lgkmcnt(0)
	s_setprio 1
	s_waitcnt lgkmcnt(7)
	v_mfma_f32_16x16x32_bf16 v[126:129], v[186:189], v[156:159], v[126:129]
	s_waitcnt lgkmcnt(5)
	v_mfma_f32_16x16x32_bf16 v[118:121], v[194:197], v[156:159], v[118:121]
	s_waitcnt lgkmcnt(3)
	v_mfma_f32_16x16x32_bf16 v[110:113], v[202:205], v[156:159], v[110:113]
	v_mfma_f32_16x16x32_bf16 v[106:109], v[202:205], v[170:173], v[106:109]
	s_waitcnt lgkmcnt(1)
	v_mfma_f32_16x16x32_bf16 v[102:105], v[210:213], v[156:159], v[102:105]
	v_mfma_f32_16x16x32_bf16 v[126:129], v[190:193], v[166:169], v[126:129]
	v_mfma_f32_16x16x32_bf16 v[122:125], v[186:189], v[170:173], v[122:125]
	v_mfma_f32_16x16x32_bf16 v[118:121], v[198:201], v[166:169], v[118:121]
	v_mfma_f32_16x16x32_bf16 v[114:117], v[194:197], v[170:173], v[114:117]
	v_mfma_f32_16x16x32_bf16 v[110:113], v[206:209], v[166:169], v[110:113]
	v_mfma_f32_16x16x32_bf16 v[106:109], v[206:209], v[174:177], v[106:109]
	s_waitcnt lgkmcnt(0)
	v_mfma_f32_16x16x32_bf16 v[102:105], v[214:217], v[166:169], v[102:105]
	v_mfma_f32_16x16x32_bf16 v[98:101], v[210:213], v[170:173], v[98:101]
	v_mfma_f32_16x16x32_bf16 v[150:153], v[190:193], v[174:177], v[122:125]
	v_mfma_f32_16x16x32_bf16 v[218:221], v[198:201], v[174:177], v[114:117]
	v_mfma_f32_16x16x32_bf16 v[222:225], v[214:217], v[174:177], v[98:101]
	s_setprio 0
	s_barrier
	s_nop 2
	ds_read_b128 v[98:101], v149
	ds_read_b128 v[114:117], v149 offset:1024
	ds_read_b128 v[122:125], v149 offset:2048
	ds_read_b128 v[146:149], v149 offset:3072
	s_barrier
	s_waitcnt lgkmcnt(0)
	s_setprio 1
	s_waitcnt lgkmcnt(3)
	v_mfma_f32_16x16x32_bf16 v[94:97], v[186:189], v[98:101], v[94:97]
	s_waitcnt lgkmcnt(1)
	v_mfma_f32_16x16x32_bf16 v[82:85], v[194:197], v[122:125], v[82:85]
	v_mfma_f32_16x16x32_bf16 v[78:81], v[202:205], v[98:101], v[78:81]
	v_mfma_f32_16x16x32_bf16 v[70:73], v[210:213], v[98:101], v[70:73]
	v_mfma_f32_16x16x32_bf16 v[94:97], v[190:193], v[114:117], v[94:97]
	v_mfma_f32_16x16x32_bf16 v[90:93], v[186:189], v[122:125], v[90:93]
	v_mfma_f32_16x16x32_bf16 v[86:89], v[194:197], v[98:101], v[86:89]
	s_waitcnt lgkmcnt(0)
	v_mfma_f32_16x16x32_bf16 v[82:85], v[198:201], v[146:149], v[82:85]
	v_mfma_f32_16x16x32_bf16 v[78:81], v[206:209], v[114:117], v[78:81]
	v_mfma_f32_16x16x32_bf16 v[74:77], v[202:205], v[122:125], v[74:77]
	v_mfma_f32_16x16x32_bf16 v[70:73], v[214:217], v[114:117], v[70:73]
	v_mfma_f32_16x16x32_bf16 v[66:69], v[210:213], v[122:125], v[66:69]
	v_mfma_f32_16x16x32_bf16 v[186:189], v[190:193], v[146:149], v[90:93]
	v_mfma_f32_16x16x32_bf16 v[190:193], v[198:201], v[114:117], v[86:89]
	v_mfma_f32_16x16x32_bf16 v[194:197], v[206:209], v[146:149], v[74:77]
	v_mfma_f32_16x16x32_bf16 v[198:201], v[214:217], v[146:149], v[66:69]
	s_setprio 0
	s_barrier
	s_nop 1
	ds_read_b128 v[66:69], v143 offset:16384
	ds_read_b128 v[74:77], v143 offset:17408
	ds_read_b128 v[86:89], v142 offset:16384
	ds_read_b128 v[90:93], v142 offset:17408
	ds_read_b128 v[202:205], v141 offset:16384
	ds_read_b128 v[206:209], v141 offset:17408
	ds_read_b128 v[210:213], v140 offset:16384
	ds_read_b128 v[214:217], v140 offset:17408
	s_waitcnt vmcnt(4)
	s_barrier
	s_waitcnt lgkmcnt(0)
	s_setprio 1
	s_waitcnt lgkmcnt(7)
	v_mfma_f32_16x16x32_bf16 v[58:61], v[66:69], v[170:173], v[58:61]
	s_waitcnt lgkmcnt(5)
	v_mfma_f32_16x16x32_bf16 v[54:57], v[86:89], v[156:159], v[54:57]
	s_waitcnt lgkmcnt(3)
	v_mfma_f32_16x16x32_bf16 v[46:49], v[202:205], v[156:159], v[46:49]
	s_waitcnt lgkmcnt(1)
	v_mfma_f32_16x16x32_bf16 v[38:41], v[210:213], v[156:159], v[38:41]
	v_mfma_f32_16x16x32_bf16 v[62:65], v[66:69], v[156:159], v[62:65]
	v_mfma_f32_16x16x32_bf16 v[58:61], v[74:77], v[174:177], v[58:61]
	v_mfma_f32_16x16x32_bf16 v[54:57], v[90:93], v[166:169], v[54:57]
	v_mfma_f32_16x16x32_bf16 v[50:53], v[86:89], v[170:173], v[50:53]
	v_mfma_f32_16x16x32_bf16 v[46:49], v[206:209], v[166:169], v[46:49]
	v_mfma_f32_16x16x32_bf16 v[42:45], v[202:205], v[170:173], v[42:45]
	s_waitcnt lgkmcnt(0)
	v_mfma_f32_16x16x32_bf16 v[38:41], v[214:217], v[166:169], v[38:41]
	v_mfma_f32_16x16x32_bf16 v[34:37], v[210:213], v[170:173], v[34:37]
	v_mfma_f32_16x16x32_bf16 v[226:229], v[74:77], v[166:169], v[62:65]
	v_mfma_f32_16x16x32_bf16 v[230:233], v[90:93], v[174:177], v[50:53]
	v_mfma_f32_16x16x32_bf16 v[234:237], v[206:209], v[174:177], v[42:45]
	v_mfma_f32_16x16x32_bf16 v[154:157], v[214:217], v[174:177], v[34:37]
	s_setprio 0
	s_setprio 1
	v_mfma_f32_16x16x32_bf16 v[28:31], v[66:69], v[98:101], v[28:31]
	v_mfma_f32_16x16x32_bf16 v[20:23], v[86:89], v[98:101], v[20:23]
	v_mfma_f32_16x16x32_bf16 v[12:15], v[202:205], v[98:101], v[12:15]
	v_mfma_f32_16x16x32_bf16 v[4:7], v[210:213], v[98:101], v[4:7]
	v_mfma_f32_16x16x32_bf16 v[28:31], v[74:77], v[114:117], v[28:31]
	v_mfma_f32_16x16x32_bf16 v[24:27], v[66:69], v[122:125], v[24:27]
	v_mfma_f32_16x16x32_bf16 v[20:23], v[90:93], v[114:117], v[20:23]
	v_mfma_f32_16x16x32_bf16 v[16:19], v[86:89], v[122:125], v[16:19]
	v_mfma_f32_16x16x32_bf16 v[12:15], v[206:209], v[114:117], v[12:15]
	v_mfma_f32_16x16x32_bf16 v[8:11], v[202:205], v[122:125], v[8:11]
	v_mfma_f32_16x16x32_bf16 v[4:7], v[214:217], v[114:117], v[4:7]
	v_mfma_f32_16x16x32_bf16 v[0:3], v[210:213], v[122:125], v[0:3]
	v_mfma_f32_16x16x32_bf16 v[158:161], v[74:77], v[146:149], v[24:27]
	v_mfma_f32_16x16x32_bf16 v[166:169], v[90:93], v[146:149], v[16:19]
	v_mfma_f32_16x16x32_bf16 v[170:173], v[206:209], v[146:149], v[8:11]
	v_mfma_f32_16x16x32_bf16 v[146:149], v[214:217], v[146:149], v[0:3]
	s_setprio 0
	s_barrier
; #define LDA(dst, b, h) _Pragma("unroll") for (int m = 0; m < 4; ++m) _Pragma("unroll") for (int k = 0; k < 2; ++k) \
;     dst[m][k] = *reinterpret_cast<const bf16x8*>((char*)SA(b, h) + lds_byte(wr * 64 + m * 16 + fr, k * 32 + fq * 8))
; #define LDB(dst, b, h) _Pragma("unroll") for (int n = 0; n < 2; ++n) _Pragma("unroll") for (int k = 0; k < 2; ++k) \
;     dst[n][k] = *reinterpret_cast<const bf16x8*>((char*)SB(b, h) + lds_byte(wc * 32 + n * 16 + fr, k * 32 + fq * 8))
; #define MMA(ai, bj, At, Bt_) do { __builtin_amdgcn_s_setprio(1); \
;     _Pragma("unroll") for (int m = 0; m < 4; ++m) _Pragma("unroll") for (int n = 0; n < 2; ++n) _Pragma("unroll") for (int k = 0; k < 2; ++k) \
;       acc[ai][bj][m][n] = __builtin_amdgcn_mfma_f32_16x16x32_bf16(At[m][k], Bt_[n][k], acc[ai][bj][m][n], 0, 0, 0); \
;     __builtin_amdgcn_s_setprio(0); } while (0)
; #define WAIT_V(n) asm volatile("s_waitcnt vmcnt(" #n ")" ::: "memory")
; #define WAIT_L(n) asm volatile("s_waitcnt lgkmcnt(" #n ")" ::: "memory")
; #define BAR __builtin_amdgcn_s_barrier()
; template <class Epi> ...
;     ...
;   { LDB(B0, 1, 0); LDA(At, 1, 0); WAIT_V(2); BAR; WAIT_L(0); MMA(0, 0, At, B0); BAR;
;     LDB(B1, 1, 1); WAIT_V(0); BAR; WAIT_L(0); MMA(0, 1, At, B1); BAR;
;     LDA(At, 1, 1); BAR; WAIT_L(0); MMA(1, 0, At, B0); MMA(1, 1, At, B1); BAR; }
;   if (wr == 0) BAR;
	ds_read_b128 v[174:177], v145
	ds_read_b128 v[202:205], v145 offset:1024
	ds_read_b128 v[206:209], v145 offset:2048
	ds_read_b128 v[210:213], v145 offset:3072
	ds_read_b128 v[0:3], v143 offset:32768
	ds_read_b128 v[8:11], v143 offset:33792
	ds_read_b128 v[16:19], v142 offset:32768
	ds_read_b128 v[34:37], v142 offset:33792
	ds_read_b128 v[214:217], v141 offset:32768
	ds_read_b128 v[238:241], v141 offset:33792
	ds_read_b128 v[242:245], v140 offset:32768
	ds_read_b128 v[246:249], v140 offset:33792
	s_waitcnt vmcnt(2)
	s_barrier
	s_waitcnt lgkmcnt(0)
	s_setprio 1
	s_waitcnt lgkmcnt(7)
	v_mfma_f32_16x16x32_bf16 v[24:27], v[0:3], v[174:177], v[126:129]
	s_waitcnt lgkmcnt(6)
	v_mfma_f32_16x16x32_bf16 v[122:125], v[8:11], v[202:205], v[24:27]
	v_mfma_f32_16x16x32_bf16 v[24:27], v[0:3], v[206:209], v[150:153]
	v_mfma_f32_16x16x32_bf16 v[90:93], v[8:11], v[210:213], v[24:27]
	s_waitcnt lgkmcnt(5)
	v_mfma_f32_16x16x32_bf16 v[24:27], v[16:19], v[174:177], v[118:121]
	s_waitcnt lgkmcnt(4)
	v_mfma_f32_16x16x32_bf16 v[114:117], v[34:37], v[202:205], v[24:27]
	v_mfma_f32_16x16x32_bf16 v[24:27], v[16:19], v[206:209], v[218:221]
	v_mfma_f32_16x16x32_bf16 v[86:89], v[34:37], v[210:213], v[24:27]
	s_waitcnt lgkmcnt(3)
	v_mfma_f32_16x16x32_bf16 v[24:27], v[214:217], v[174:177], v[110:113]
	s_waitcnt lgkmcnt(2)
	v_mfma_f32_16x16x32_bf16 v[110:113], v[238:241], v[202:205], v[24:27]
	v_mfma_f32_16x16x32_bf16 v[24:27], v[214:217], v[206:209], v[106:109]
	v_mfma_f32_16x16x32_bf16 v[74:77], v[238:241], v[210:213], v[24:27]
	s_waitcnt lgkmcnt(1)
	v_mfma_f32_16x16x32_bf16 v[24:27], v[242:245], v[174:177], v[102:105]
	s_waitcnt lgkmcnt(0)
	v_mfma_f32_16x16x32_bf16 v[98:101], v[246:249], v[202:205], v[24:27]
	v_mfma_f32_16x16x32_bf16 v[24:27], v[242:245], v[206:209], v[222:225]
	v_mfma_f32_16x16x32_bf16 v[66:69], v[246:249], v[210:213], v[24:27]
	s_setprio 0
	s_barrier
	ds_read_b128 v[150:153], v144
	ds_read_b128 v[218:221], v144 offset:1024
	ds_read_b128 v[222:225], v144 offset:2048
	ds_read_b128 v[250:253], v144 offset:3072
	s_waitcnt vmcnt(0)
	s_barrier
	s_waitcnt lgkmcnt(0)
	s_setprio 1
	s_waitcnt lgkmcnt(3)
	v_mfma_f32_16x16x32_bf16 v[24:27], v[0:3], v[150:153], v[94:97]
	s_waitcnt lgkmcnt(1)
	v_mfma_f32_16x16x32_bf16 v[0:3], v[0:3], v[222:225], v[186:189]
	v_mfma_f32_16x16x32_bf16 v[62:65], v[8:11], v[218:221], v[24:27]
	s_waitcnt lgkmcnt(0)
	v_mfma_f32_16x16x32_bf16 v[24:27], v[8:11], v[250:253], v[0:3]
	v_mfma_f32_16x16x32_bf16 v[0:3], v[16:19], v[150:153], v[190:193]
	v_mfma_f32_16x16x32_bf16 v[50:53], v[34:37], v[218:221], v[0:3]
	v_mfma_f32_16x16x32_bf16 v[0:3], v[16:19], v[222:225], v[82:85]
	v_mfma_f32_16x16x32_bf16 v[16:19], v[34:37], v[250:253], v[0:3]
	v_mfma_f32_16x16x32_bf16 v[0:3], v[214:217], v[150:153], v[78:81]
	v_mfma_f32_16x16x32_bf16 v[42:45], v[238:241], v[218:221], v[0:3]
	v_mfma_f32_16x16x32_bf16 v[0:3], v[214:217], v[222:225], v[194:197]
	v_mfma_f32_16x16x32_bf16 v[8:11], v[238:241], v[250:253], v[0:3]
	v_mfma_f32_16x16x32_bf16 v[0:3], v[242:245], v[150:153], v[70:73]
	v_mfma_f32_16x16x32_bf16 v[34:37], v[246:249], v[218:221], v[0:3]
	v_mfma_f32_16x16x32_bf16 v[0:3], v[242:245], v[222:225], v[198:201]
	v_mfma_f32_16x16x32_bf16 v[0:3], v[246:249], v[250:253], v[0:3]
	s_setprio 0
	s_barrier
	ds_read_b128 v[186:189], v143 offset:49152
	ds_read_b128 v[190:193], v143 offset:50176
	ds_read_b128 v[194:197], v142 offset:49152
	ds_read_b128 v[142:145], v142 offset:50176
	ds_read_b128 v[198:201], v141 offset:49152
	ds_read_b128 v[214:217], v141 offset:50176
	ds_read_b128 v[238:241], v140 offset:49152
	ds_read_b128 v[242:245], v140 offset:50176
	s_barrier
	s_waitcnt lgkmcnt(0)
	s_setprio 1
	s_waitcnt lgkmcnt(5)
	v_mfma_f32_16x16x32_bf16 v[54:57], v[194:197], v[174:177], v[54:57]
	s_waitcnt lgkmcnt(3)
	v_mfma_f32_16x16x32_bf16 v[46:49], v[198:201], v[174:177], v[46:49]
	s_waitcnt lgkmcnt(1)
	v_mfma_f32_16x16x32_bf16 v[38:41], v[238:241], v[174:177], v[38:41]
	v_mfma_f32_16x16x32_bf16 v[70:73], v[186:189], v[174:177], v[226:229]
	v_mfma_f32_16x16x32_bf16 v[58:61], v[186:189], v[206:209], v[58:61]
	v_mfma_f32_16x16x32_bf16 v[118:121], v[142:145], v[202:205], v[54:57]
	v_mfma_f32_16x16x32_bf16 v[54:57], v[194:197], v[206:209], v[230:233]
	v_mfma_f32_16x16x32_bf16 v[106:109], v[214:217], v[202:205], v[46:49]
	v_mfma_f32_16x16x32_bf16 v[46:49], v[198:201], v[206:209], v[234:237]
	s_waitcnt lgkmcnt(0)
	v_mfma_f32_16x16x32_bf16 v[102:105], v[242:245], v[202:205], v[38:41]
	v_mfma_f32_16x16x32_bf16 v[38:41], v[238:241], v[206:209], v[154:157]
	v_mfma_f32_16x16x32_bf16 v[126:129], v[190:193], v[202:205], v[70:73]
	v_mfma_f32_16x16x32_bf16 v[94:97], v[190:193], v[210:213], v[58:61]
	v_mfma_f32_16x16x32_bf16 v[82:85], v[142:145], v[210:213], v[54:57]
	v_mfma_f32_16x16x32_bf16 v[78:81], v[214:217], v[210:213], v[46:49]
	v_mfma_f32_16x16x32_bf16 v[70:73], v[242:245], v[210:213], v[38:41]
	s_setprio 0
	s_setprio 1
	v_mfma_f32_16x16x32_bf16 v[28:31], v[186:189], v[150:153], v[28:31]
	v_mfma_f32_16x16x32_bf16 v[20:23], v[194:197], v[150:153], v[20:23]
	v_mfma_f32_16x16x32_bf16 v[12:15], v[198:201], v[150:153], v[12:15]
	v_mfma_f32_16x16x32_bf16 v[4:7], v[238:241], v[150:153], v[4:7]
	v_mfma_f32_16x16x32_bf16 v[58:61], v[190:193], v[218:221], v[28:31]
	v_mfma_f32_16x16x32_bf16 v[28:31], v[186:189], v[222:225], v[158:161]
	v_mfma_f32_16x16x32_bf16 v[54:57], v[142:145], v[218:221], v[20:23]
	v_mfma_f32_16x16x32_bf16 v[20:23], v[194:197], v[222:225], v[166:169]
	v_mfma_f32_16x16x32_bf16 v[46:49], v[214:217], v[218:221], v[12:15]
	v_mfma_f32_16x16x32_bf16 v[12:15], v[198:201], v[222:225], v[170:173]
	v_mfma_f32_16x16x32_bf16 v[38:41], v[242:245], v[218:221], v[4:7]
	v_mfma_f32_16x16x32_bf16 v[4:7], v[238:241], v[222:225], v[146:149]
	v_mfma_f32_16x16x32_bf16 v[28:31], v[190:193], v[250:253], v[28:31]
	v_mfma_f32_16x16x32_bf16 v[20:23], v[142:145], v[250:253], v[20:23]
	v_mfma_f32_16x16x32_bf16 v[12:15], v[214:217], v[250:253], v[12:15]
	v_mfma_f32_16x16x32_bf16 v[4:7], v[242:245], v[250:253], v[4:7]
	s_setprio 0
	v_cmp_gt_u32_e32 vcc, s59, v130
	s_barrier
	s_and_saveexec_b64 s[10:11], vcc
	s_cbranch_execz .LBB0_2256
	s_barrier

; #define STAGE(P, BASE, br, kt) do { int _so = ((br) * K + (kt) * BK) * 2; \
;     __builtin_amdgcn_raw_ptr_buffer_load_lds(rs_##BASE, (__attribute__((address_space(3))) void*)((char*)(P) + tx * 16), 16, voff0, _so, 0, 0); \
;     __builtin_amdgcn_raw_ptr_buffer_load_lds(rs_##BASE, (__attribute__((address_space(3))) void*)((char*)(P) + tx * 16 + 8192), 16, voff1, _so, 0, 0); } while (0)
; #define LDA(dst, b, h) _Pragma("unroll") for (int m = 0; m < 4; ++m) _Pragma("unroll") for (int k = 0; k < 2; ++k) \
;     dst[m][k] = *reinterpret_cast<const bf16x8*>((char*)SA(b, h) + lds_byte(wr * 64 + m * 16 + fr, k * 32 + fq * 8))
; #define LDB(dst, b, h) _Pragma("unroll") for (int n = 0; n < 2; ++n) _Pragma("unroll") for (int k = 0; k < 2; ++k) \
;     dst[n][k] = *reinterpret_cast<const bf16x8*>((char*)SB(b, h) + lds_byte(wc * 32 + n * 16 + fr, k * 32 + fq * 8))
; #define MMA(ai, bj, At, Bt_) do { __builtin_amdgcn_s_setprio(1); \
;     _Pragma("unroll") for (int m = 0; m < 4; ++m) _Pragma("unroll") for (int n = 0; n < 2; ++n) _Pragma("unroll") for (int k = 0; k < 2; ++k) \
;       acc[ai][bj][m][n] = __builtin_amdgcn_mfma_f32_16x16x32_bf16(At[m][k], Bt_[n][k], acc[ai][bj][m][n], 0, 0, 0); \
;     __builtin_amdgcn_s_setprio(0); } while (0)
; #define WAIT_V(n) asm volatile("s_waitcnt vmcnt(" #n ")" ::: "memory")
; #define WAIT_L(n) asm volatile("s_waitcnt lgkmcnt(" #n ")" ::: "memory")
; template <class Epi> ...
;     ...
;   { int _r, _c; stage_rc(tx * 16, _r, _c); voff0 = (_r * K + _c) * 2; stage_rc(tx * 16 + 8192, _r, _c); voff1 = (_r * K + _c) * 2; }
;   __amdgpu_buffer_rsrc_t rs_A = __builtin_amdgcn_make_buffer_rsrc((void*)A, 0, 0x7fffffff, 0x00020000);
;   __amdgpu_buffer_rsrc_t rs_Bt = __builtin_amdgcn_make_buffer_rsrc((void*)Bt, 0, 0x7fffffff, 0x00020000);
;   if (!pre) {
;     STAGE(SB(0, 0), Bt, bcol, 0); STAGE(SA(0, 0), A, brow, 0);
;     STAGE(SB(0, 1), Bt, bcol + HALF, 0); STAGE(SA(0, 1), A, brow + HALF, 0);
;   }
;   if (wr == 1) BAR;
;   if (pre) { WAIT_V(0); } else { WAIT_V(4); }
;   BAR;
;   STAGE(SB(1, 0), Bt, bcol, 1); STAGE(SA(1, 0), A, brow, 1); STAGE(SB(1, 1), Bt, bcol + HALF, 1);
;   WAIT_V(6); BAR;
;     ...
;     LDB(B0, 0, 0); SCHED; LDA(At, 0, 0); STAGE(SA(1, 1), A, brow + HALF, t + 1);
;     WAIT_L(8); BAR; WAIT_L(0); MMA(0, 0, At, B0); BAR; SCHED;
;     LDB(B1, 0, 1); STAGE(SB(0, 0), Bt, bcol, t + 2);
;     BAR; WAIT_L(0); MMA(0, 1, At, B1); BAR;
.LBB0_2335:
	v_readlane_b32 s23, v254, 30
	s_or_b32 s6, s22, 0x80
	v_add_u32_e32 v148, 0x8000, v136
	v_add_u32_e32 v146, s23, v0
	v_add_u32_e32 v147, 0x2000, v146
	v_readfirstlane_b32 s7, v146
	s_mov_b32 m0, s7
	v_readfirstlane_b32 s7, v147
	s_barrier
	buffer_load_dwordx4 v32, s[76:79], s6 offen lds
	s_mov_b32 m0, s7
	v_readfirstlane_b32 s15, v148
	v_add_u32_e32 v150, 0xa000, v136
	v_readlane_b32 s24, v254, 31
	buffer_load_dwordx4 v131, s[76:79], s6 offen lds
	s_or_b32 s14, s21, 0x80
	s_mov_b32 s6, s78
	s_mov_b32 s7, s79
	s_mov_b32 m0, s15
	v_readfirstlane_b32 s15, v150
	v_add_u32_e32 v153, s24, v0
	buffer_load_dwordx4 v32, s[4:7], s14 offen lds
	s_mov_b32 m0, s15
	v_readfirstlane_b32 s15, v153
	v_add_u32_e32 v154, 0x2000, v153
	buffer_load_dwordx4 v131, s[4:7], s14 offen lds
	s_add_i32 s14, s22, 0xb0080
	s_mov_b32 m0, s15
	v_readfirstlane_b32 s15, v154
	buffer_load_dwordx4 v32, s[76:79], s14 offen lds
	s_mov_b32 m0, s15
	v_and_b32_e32 v2, 15, v130
	buffer_load_dwordx4 v131, s[76:79], s14 offen lds
	v_lshlrev_b32_e32 v0, 6, v2
	v_lshlrev_b32_e32 v2, 2, v130
	v_and_b32_e32 v3, 48, v130
	v_and_b32_e32 v2, 32, v2
	v_bitop3_b32 v0, v0, v2, v3 bitop3:0x36
	s_waitcnt vmcnt(11)
	v_lshlrev_b32_e32 v8, 6, v130
	s_movk_i32 s14, 0x3c0
	s_waitcnt vmcnt(6)
	v_add_u32_e32 v4, s71, v0
	v_add_u32_e32 v5, s73, v0
	v_add_u32_e32 v6, s23, v0
	v_add_u32_e32 v7, s24, v0
	v_lshlrev_b32_e32 v1, 13, v1
	v_add_u32_e32 v10, 0, v0
	v_and_or_b32 v0, v8, s14, v3
	v_and_b32_e32 v9, 0x3000, v8
	v_xad_u32 v2, v0, v2, 0
	v_or_b32_e32 v3, 0x800, v1
	v_or_b32_e32 v8, 0x1000, v1
	v_or_b32_e32 v11, 0x1800, v1
	v_add_u32_e32 v152, 0xc000, v136
	v_add_u32_e32 v151, 0xe000, v136
	v_add_u32_e32 v139, 0x2000, v137
	v_add_u32_e32 v138, 0x2000, v134
	s_mov_b32 s14, -2
	s_mov_b32 s15, 0
	v_add_u32_e32 v155, v4, v9
	v_add_u32_e32 v143, v10, v1
	v_add_u32_e32 v142, v2, v3
	v_add_u32_e32 v141, v2, v8
	v_add_u32_e32 v140, v2, v11
	v_add_u32_e32 v149, v5, v9
	v_add_u32_e32 v145, v6, v9
	v_add_u32_e32 v144, v7, v9
	s_waitcnt vmcnt(10)
	s_barrier
.Lpk8:
	ds_read_b128 v[156:159], v155
	ds_read_b128 v[166:169], v155 offset:1024
	ds_read_b128 v[170:173], v155 offset:2048
	ds_read_b128 v[174:177], v155 offset:3072
	s_add_i32 s23, s21, s15
	v_readfirstlane_b32 s25, v152
	s_add_i32 s24, s23, 0xb0080
	s_mov_b32 m0, s25
	v_readfirstlane_b32 s25, v151
	ds_read_b128 v[186:189], v143
	ds_read_b128 v[190:193], v143 offset:1024
	ds_read_b128 v[194:197], v142
	ds_read_b128 v[198:201], v142 offset:1024
	ds_read_b128 v[202:205], v141
	ds_read_b128 v[206:209], v141 offset:1024
	ds_read_b128 v[210:213], v140
	ds_read_b128 v[214:217], v140 offset:1024
	buffer_load_dwordx4 v32, s[4:7], s24 offen lds
	s_mov_b32 m0, s25
	s_nop 0
	buffer_load_dwordx4 v131, s[4:7], s24 offen lds
	s_waitcnt lgkmcnt(8)
	s_barrier
	s_waitcnt lgkmcnt(0)
	s_setprio 1
	s_waitcnt lgkmcnt(7)
	v_mfma_f32_16x16x32_bf16 v[126:129], v[186:189], v[156:159], 0
	v_mfma_f32_16x16x32_bf16 v[122:125], v[186:189], v[170:173], 0
	s_waitcnt lgkmcnt(5)
	v_mfma_f32_16x16x32_bf16 v[118:121], v[194:197], v[156:159], 0
	v_mfma_f32_16x16x32_bf16 v[114:117], v[194:197], v[170:173], 0
	s_waitcnt lgkmcnt(3)
	v_mfma_f32_16x16x32_bf16 v[110:113], v[202:205], v[156:159], 0
	v_mfma_f32_16x16x32_bf16 v[106:109], v[202:205], v[170:173], 0
	s_waitcnt lgkmcnt(1)
	v_mfma_f32_16x16x32_bf16 v[102:105], v[210:213], v[156:159], 0
	v_mfma_f32_16x16x32_bf16 v[98:101], v[210:213], v[170:173], 0
	v_mfma_f32_16x16x32_bf16 v[126:129], v[190:193], v[166:169], v[126:129]
	v_mfma_f32_16x16x32_bf16 v[122:125], v[190:193], v[174:177], v[122:125]
	v_mfma_f32_16x16x32_bf16 v[118:121], v[198:201], v[166:169], v[118:121]
	v_mfma_f32_16x16x32_bf16 v[114:117], v[198:201], v[174:177], v[114:117]
	v_mfma_f32_16x16x32_bf16 v[110:113], v[206:209], v[166:169], v[110:113]
	v_mfma_f32_16x16x32_bf16 v[106:109], v[206:209], v[174:177], v[106:109]
	s_waitcnt lgkmcnt(0)
	v_mfma_f32_16x16x32_bf16 v[102:105], v[214:217], v[166:169], v[102:105]
	v_mfma_f32_16x16x32_bf16 v[98:101], v[214:217], v[174:177], v[98:101]
	s_setprio 0
	s_barrier
	s_add_i32 s24, s22, s15
	v_readfirstlane_b32 s26, v137
	s_add_i32 s25, s24, 0x100
	s_mov_b32 m0, s26
	v_readfirstlane_b32 s26, v139
	ds_read_b128 v[218:221], v149
	ds_read_b128 v[222:225], v149 offset:1024
	ds_read_b128 v[226:229], v149 offset:2048
	ds_read_b128 v[230:233], v149 offset:3072
	buffer_load_dwordx4 v32, s[76:79], s25 offen lds
	s_mov_b32 m0, s26
	s_nop 0
	buffer_load_dwordx4 v131, s[76:79], s25 offen lds
	s_barrier
	s_waitcnt lgkmcnt(0)
	s_setprio 1
	s_waitcnt lgkmcnt(3)
	v_mfma_f32_16x16x32_bf16 v[94:97], v[186:189], v[218:221], 0
	s_waitcnt lgkmcnt(1)
	v_mfma_f32_16x16x32_bf16 v[90:93], v[186:189], v[226:229], 0
	v_mfma_f32_16x16x32_bf16 v[86:89], v[194:197], v[218:221], 0
	v_mfma_f32_16x16x32_bf16 v[82:85], v[194:197], v[226:229], 0
	v_mfma_f32_16x16x32_bf16 v[78:81], v[202:205], v[218:221], 0
	v_mfma_f32_16x16x32_bf16 v[74:77], v[202:205], v[226:229], 0
	v_mfma_f32_16x16x32_bf16 v[70:73], v[210:213], v[218:221], 0
	v_mfma_f32_16x16x32_bf16 v[66:69], v[210:213], v[226:229], 0
	v_mfma_f32_16x16x32_bf16 v[94:97], v[190:193], v[222:225], v[94:97]
	s_waitcnt lgkmcnt(0)
	v_mfma_f32_16x16x32_bf16 v[90:93], v[190:193], v[230:233], v[90:93]
	v_mfma_f32_16x16x32_bf16 v[86:89], v[198:201], v[222:225], v[86:89]
	v_mfma_f32_16x16x32_bf16 v[82:85], v[198:201], v[230:233], v[82:85]
	v_mfma_f32_16x16x32_bf16 v[78:81], v[206:209], v[222:225], v[78:81]
	v_mfma_f32_16x16x32_bf16 v[74:77], v[206:209], v[230:233], v[74:77]
	v_mfma_f32_16x16x32_bf16 v[70:73], v[214:217], v[222:225], v[70:73]
	v_mfma_f32_16x16x32_bf16 v[66:69], v[214:217], v[230:233], v[66:69]
	s_setprio 0
	v_readfirstlane_b32 s26, v136
	s_add_i32 s25, s23, 0x100
	s_mov_b32 m0, s26
	v_readfirstlane_b32 s26, v135
	s_barrier
; #define STAGE(P, BASE, br, kt) do { int _so = ((br) * K + (kt) * BK) * 2; \
;     __builtin_amdgcn_raw_ptr_buffer_load_lds(rs_##BASE, (__attribute__((address_space(3))) void*)((char*)(P) + tx * 16), 16, voff0, _so, 0, 0); \
;     __builtin_amdgcn_raw_ptr_buffer_load_lds(rs_##BASE, (__attribute__((address_space(3))) void*)((char*)(P) + tx * 16 + 8192), 16, voff1, _so, 0, 0); } while (0)
; #define LDA(dst, b, h) _Pragma("unroll") for (int m = 0; m < 4; ++m) _Pragma("unroll") for (int k = 0; k < 2; ++k) \
;     dst[m][k] = *reinterpret_cast<const bf16x8*>((char*)SA(b, h) + lds_byte(wr * 64 + m * 16 + fr, k * 32 + fq * 8))
; #define LDB(dst, b, h) _Pragma("unroll") for (int n = 0; n < 2; ++n) _Pragma("unroll") for (int k = 0; k < 2; ++k) \
;     dst[n][k] = *reinterpret_cast<const bf16x8*>((char*)SB(b, h) + lds_byte(wc * 32 + n * 16 + fr, k * 32 + fq * 8))
; #define MMA(ai, bj, At, Bt_) do { __builtin_amdgcn_s_setprio(1); \
;     _Pragma("unroll") for (int m = 0; m < 4; ++m) _Pragma("unroll") for (int n = 0; n < 2; ++n) _Pragma("unroll") for (int k = 0; k < 2; ++k) \
;       acc[ai][bj][m][n] = __builtin_amdgcn_mfma_f32_16x16x32_bf16(At[m][k], Bt_[n][k], acc[ai][bj][m][n], 0, 0, 0); \
;     __builtin_amdgcn_s_setprio(0); } while (0)
; #define WAIT_V(n) asm volatile("s_waitcnt vmcnt(" #n ")" ::: "memory")
; #define WAIT_L(n) asm volatile("s_waitcnt lgkmcnt(" #n ")" ::: "memory")
; #define BAR __builtin_amdgcn_s_barrier()
; #define SCHED __builtin_amdgcn_sched_barrier(0)
; template <class Epi> ...
;     ...
;     LDA(At, 0, 1); STAGE(SA(0, 0), A, brow, t + 2);
;     BAR; WAIT_L(0); MMA(1, 0, At, B0); BAR; SCHED;
;     STAGE(SB(0, 1), Bt, bcol + HALF, t + 2);
;     WAIT_V(6); BAR; MMA(1, 1, At, B1); BAR;
;     LDB(B0, 1, 0); SCHED; LDA(At, 1, 0); STAGE(SA(0, 1), A, brow + HALF, t + 2);
;     WAIT_L(8); BAR; WAIT_L(0); MMA(0, 0, At, B0); BAR; SCHED;
	ds_read_b128 v[186:189], v143 offset:16384
	ds_read_b128 v[190:193], v143 offset:17408
	ds_read_b128 v[194:197], v142 offset:16384
	ds_read_b128 v[198:201], v142 offset:17408
	ds_read_b128 v[202:205], v141 offset:16384
	ds_read_b128 v[206:209], v141 offset:17408
	ds_read_b128 v[210:213], v140 offset:16384
	ds_read_b128 v[214:217], v140 offset:17408
	buffer_load_dwordx4 v32, s[4:7], s25 offen lds
	s_mov_b32 m0, s26
	s_nop 0
	buffer_load_dwordx4 v131, s[4:7], s25 offen lds
	s_barrier
	s_waitcnt lgkmcnt(0)
	s_setprio 1
	s_waitcnt lgkmcnt(7)
	v_mfma_f32_16x16x32_bf16 v[62:65], v[186:189], v[156:159], 0
	v_mfma_f32_16x16x32_bf16 v[58:61], v[186:189], v[170:173], 0
	s_waitcnt lgkmcnt(5)
	v_mfma_f32_16x16x32_bf16 v[54:57], v[194:197], v[156:159], 0
	v_mfma_f32_16x16x32_bf16 v[50:53], v[194:197], v[170:173], 0
	s_waitcnt lgkmcnt(3)
	v_mfma_f32_16x16x32_bf16 v[46:49], v[202:205], v[156:159], 0
	v_mfma_f32_16x16x32_bf16 v[42:45], v[202:205], v[170:173], 0
	s_waitcnt lgkmcnt(1)
	v_mfma_f32_16x16x32_bf16 v[38:41], v[210:213], v[156:159], 0
	v_mfma_f32_16x16x32_bf16 v[34:37], v[210:213], v[170:173], 0
	v_mfma_f32_16x16x32_bf16 v[62:65], v[190:193], v[166:169], v[62:65]
	v_mfma_f32_16x16x32_bf16 v[58:61], v[190:193], v[174:177], v[58:61]
	v_mfma_f32_16x16x32_bf16 v[54:57], v[198:201], v[166:169], v[54:57]
	v_mfma_f32_16x16x32_bf16 v[50:53], v[198:201], v[174:177], v[50:53]
	v_mfma_f32_16x16x32_bf16 v[46:49], v[206:209], v[166:169], v[46:49]
	v_mfma_f32_16x16x32_bf16 v[42:45], v[206:209], v[174:177], v[42:45]
	s_waitcnt lgkmcnt(0)
	v_mfma_f32_16x16x32_bf16 v[38:41], v[214:217], v[166:169], v[38:41]
	v_mfma_f32_16x16x32_bf16 v[34:37], v[214:217], v[174:177], v[34:37]
	s_setprio 0
	s_barrier
	v_readfirstlane_b32 s26, v134
	s_add_i32 s25, s24, 0xb0100
	s_mov_b32 m0, s26
	v_readfirstlane_b32 s26, v138
	buffer_load_dwordx4 v32, s[76:79], s25 offen lds
	s_mov_b32 m0, s26
	s_nop 0
	buffer_load_dwordx4 v131, s[76:79], s25 offen lds
	s_waitcnt vmcnt(6)
	s_barrier
	s_setprio 1
	v_mfma_f32_16x16x32_bf16 v[28:31], v[186:189], v[218:221], 0
	v_mfma_f32_16x16x32_bf16 v[24:27], v[186:189], v[226:229], 0
	v_mfma_f32_16x16x32_bf16 v[20:23], v[194:197], v[218:221], 0
	v_mfma_f32_16x16x32_bf16 v[16:19], v[194:197], v[226:229], 0
	v_mfma_f32_16x16x32_bf16 v[12:15], v[202:205], v[218:221], 0
	v_mfma_f32_16x16x32_bf16 v[8:11], v[202:205], v[226:229], 0
	v_mfma_f32_16x16x32_bf16 v[4:7], v[210:213], v[218:221], 0
	v_mfma_f32_16x16x32_bf16 v[0:3], v[210:213], v[226:229], 0
	v_mfma_f32_16x16x32_bf16 v[28:31], v[190:193], v[222:225], v[28:31]
	v_mfma_f32_16x16x32_bf16 v[24:27], v[190:193], v[230:233], v[24:27]
	v_mfma_f32_16x16x32_bf16 v[20:23], v[198:201], v[222:225], v[20:23]
	v_mfma_f32_16x16x32_bf16 v[16:19], v[198:201], v[230:233], v[16:19]
	v_mfma_f32_16x16x32_bf16 v[12:15], v[206:209], v[222:225], v[12:15]
	v_mfma_f32_16x16x32_bf16 v[8:11], v[206:209], v[230:233], v[8:11]
	v_mfma_f32_16x16x32_bf16 v[4:7], v[214:217], v[222:225], v[4:7]
	v_mfma_f32_16x16x32_bf16 v[0:3], v[214:217], v[230:233], v[0:3]
	s_setprio 0
	s_barrier
	ds_read_b128 v[156:159], v145
	ds_read_b128 v[166:169], v145 offset:1024
	ds_read_b128 v[170:173], v145 offset:2048
	ds_read_b128 v[174:177], v145 offset:3072
	v_readfirstlane_b32 s26, v133
	s_add_i32 s25, s23, 0xb0100
	s_mov_b32 m0, s26
	v_readfirstlane_b32 s26, v132
	ds_read_b128 v[186:189], v143 offset:32768
	ds_read_b128 v[190:193], v143 offset:33792
	ds_read_b128 v[194:197], v142 offset:32768
	ds_read_b128 v[198:201], v142 offset:33792
	ds_read_b128 v[202:205], v141 offset:32768
	ds_read_b128 v[206:209], v141 offset:33792
	ds_read_b128 v[210:213], v140 offset:32768
	ds_read_b128 v[214:217], v140 offset:33792
	buffer_load_dwordx4 v32, s[4:7], s25 offen lds
	s_mov_b32 m0, s26
	s_nop 0
	buffer_load_dwordx4 v131, s[4:7], s25 offen lds
	s_waitcnt lgkmcnt(8)
	s_barrier
	s_waitcnt lgkmcnt(0)
	s_setprio 1
	s_waitcnt lgkmcnt(7)
	v_mfma_f32_16x16x32_bf16 v[126:129], v[186:189], v[156:159], v[126:129]
	v_mfma_f32_16x16x32_bf16 v[122:125], v[186:189], v[170:173], v[122:125]
	s_waitcnt lgkmcnt(5)
	v_mfma_f32_16x16x32_bf16 v[118:121], v[194:197], v[156:159], v[118:121]
	v_mfma_f32_16x16x32_bf16 v[114:117], v[194:197], v[170:173], v[114:117]
	s_waitcnt lgkmcnt(3)
	v_mfma_f32_16x16x32_bf16 v[110:113], v[202:205], v[156:159], v[110:113]
	v_mfma_f32_16x16x32_bf16 v[106:109], v[202:205], v[170:173], v[106:109]
	s_waitcnt lgkmcnt(1)
	v_mfma_f32_16x16x32_bf16 v[102:105], v[210:213], v[156:159], v[102:105]
	v_mfma_f32_16x16x32_bf16 v[98:101], v[210:213], v[170:173], v[98:101]
	v_mfma_f32_16x16x32_bf16 v[126:129], v[190:193], v[166:169], v[126:129]
	v_mfma_f32_16x16x32_bf16 v[122:125], v[190:193], v[174:177], v[122:125]
	v_mfma_f32_16x16x32_bf16 v[118:121], v[198:201], v[166:169], v[118:121]
	v_mfma_f32_16x16x32_bf16 v[114:117], v[198:201], v[174:177], v[114:117]
	v_mfma_f32_16x16x32_bf16 v[110:113], v[206:209], v[166:169], v[110:113]
	v_mfma_f32_16x16x32_bf16 v[106:109], v[206:209], v[174:177], v[106:109]
	s_waitcnt lgkmcnt(0)
	v_mfma_f32_16x16x32_bf16 v[102:105], v[214:217], v[166:169], v[102:105]
	v_mfma_f32_16x16x32_bf16 v[98:101], v[214:217], v[174:177], v[98:101]
	s_setprio 0
	s_barrier
; #define STAGE(P, BASE, br, kt) do { int _so = ((br) * K + (kt) * BK) * 2; \
;     __builtin_amdgcn_raw_ptr_buffer_load_lds(rs_##BASE, (__attribute__((address_space(3))) void*)((char*)(P) + tx * 16), 16, voff0, _so, 0, 0); \
;     __builtin_amdgcn_raw_ptr_buffer_load_lds(rs_##BASE, (__attribute__((address_space(3))) void*)((char*)(P) + tx * 16 + 8192), 16, voff1, _so, 0, 0); } while (0)
; #define LDA(dst, b, h) _Pragma("unroll") for (int m = 0; m < 4; ++m) _Pragma("unroll") for (int k = 0; k < 2; ++k) \
;     dst[m][k] = *reinterpret_cast<const bf16x8*>((char*)SA(b, h) + lds_byte(wr * 64 + m * 16 + fr, k * 32 + fq * 8))
; #define LDB(dst, b, h) _Pragma("unroll") for (int n = 0; n < 2; ++n) _Pragma("unroll") for (int k = 0; k < 2; ++k) \
;     dst[n][k] = *reinterpret_cast<const bf16x8*>((char*)SB(b, h) + lds_byte(wc * 32 + n * 16 + fr, k * 32 + fq * 8))
; #define MMA(ai, bj, At, Bt_) do { __builtin_amdgcn_s_setprio(1); \
;     _Pragma("unroll") for (int m = 0; m < 4; ++m) _Pragma("unroll") for (int n = 0; n < 2; ++n) _Pragma("unroll") for (int k = 0; k < 2; ++k) \
;       acc[ai][bj][m][n] = __builtin_amdgcn_mfma_f32_16x16x32_bf16(At[m][k], Bt_[n][k], acc[ai][bj][m][n], 0, 0, 0); \
;     __builtin_amdgcn_s_setprio(0); } while (0)
; #define WAIT_V(n) asm volatile("s_waitcnt vmcnt(" #n ")" ::: "memory")
; #define WAIT_L(n) asm volatile("s_waitcnt lgkmcnt(" #n ")" ::: "memory")
; #define BAR __builtin_amdgcn_s_barrier()
; #define SCHED __builtin_amdgcn_sched_barrier(0)
; template <class Epi> ...
;     ...
;   for (int t = 0; t < nt - 2; t += 2) {
;     ...
;     LDB(B1, 1, 1); STAGE(SB(1, 0), Bt, bcol, t + 3);
;     BAR; WAIT_L(0); MMA(0, 1, At, B1); BAR;
;     LDA(At, 1, 1); STAGE(SA(1, 0), A, brow, t + 3);
;     BAR; WAIT_L(0); MMA(1, 0, At, B0); BAR; SCHED;
;     STAGE(SB(1, 1), Bt, bcol + HALF, t + 3);
;     WAIT_V(6); BAR; MMA(1, 1, At, B1); BAR;
;   }
	v_readfirstlane_b32 s26, v146
	s_add_i32 s25, s24, 0x180
	s_mov_b32 m0, s26
	v_readfirstlane_b32 s26, v147
	ds_read_b128 v[218:221], v144
	ds_read_b128 v[222:225], v144 offset:1024
	ds_read_b128 v[226:229], v144 offset:2048
	ds_read_b128 v[230:233], v144 offset:3072
	buffer_load_dwordx4 v32, s[76:79], s25 offen lds
	s_mov_b32 m0, s26
	s_nop 0
	buffer_load_dwordx4 v131, s[76:79], s25 offen lds
	s_barrier
	s_waitcnt lgkmcnt(0)
	s_setprio 1
	s_waitcnt lgkmcnt(3)
	v_mfma_f32_16x16x32_bf16 v[94:97], v[186:189], v[218:221], v[94:97]
	s_waitcnt lgkmcnt(1)
	v_mfma_f32_16x16x32_bf16 v[90:93], v[186:189], v[226:229], v[90:93]
	v_mfma_f32_16x16x32_bf16 v[86:89], v[194:197], v[218:221], v[86:89]
	v_mfma_f32_16x16x32_bf16 v[82:85], v[194:197], v[226:229], v[82:85]
	v_mfma_f32_16x16x32_bf16 v[78:81], v[202:205], v[218:221], v[78:81]
	v_mfma_f32_16x16x32_bf16 v[74:77], v[202:205], v[226:229], v[74:77]
	v_mfma_f32_16x16x32_bf16 v[70:73], v[210:213], v[218:221], v[70:73]
	v_mfma_f32_16x16x32_bf16 v[66:69], v[210:213], v[226:229], v[66:69]
	v_mfma_f32_16x16x32_bf16 v[94:97], v[190:193], v[222:225], v[94:97]
	s_waitcnt lgkmcnt(0)
	v_mfma_f32_16x16x32_bf16 v[90:93], v[190:193], v[230:233], v[90:93]
	v_mfma_f32_16x16x32_bf16 v[86:89], v[198:201], v[222:225], v[86:89]
	v_mfma_f32_16x16x32_bf16 v[82:85], v[198:201], v[230:233], v[82:85]
	v_mfma_f32_16x16x32_bf16 v[78:81], v[206:209], v[222:225], v[78:81]
	v_mfma_f32_16x16x32_bf16 v[74:77], v[206:209], v[230:233], v[74:77]
	v_mfma_f32_16x16x32_bf16 v[70:73], v[214:217], v[222:225], v[70:73]
	v_mfma_f32_16x16x32_bf16 v[66:69], v[214:217], v[230:233], v[66:69]
	s_setprio 0
	v_readfirstlane_b32 s25, v148
	s_addk_i32 s23, 0x180
	s_mov_b32 m0, s25
	v_readfirstlane_b32 s25, v150
	s_barrier
	ds_read_b128 v[186:189], v143 offset:49152
	ds_read_b128 v[190:193], v143 offset:50176
	ds_read_b128 v[194:197], v142 offset:49152
	ds_read_b128 v[198:201], v142 offset:50176
	ds_read_b128 v[202:205], v141 offset:49152
	ds_read_b128 v[206:209], v141 offset:50176
	ds_read_b128 v[210:213], v140 offset:49152
	ds_read_b128 v[214:217], v140 offset:50176
	buffer_load_dwordx4 v32, s[4:7], s23 offen lds
	s_mov_b32 m0, s25
	s_nop 0
	buffer_load_dwordx4 v131, s[4:7], s23 offen lds
	s_barrier
	s_waitcnt lgkmcnt(0)
	s_setprio 1
	s_waitcnt lgkmcnt(7)
	v_mfma_f32_16x16x32_bf16 v[62:65], v[186:189], v[156:159], v[62:65]
	v_mfma_f32_16x16x32_bf16 v[58:61], v[186:189], v[170:173], v[58:61]
	s_waitcnt lgkmcnt(5)
	v_mfma_f32_16x16x32_bf16 v[54:57], v[194:197], v[156:159], v[54:57]
	v_mfma_f32_16x16x32_bf16 v[50:53], v[194:197], v[170:173], v[50:53]
	s_waitcnt lgkmcnt(3)
	v_mfma_f32_16x16x32_bf16 v[46:49], v[202:205], v[156:159], v[46:49]
	v_mfma_f32_16x16x32_bf16 v[42:45], v[202:205], v[170:173], v[42:45]
	s_waitcnt lgkmcnt(1)
	v_mfma_f32_16x16x32_bf16 v[38:41], v[210:213], v[156:159], v[38:41]
	v_mfma_f32_16x16x32_bf16 v[34:37], v[210:213], v[170:173], v[34:37]
	v_mfma_f32_16x16x32_bf16 v[62:65], v[190:193], v[166:169], v[62:65]
	v_mfma_f32_16x16x32_bf16 v[58:61], v[190:193], v[174:177], v[58:61]
	v_mfma_f32_16x16x32_bf16 v[54:57], v[198:201], v[166:169], v[54:57]
	v_mfma_f32_16x16x32_bf16 v[50:53], v[198:201], v[174:177], v[50:53]
	v_mfma_f32_16x16x32_bf16 v[46:49], v[206:209], v[166:169], v[46:49]
	v_mfma_f32_16x16x32_bf16 v[42:45], v[206:209], v[174:177], v[42:45]
	s_waitcnt lgkmcnt(0)
	v_mfma_f32_16x16x32_bf16 v[38:41], v[214:217], v[166:169], v[38:41]
	v_mfma_f32_16x16x32_bf16 v[34:37], v[214:217], v[174:177], v[34:37]
	s_setprio 0
	s_barrier
	v_readfirstlane_b32 s23, v153
	s_add_i32 s24, s24, 0xb0180
	s_mov_b32 m0, s23
	v_readfirstlane_b32 s23, v154
	buffer_load_dwordx4 v32, s[76:79], s24 offen lds
	s_mov_b32 m0, s23
	s_nop 0
	buffer_load_dwordx4 v131, s[76:79], s24 offen lds
	s_waitcnt vmcnt(6)
	s_barrier
	s_setprio 1
	v_mfma_f32_16x16x32_bf16 v[28:31], v[186:189], v[218:221], v[28:31]
	v_mfma_f32_16x16x32_bf16 v[24:27], v[186:189], v[226:229], v[24:27]
	v_mfma_f32_16x16x32_bf16 v[20:23], v[194:197], v[218:221], v[20:23]
	v_mfma_f32_16x16x32_bf16 v[16:19], v[194:197], v[226:229], v[16:19]
	v_mfma_f32_16x16x32_bf16 v[12:15], v[202:205], v[218:221], v[12:15]
	v_mfma_f32_16x16x32_bf16 v[8:11], v[202:205], v[226:229], v[8:11]
	v_mfma_f32_16x16x32_bf16 v[4:7], v[210:213], v[218:221], v[4:7]
	v_mfma_f32_16x16x32_bf16 v[0:3], v[210:213], v[226:229], v[0:3]
	v_mfma_f32_16x16x32_bf16 v[28:31], v[190:193], v[222:225], v[28:31]
	v_mfma_f32_16x16x32_bf16 v[24:27], v[190:193], v[230:233], v[24:27]
	v_mfma_f32_16x16x32_bf16 v[20:23], v[198:201], v[222:225], v[20:23]
	v_mfma_f32_16x16x32_bf16 v[16:19], v[198:201], v[230:233], v[16:19]
	v_mfma_f32_16x16x32_bf16 v[12:15], v[206:209], v[222:225], v[12:15]
	v_mfma_f32_16x16x32_bf16 v[8:11], v[206:209], v[230:233], v[8:11]
	v_mfma_f32_16x16x32_bf16 v[4:7], v[214:217], v[222:225], v[4:7]
	v_mfma_f32_16x16x32_bf16 v[0:3], v[214:217], v[230:233], v[0:3]
	s_setprio 0
	s_add_i32 s14, s14, 2
	s_addk_i32 s15, 0x100
	s_cmp_lt_u32 s14, 40
	s_barrier
	s_cbranch_scc1 .LBB0_2336
	s_branch .Lpx8

; #define STAGE(P, BASE, br, kt) do { int _so = ((br) * K + (kt) * BK) * 2; \
;     __builtin_amdgcn_raw_ptr_buffer_load_lds(rs_##BASE, (__attribute__((address_space(3))) void*)((char*)(P) + tx * 16), 16, voff0, _so, 0, 0); \
;     __builtin_amdgcn_raw_ptr_buffer_load_lds(rs_##BASE, (__attribute__((address_space(3))) void*)((char*)(P) + tx * 16 + 8192), 16, voff1, _so, 0, 0); } while (0)
; #define LDA(dst, b, h) _Pragma("unroll") for (int m = 0; m < 4; ++m) _Pragma("unroll") for (int k = 0; k < 2; ++k) \
;     dst[m][k] = *reinterpret_cast<const bf16x8*>((char*)SA(b, h) + lds_byte(wr * 64 + m * 16 + fr, k * 32 + fq * 8))
; #define LDB(dst, b, h) _Pragma("unroll") for (int n = 0; n < 2; ++n) _Pragma("unroll") for (int k = 0; k < 2; ++k) \
;     dst[n][k] = *reinterpret_cast<const bf16x8*>((char*)SB(b, h) + lds_byte(wc * 32 + n * 16 + fr, k * 32 + fq * 8))
; #define MMA(ai, bj, At, Bt_) do { __builtin_amdgcn_s_setprio(1); \
;     _Pragma("unroll") for (int m = 0; m < 4; ++m) _Pragma("unroll") for (int n = 0; n < 2; ++n) _Pragma("unroll") for (int k = 0; k < 2; ++k) \
;       acc[ai][bj][m][n] = __builtin_amdgcn_mfma_f32_16x16x32_bf16(At[m][k], Bt_[n][k], acc[ai][bj][m][n], 0, 0, 0); \
;     __builtin_amdgcn_s_setprio(0); } while (0)
; #define WAIT_V(n) asm volatile("s_waitcnt vmcnt(" #n ")" ::: "memory")
; #define WAIT_L(n) asm volatile("s_waitcnt lgkmcnt(" #n ")" ::: "memory")
; #define BAR __builtin_amdgcn_s_barrier()
; template <class Epi> ...
;     ...
;   { LDB(B0, 0, 0); LDA(At, 0, 0); STAGE(SA(1, 1), A, brow + HALF, nt - 1);
;     BAR; WAIT_L(0); MMA(0, 0, At, B0); BAR;
;     LDB(B1, 0, 1); BAR; WAIT_L(0); MMA(0, 1, At, B1); BAR;
;     LDA(At, 0, 1); WAIT_V(4); BAR; WAIT_L(0); MMA(1, 0, At, B0); MMA(1, 1, At, B1); BAR; }
.Lpx8:
	v_readfirstlane_b32 s14, v152
	s_add_i32 s21, s21, 0xb1580
	s_mov_b32 s6, s78
	s_mov_b32 s7, s79
	s_mov_b32 m0, s14
	v_readfirstlane_b32 s14, v151
	ds_read_b128 v[156:159], v155
	ds_read_b128 v[166:169], v155 offset:1024
	ds_read_b128 v[170:173], v155 offset:2048
	ds_read_b128 v[174:177], v155 offset:3072
	ds_read_b128 v[186:189], v143
	ds_read_b128 v[190:193], v143 offset:1024
	ds_read_b128 v[194:197], v142
	ds_read_b128 v[198:201], v142 offset:1024
	ds_read_b128 v[202:205], v141
	ds_read_b128 v[206:209], v141 offset:1024
	ds_read_b128 v[210:213], v140
	ds_read_b128 v[214:217], v140 offset:1024
	buffer_load_dwordx4 v32, s[4:7], s21 offen lds
	s_mov_b32 m0, s14
	s_nop 0
	buffer_load_dwordx4 v131, s[4:7], s21 offen lds
	s_barrier
	s_waitcnt lgkmcnt(0)
	s_setprio 1
	s_waitcnt lgkmcnt(7)
	v_mfma_f32_16x16x32_bf16 v[126:129], v[186:189], v[156:159], v[126:129]
	v_mfma_f32_16x16x32_bf16 v[122:125], v[186:189], v[170:173], v[122:125]
	s_waitcnt lgkmcnt(5)
	v_mfma_f32_16x16x32_bf16 v[118:121], v[194:197], v[156:159], v[118:121]
	v_mfma_f32_16x16x32_bf16 v[114:117], v[194:197], v[170:173], v[114:117]
	s_waitcnt lgkmcnt(3)
	v_mfma_f32_16x16x32_bf16 v[110:113], v[202:205], v[156:159], v[110:113]
	v_mfma_f32_16x16x32_bf16 v[106:109], v[202:205], v[170:173], v[106:109]
	s_waitcnt lgkmcnt(1)
	v_mfma_f32_16x16x32_bf16 v[102:105], v[210:213], v[156:159], v[102:105]
	v_mfma_f32_16x16x32_bf16 v[98:101], v[210:213], v[170:173], v[98:101]
	v_mfma_f32_16x16x32_bf16 v[126:129], v[190:193], v[166:169], v[126:129]
	v_mfma_f32_16x16x32_bf16 v[122:125], v[190:193], v[174:177], v[122:125]
	v_mfma_f32_16x16x32_bf16 v[118:121], v[198:201], v[166:169], v[118:121]
	v_mfma_f32_16x16x32_bf16 v[114:117], v[198:201], v[174:177], v[114:117]
	v_mfma_f32_16x16x32_bf16 v[110:113], v[206:209], v[166:169], v[110:113]
	v_mfma_f32_16x16x32_bf16 v[106:109], v[206:209], v[174:177], v[106:109]
	s_waitcnt lgkmcnt(0)
	v_mfma_f32_16x16x32_bf16 v[102:105], v[214:217], v[166:169], v[102:105]
	v_mfma_f32_16x16x32_bf16 v[98:101], v[214:217], v[174:177], v[98:101]
	s_setprio 0
	s_barrier
	ds_read_b128 v[150:153], v149
	ds_read_b128 v[218:221], v149 offset:1024
	ds_read_b128 v[222:225], v149 offset:2048
	ds_read_b128 v[146:149], v149 offset:3072
	s_barrier
	s_waitcnt lgkmcnt(0)
	s_setprio 1
	s_waitcnt lgkmcnt(3)
	v_mfma_f32_16x16x32_bf16 v[78:81], v[202:205], v[150:153], v[78:81]
	s_waitcnt lgkmcnt(1)
	v_mfma_f32_16x16x32_bf16 v[74:77], v[202:205], v[222:225], v[74:77]
	v_mfma_f32_16x16x32_bf16 v[70:73], v[210:213], v[150:153], v[70:73]
	v_mfma_f32_16x16x32_bf16 v[66:69], v[210:213], v[222:225], v[66:69]
	v_mfma_f32_16x16x32_bf16 v[94:97], v[186:189], v[150:153], v[94:97]
	v_mfma_f32_16x16x32_bf16 v[90:93], v[186:189], v[222:225], v[90:93]
	v_mfma_f32_16x16x32_bf16 v[86:89], v[194:197], v[150:153], v[86:89]
	v_mfma_f32_16x16x32_bf16 v[82:85], v[194:197], v[222:225], v[82:85]
	v_mfma_f32_16x16x32_bf16 v[78:81], v[206:209], v[218:221], v[78:81]
	s_waitcnt lgkmcnt(0)
	v_mfma_f32_16x16x32_bf16 v[74:77], v[206:209], v[146:149], v[74:77]
	v_mfma_f32_16x16x32_bf16 v[70:73], v[214:217], v[218:221], v[70:73]
	v_mfma_f32_16x16x32_bf16 v[66:69], v[214:217], v[146:149], v[66:69]
	v_mfma_f32_16x16x32_bf16 v[226:229], v[190:193], v[218:221], v[94:97]
	v_mfma_f32_16x16x32_bf16 v[186:189], v[190:193], v[146:149], v[90:93]
	v_mfma_f32_16x16x32_bf16 v[190:193], v[198:201], v[218:221], v[86:89]
	v_mfma_f32_16x16x32_bf16 v[194:197], v[198:201], v[146:149], v[82:85]
	s_setprio 0
	s_barrier
	s_nop 0
	ds_read_b128 v[82:85], v143 offset:16384
	ds_read_b128 v[86:89], v143 offset:17408
	ds_read_b128 v[90:93], v142 offset:16384
	ds_read_b128 v[94:97], v142 offset:17408
	ds_read_b128 v[198:201], v141 offset:16384
	ds_read_b128 v[202:205], v141 offset:17408
	ds_read_b128 v[206:209], v140 offset:16384
	ds_read_b128 v[210:213], v140 offset:17408
	s_waitcnt vmcnt(4)
	s_barrier
	s_waitcnt lgkmcnt(0)
	s_setprio 1
	s_waitcnt lgkmcnt(3)
	v_mfma_f32_16x16x32_bf16 v[46:49], v[198:201], v[156:159], v[46:49]
	v_mfma_f32_16x16x32_bf16 v[42:45], v[198:201], v[170:173], v[42:45]
	s_waitcnt lgkmcnt(1)
	v_mfma_f32_16x16x32_bf16 v[38:41], v[206:209], v[156:159], v[38:41]
	v_mfma_f32_16x16x32_bf16 v[34:37], v[206:209], v[170:173], v[34:37]
	v_mfma_f32_16x16x32_bf16 v[62:65], v[82:85], v[156:159], v[62:65]
	v_mfma_f32_16x16x32_bf16 v[58:61], v[82:85], v[170:173], v[58:61]
	v_mfma_f32_16x16x32_bf16 v[54:57], v[90:93], v[156:159], v[54:57]
	v_mfma_f32_16x16x32_bf16 v[50:53], v[90:93], v[170:173], v[50:53]
	v_mfma_f32_16x16x32_bf16 v[46:49], v[202:205], v[166:169], v[46:49]
	v_mfma_f32_16x16x32_bf16 v[42:45], v[202:205], v[174:177], v[42:45]
	s_waitcnt lgkmcnt(0)
	v_mfma_f32_16x16x32_bf16 v[38:41], v[210:213], v[166:169], v[38:41]
	v_mfma_f32_16x16x32_bf16 v[34:37], v[210:213], v[174:177], v[34:37]
	v_mfma_f32_16x16x32_bf16 v[214:217], v[86:89], v[166:169], v[62:65]
	v_mfma_f32_16x16x32_bf16 v[230:233], v[86:89], v[174:177], v[58:61]
	v_mfma_f32_16x16x32_bf16 v[234:237], v[94:97], v[166:169], v[54:57]
	v_mfma_f32_16x16x32_bf16 v[238:241], v[94:97], v[174:177], v[50:53]
	s_setprio 0
	s_setprio 1
	v_mfma_f32_16x16x32_bf16 v[0:3], v[206:209], v[222:225], v[0:3]
	v_mfma_f32_16x16x32_bf16 v[28:31], v[82:85], v[150:153], v[28:31]
	v_mfma_f32_16x16x32_bf16 v[24:27], v[82:85], v[222:225], v[24:27]
	v_mfma_f32_16x16x32_bf16 v[20:23], v[90:93], v[150:153], v[20:23]
	v_mfma_f32_16x16x32_bf16 v[16:19], v[90:93], v[222:225], v[16:19]
	v_mfma_f32_16x16x32_bf16 v[12:15], v[198:201], v[150:153], v[12:15]
	v_mfma_f32_16x16x32_bf16 v[8:11], v[198:201], v[222:225], v[8:11]
	v_mfma_f32_16x16x32_bf16 v[4:7], v[206:209], v[150:153], v[4:7]
	v_mfma_f32_16x16x32_bf16 v[0:3], v[210:213], v[146:149], v[0:3]
	v_mfma_f32_16x16x32_bf16 v[154:157], v[86:89], v[218:221], v[28:31]
	v_mfma_f32_16x16x32_bf16 v[158:161], v[86:89], v[146:149], v[24:27]
	v_mfma_f32_16x16x32_bf16 v[166:169], v[94:97], v[218:221], v[20:23]
	v_mfma_f32_16x16x32_bf16 v[170:173], v[94:97], v[146:149], v[16:19]
	v_mfma_f32_16x16x32_bf16 v[174:177], v[202:205], v[218:221], v[12:15]
	v_mfma_f32_16x16x32_bf16 v[198:201], v[202:205], v[146:149], v[8:11]
	v_mfma_f32_16x16x32_bf16 v[150:153], v[210:213], v[218:221], v[4:7]
	s_setprio 0
	s_barrier
; #define LDA(dst, b, h) _Pragma("unroll") for (int m = 0; m < 4; ++m) _Pragma("unroll") for (int k = 0; k < 2; ++k) \
;     dst[m][k] = *reinterpret_cast<const bf16x8*>((char*)SA(b, h) + lds_byte(wr * 64 + m * 16 + fr, k * 32 + fq * 8))
; #define LDB(dst, b, h) _Pragma("unroll") for (int n = 0; n < 2; ++n) _Pragma("unroll") for (int k = 0; k < 2; ++k) \
;     dst[n][k] = *reinterpret_cast<const bf16x8*>((char*)SB(b, h) + lds_byte(wc * 32 + n * 16 + fr, k * 32 + fq * 8))
; #define MMA(ai, bj, At, Bt_) do { __builtin_amdgcn_s_setprio(1); \
;     _Pragma("unroll") for (int m = 0; m < 4; ++m) _Pragma("unroll") for (int n = 0; n < 2; ++n) _Pragma("unroll") for (int k = 0; k < 2; ++k) \
;       acc[ai][bj][m][n] = __builtin_amdgcn_mfma_f32_16x16x32_bf16(At[m][k], Bt_[n][k], acc[ai][bj][m][n], 0, 0, 0); \
;     __builtin_amdgcn_s_setprio(0); } while (0)
; #define WAIT_V(n) asm volatile("s_waitcnt vmcnt(" #n ")" ::: "memory")
; #define WAIT_L(n) asm volatile("s_waitcnt lgkmcnt(" #n ")" ::: "memory")
; #define BAR __builtin_amdgcn_s_barrier()
; template <class Epi> ...
;     ...
;   { LDB(B0, 1, 0); LDA(At, 1, 0); WAIT_V(2); BAR; WAIT_L(0); MMA(0, 0, At, B0); BAR;
;     LDB(B1, 1, 1); WAIT_V(0); BAR; WAIT_L(0); MMA(0, 1, At, B1); BAR;
;     LDA(At, 1, 1); BAR; WAIT_L(0); MMA(1, 0, At, B0); MMA(1, 1, At, B1); BAR; }
;   if (wr == 0) BAR;
	s_nop 0
	ds_read_b128 v[4:7], v145
	ds_read_b128 v[8:11], v145 offset:1024
	ds_read_b128 v[12:15], v145 offset:2048
	ds_read_b128 v[146:149], v145 offset:3072
	ds_read_b128 v[16:19], v143 offset:32768
	ds_read_b128 v[20:23], v143 offset:33792
	ds_read_b128 v[24:27], v142 offset:32768
	ds_read_b128 v[50:53], v142 offset:33792
	ds_read_b128 v[202:205], v141 offset:32768
	ds_read_b128 v[206:209], v141 offset:33792
	ds_read_b128 v[210:213], v140 offset:32768
	ds_read_b128 v[218:221], v140 offset:33792
	s_waitcnt vmcnt(2)
	s_barrier
	s_waitcnt lgkmcnt(0)
	s_setprio 1
	s_waitcnt lgkmcnt(7)
	v_mfma_f32_16x16x32_bf16 v[28:31], v[16:19], v[4:7], v[126:129]
	s_waitcnt lgkmcnt(6)
	v_mfma_f32_16x16x32_bf16 v[126:129], v[20:23], v[8:11], v[28:31]
	v_mfma_f32_16x16x32_bf16 v[28:31], v[16:19], v[12:15], v[122:125]
	v_mfma_f32_16x16x32_bf16 v[94:97], v[20:23], v[146:149], v[28:31]
	s_waitcnt lgkmcnt(5)
	v_mfma_f32_16x16x32_bf16 v[28:31], v[24:27], v[4:7], v[118:121]
	s_waitcnt lgkmcnt(4)
	v_mfma_f32_16x16x32_bf16 v[122:125], v[50:53], v[8:11], v[28:31]
	v_mfma_f32_16x16x32_bf16 v[28:31], v[24:27], v[12:15], v[114:117]
	v_mfma_f32_16x16x32_bf16 v[90:93], v[50:53], v[146:149], v[28:31]
	s_waitcnt lgkmcnt(3)
	v_mfma_f32_16x16x32_bf16 v[28:31], v[202:205], v[4:7], v[110:113]
	s_waitcnt lgkmcnt(2)
	v_mfma_f32_16x16x32_bf16 v[118:121], v[206:209], v[8:11], v[28:31]
	v_mfma_f32_16x16x32_bf16 v[28:31], v[202:205], v[12:15], v[106:109]
	v_mfma_f32_16x16x32_bf16 v[86:89], v[206:209], v[146:149], v[28:31]
	s_waitcnt lgkmcnt(1)
	v_mfma_f32_16x16x32_bf16 v[28:31], v[210:213], v[4:7], v[102:105]
	s_waitcnt lgkmcnt(0)
	v_mfma_f32_16x16x32_bf16 v[114:117], v[218:221], v[8:11], v[28:31]
	v_mfma_f32_16x16x32_bf16 v[28:31], v[210:213], v[12:15], v[98:101]
	v_mfma_f32_16x16x32_bf16 v[82:85], v[218:221], v[146:149], v[28:31]
	s_setprio 0
	s_barrier
	ds_read_b128 v[222:225], v144
	ds_read_b128 v[242:245], v144 offset:1024
	ds_read_b128 v[246:249], v144 offset:2048
	ds_read_b128 v[250:253], v144 offset:3072
	s_waitcnt vmcnt(0)
	s_barrier
	s_waitcnt lgkmcnt(0)
	s_setprio 1
	s_waitcnt lgkmcnt(3)
	v_mfma_f32_16x16x32_bf16 v[28:31], v[16:19], v[222:225], v[226:229]
	s_waitcnt lgkmcnt(1)
	v_mfma_f32_16x16x32_bf16 v[16:19], v[16:19], v[246:249], v[186:189]
	v_mfma_f32_16x16x32_bf16 v[62:65], v[20:23], v[242:245], v[28:31]
	s_waitcnt lgkmcnt(0)
	v_mfma_f32_16x16x32_bf16 v[28:31], v[20:23], v[250:253], v[16:19]
	v_mfma_f32_16x16x32_bf16 v[16:19], v[24:27], v[222:225], v[190:193]
	v_mfma_f32_16x16x32_bf16 v[58:61], v[50:53], v[242:245], v[16:19]
	v_mfma_f32_16x16x32_bf16 v[16:19], v[24:27], v[246:249], v[194:197]
	v_mfma_f32_16x16x32_bf16 v[24:27], v[50:53], v[250:253], v[16:19]
	v_mfma_f32_16x16x32_bf16 v[16:19], v[202:205], v[222:225], v[78:81]
	v_mfma_f32_16x16x32_bf16 v[54:57], v[206:209], v[242:245], v[16:19]
	v_mfma_f32_16x16x32_bf16 v[16:19], v[202:205], v[246:249], v[74:77]
	v_mfma_f32_16x16x32_bf16 v[20:23], v[206:209], v[250:253], v[16:19]
	v_mfma_f32_16x16x32_bf16 v[16:19], v[210:213], v[222:225], v[70:73]
	v_mfma_f32_16x16x32_bf16 v[50:53], v[218:221], v[242:245], v[16:19]
	v_mfma_f32_16x16x32_bf16 v[16:19], v[210:213], v[246:249], v[66:69]
	v_mfma_f32_16x16x32_bf16 v[16:19], v[218:221], v[250:253], v[16:19]
	s_setprio 0
	s_barrier
	ds_read_b128 v[186:189], v143 offset:49152
	ds_read_b128 v[190:193], v143 offset:50176
	ds_read_b128 v[194:197], v142 offset:49152
	ds_read_b128 v[142:145], v142 offset:50176
	ds_read_b128 v[202:205], v141 offset:49152
	ds_read_b128 v[206:209], v141 offset:50176
	ds_read_b128 v[210:213], v140 offset:49152
	ds_read_b128 v[218:221], v140 offset:50176
	s_barrier
	s_waitcnt lgkmcnt(0)
	s_setprio 1
	s_waitcnt lgkmcnt(7)
	v_mfma_f32_16x16x32_bf16 v[66:69], v[186:189], v[4:7], v[214:217]
	s_waitcnt lgkmcnt(6)
	v_mfma_f32_16x16x32_bf16 v[110:113], v[190:193], v[8:11], v[66:69]
	v_mfma_f32_16x16x32_bf16 v[66:69], v[186:189], v[12:15], v[230:233]
	v_mfma_f32_16x16x32_bf16 v[78:81], v[190:193], v[146:149], v[66:69]
	s_waitcnt lgkmcnt(5)
	v_mfma_f32_16x16x32_bf16 v[66:69], v[194:197], v[4:7], v[234:237]
	s_waitcnt lgkmcnt(3)
	v_mfma_f32_16x16x32_bf16 v[46:49], v[202:205], v[4:7], v[46:49]
	s_waitcnt lgkmcnt(1)
	v_mfma_f32_16x16x32_bf16 v[4:7], v[210:213], v[4:7], v[38:41]
	v_mfma_f32_16x16x32_bf16 v[106:109], v[142:145], v[8:11], v[66:69]
	v_mfma_f32_16x16x32_bf16 v[66:69], v[194:197], v[12:15], v[238:241]
	v_mfma_f32_16x16x32_bf16 v[42:45], v[202:205], v[12:15], v[42:45]
	s_waitcnt lgkmcnt(0)
	v_mfma_f32_16x16x32_bf16 v[98:101], v[218:221], v[8:11], v[4:7]
	v_mfma_f32_16x16x32_bf16 v[4:7], v[210:213], v[12:15], v[34:37]
	v_mfma_f32_16x16x32_bf16 v[74:77], v[142:145], v[146:149], v[66:69]
	v_mfma_f32_16x16x32_bf16 v[102:105], v[206:209], v[8:11], v[46:49]
	v_mfma_f32_16x16x32_bf16 v[70:73], v[206:209], v[146:149], v[42:45]
	v_mfma_f32_16x16x32_bf16 v[66:69], v[218:221], v[146:149], v[4:7]
	s_setprio 0
	s_setprio 1
	v_mfma_f32_16x16x32_bf16 v[4:7], v[186:189], v[222:225], v[154:157]
	v_mfma_f32_16x16x32_bf16 v[46:49], v[190:193], v[242:245], v[4:7]
	v_mfma_f32_16x16x32_bf16 v[4:7], v[186:189], v[246:249], v[158:161]
	v_mfma_f32_16x16x32_bf16 v[12:15], v[190:193], v[250:253], v[4:7]
	v_mfma_f32_16x16x32_bf16 v[4:7], v[194:197], v[222:225], v[166:169]
	v_mfma_f32_16x16x32_bf16 v[42:45], v[142:145], v[242:245], v[4:7]
	v_mfma_f32_16x16x32_bf16 v[4:7], v[194:197], v[246:249], v[170:173]
	v_mfma_f32_16x16x32_bf16 v[8:11], v[142:145], v[250:253], v[4:7]
	v_mfma_f32_16x16x32_bf16 v[4:7], v[202:205], v[222:225], v[174:177]
	v_mfma_f32_16x16x32_bf16 v[38:41], v[206:209], v[242:245], v[4:7]
	v_mfma_f32_16x16x32_bf16 v[4:7], v[202:205], v[246:249], v[198:201]
	v_mfma_f32_16x16x32_bf16 v[34:37], v[210:213], v[222:225], v[150:153]
	v_mfma_f32_16x16x32_bf16 v[0:3], v[210:213], v[246:249], v[0:3]
	v_mfma_f32_16x16x32_bf16 v[4:7], v[206:209], v[250:253], v[4:7]
	v_mfma_f32_16x16x32_bf16 v[34:37], v[218:221], v[242:245], v[34:37]
	v_mfma_f32_16x16x32_bf16 v[0:3], v[218:221], v[250:253], v[0:3]
	s_setprio 0
	v_cmp_gt_u32_e32 vcc, s59, v130
	s_barrier
	s_and_saveexec_b64 s[6:7], vcc
	s_cbranch_execz .LBB0_2339
	s_barrier
